# v47 + rw_post: staged loads, segment correction as f32 MFMA 32x32x2 per unit (operands via LDS transposition), permlane32 swap to lane=v
# speedup vs baseline: 1.0118x; 1.0049x over previous
; #define POST_LD(Y_, V_, G_, R_, C_, t) do { _Pragma("unroll") for (int q = 0; q < 8; ++q) { const size_t o_ = (size_t)((t) + q) * DH; Y_[q] = yp[o_]; V_[q] = vp[o_]; G_[q] = gp[o_]; R_[q] = rp[((t) + q) * 32]; C_[q] = cp[o_]; } } while (0)
; __device__ __forceinline__ void rw_post(Frame& F) {
;     const float* Y = (const float*)(F.ws + WS_Y); const float* C = (const float*)(F.ws + WS_C); const float* SST = (const float*)(F.ws + WS_SST); const float* VS = (const float*)(F.ws + WS_VS);
;     const float* RK = (const float*)(F.ws + WS_RK); const bf16* G = (const bf16*)(F.ws + WS_G);
;     bf16* OB = (bf16*)(F.ws + WS_OB); const float* lng = F.in[I_LNG]; const float* lnb = F.in[I_LNB];
;     const int lane = F.lane;
;     for (int u = F.gw; u < 32 * (MR / 64); u += F.NGW) { const int h = u & 31, rb0 = (u >> 5) * 64, col = h * 64 + lane;
;         const float g_ = lng[col], b_ = lnb[col];
;         const int k = rb0 < MPR ? (rb0 / SEGLEN) : 0;
;         f32x4 Sr[16];
;         if (k > 0) {
; #pragma unroll
;             for (int q = 0; q < 16; ++q) Sr[q] = *(const f32x4*)(SST + ((size_t)(h * NSEG + k) * 64 + lane) * 64 + 4 * q); }
;         const float* yp = Y + (size_t)rb0 * DH + col; const float* vp = VS + (size_t)rb0 * DH + col; const bf16* gp = G + (size_t)rb0 * DH + col; const float* rp = RK + (size_t)rb0 * 32 + h;
;         const float* cp = k > 0 ? C + (size_t)(rb0 - SEGLEN) * DH + col : yp;
;         float y[8], vv[8], rk[8], cc[8]; bf16 gg[8];
;     ...
;         POST_LD(y, vv, gg, rk, cc, 0);
.LBB0_1160:
	s_or_b64 exec, exec, s[6:7]
	s_cmpk_gt_i32 s94, 0x203f
	s_waitcnt lgkmcnt(0)
	s_barrier
	s_cbranch_scc1 .LBB0_1170
	s_load_dwordx4 s[16:19], s[74:75], 0xc0
	v_readlane_b32 s24, v240, 2
	v_lshlrev_b32_e32 v1, 2, v178
	v_lshlrev_b32_e32 v2, 1, v178
	v_lshlrev_b32_e32 v11, 4, v178
	v_mov_b32_e32 v5, 0
	v_mov_b32_e32 v8, 0x260
	v_mov_b32_e32 v9, 0x3a27c5ac
	s_mov_b32 s68, 0xf800000
	s_mov_b32 s33, s24
	s_lshl_b32 s30, s24, 11
	v_add_u32_e32 v12, s30, v11
	v_add_u32_e32 v13, 0xa000, v12
	s_lshl_b32 s30, s24, 10
	s_add_i32 s30, s30, 0x8000
	v_add_u32_e32 v14, s30, v11
	v_add_u32_e32 v15, 0xa000, v14
	s_lshl_b32 s30, s24, 8
	v_add_u32_e32 v154, s30, v1
	v_add_u32_e32 v155, 0xa000, v154
	s_lshl_b32 s30, s24, 7
	s_add_i32 s30, s30, 0x8000
	v_add_u32_e32 v156, s30, v2
	v_add_u32_e32 v157, 0xa000, v156
	v_and_b32_e32 v158, 7, v178
	v_lshlrev_b32_e32 v158, 7, v158
	s_mov_b32 s20, s94
	s_waitcnt lgkmcnt(0)
.Lpo_unit:
	s_and_b32 s21, s20, 31
	s_lshr_b32 s22, s20, 5
	s_lshl_b32 s22, s22, 6
	s_lshr_b32 s23, s22, 10
	s_cmpk_lt_i32 s22, 0x4000
	s_cselect_b32 s23, s23, 0
	s_add_i32 s34, s22, s33
	s_and_b32 s35, s21, 24
	s_lshl_b32 s30, s34, 13
	s_lshl_b32 s31, s35, 8
	s_add_u32 s30, s30, s31
	s_add_u32 s6, s90, s30
	s_addc_u32 s7, s91, 0
	s_add_u32 s8, s6, 0x28700000
	s_addc_u32 s9, s7, 0
	s_add_u32 s6, s6, 0x39900000
	s_addc_u32 s7, s7, 0
	s_lshl_b32 s30, s34, 12
	s_lshl_b32 s31, s35, 7
	s_add_u32 s30, s30, s31
	s_add_u32 s10, s90, s30
	s_addc_u32 s11, s91, 0
	s_add_u32 s10, s10, 0x30800000
	s_addc_u32 s11, s11, 0
	s_lshl_b32 s30, s22, 12
	s_lshl_b32 s31, s21, 7
	s_add_u32 s30, s30, s31
	s_add_u32 s28, s90, s30
	s_addc_u32 s29, s91, 0
	s_add_u32 s28, s28, 0x18500000
	s_addc_u32 s29, s29, 0
	s_lshl_b32 s30, s22, 7
	s_lshl_b32 s31, s21, 2
	s_add_u32 s30, s30, s31
	s_add_u32 s12, s90, s30
	s_addc_u32 s13, s91, 0
	s_add_u32 s12, s12, 0x6e200000
	s_addc_u32 s13, s13, 0
	s_lshl_b32 s31, s21, 8
	s_add_u32 s30, s16, s31
	s_addc_u32 s31, s17, 0
	global_load_dword v6, v1, s[30:31]
	s_lshl_b32 s31, s21, 8
	s_add_u32 s30, s18, s31
	s_addc_u32 s31, s19, 0
	global_load_dword v7, v1, s[30:31]
	s_barrier
	s_cmp_eq_u32 s23, 0
	s_cbranch_scc1 .Lpo_zero
	s_lshl_b32 s30, s21, 4
	s_add_u32 s30, s30, s23
	s_lshl_b32 s30, s30, 14
	s_add_u32 s30, s90, s30
	s_addc_u32 s31, s91, 0
	s_add_u32 s30, s30, 0x6fb00000
	s_addc_u32 s31, s31, 0
	s_lshl_b32 s34, s22, 13
	s_lshl_b32 s35, s21, 8
	s_add_u32 s34, s34, s35
	s_add_u32 s34, s90, s34
	s_addc_u32 s35, s91, 0
	s_add_u32 s34, s34, 0x41200000
	s_addc_u32 s35, s35, 0
	v_lshrrev_b32_e32 v170, 4, v178
	v_and_b32_e32 v168, 15, v178
	v_lshlrev_b32_e32 v171, 4, v168
	v_lshl_add_u32 v171, v170, 13, v171
	v_mul_u32_u24_e32 v172, 0x110, v170
	v_lshl_add_u32 v172, v168, 3, v172
	s_mul_i32 s36, s33, 0x4400
	v_add_u32_e32 v172, s36, v172
	v_and_b32_e32 v170, 31, v178
	v_mul_u32_u24_e32 v173, 0x110, v170
	v_lshrrev_b32_e32 v168, 5, v178
	v_lshl_add_u32 v173, v168, 7, v173
	v_add_u32_e32 v173, s36, v173
	global_load_dwordx4 v[80:83], v11, s[30:31]
	global_load_dwordx4 v[84:87], v11, s[30:31] offset:1024
	global_load_dwordx4 v[88:91], v11, s[30:31] offset:2048
	global_load_dwordx4 v[92:95], v11, s[30:31] offset:3072
	s_add_u32 s30, s30, 0x1000
	s_addc_u32 s31, s31, 0
	global_load_dwordx4 v[96:99], v11, s[30:31]
	global_load_dwordx4 v[100:103], v11, s[30:31] offset:1024
	global_load_dwordx4 v[104:107], v11, s[30:31] offset:2048
	global_load_dwordx4 v[108:111], v11, s[30:31] offset:3072
	s_add_u32 s30, s30, 0x1000
	s_addc_u32 s31, s31, 0
	global_load_dwordx4 v[112:115], v11, s[30:31]
	global_load_dwordx4 v[116:119], v11, s[30:31] offset:1024
	global_load_dwordx4 v[120:123], v11, s[30:31] offset:2048
	global_load_dwordx4 v[124:127], v11, s[30:31] offset:3072
	s_add_u32 s30, s30, 0x1000
	s_addc_u32 s31, s31, 0
	global_load_dwordx4 v[128:131], v11, s[30:31]
	global_load_dwordx4 v[132:135], v11, s[30:31] offset:1024
	global_load_dwordx4 v[136:139], v11, s[30:31] offset:2048
	global_load_dwordx4 v[140:143], v11, s[30:31] offset:3072
	s_waitcnt vmcnt(0)
	ds_write_b32 v172, v80 offset:0
	ds_write_b32 v172, v82 offset:4
	ds_write_b32 v172, v81 offset:128
	ds_write_b32 v172, v83 offset:132
	ds_write_b32 v172, v84 offset:1088
	ds_write_b32 v172, v86 offset:1092
	ds_write_b32 v172, v85 offset:1216
	ds_write_b32 v172, v87 offset:1220
	ds_write_b32 v172, v88 offset:2176
	ds_write_b32 v172, v90 offset:2180
	ds_write_b32 v172, v89 offset:2304
	ds_write_b32 v172, v91 offset:2308
	ds_write_b32 v172, v92 offset:3264
	ds_write_b32 v172, v94 offset:3268
	ds_write_b32 v172, v93 offset:3392
	ds_write_b32 v172, v95 offset:3396
	ds_write_b32 v172, v96 offset:4352
	ds_write_b32 v172, v98 offset:4356
	ds_write_b32 v172, v97 offset:4480
	ds_write_b32 v172, v99 offset:4484
	ds_write_b32 v172, v100 offset:5440
	ds_write_b32 v172, v102 offset:5444
	ds_write_b32 v172, v101 offset:5568
	ds_write_b32 v172, v103 offset:5572
	ds_write_b32 v172, v104 offset:6528
	ds_write_b32 v172, v106 offset:6532
	ds_write_b32 v172, v105 offset:6656
	ds_write_b32 v172, v107 offset:6660
	ds_write_b32 v172, v108 offset:7616
	ds_write_b32 v172, v110 offset:7620
	ds_write_b32 v172, v109 offset:7744
	ds_write_b32 v172, v111 offset:7748
	ds_write_b32 v172, v112 offset:8704
	ds_write_b32 v172, v114 offset:8708
	ds_write_b32 v172, v113 offset:8832
	ds_write_b32 v172, v115 offset:8836
	ds_write_b32 v172, v116 offset:9792
	ds_write_b32 v172, v118 offset:9796
	ds_write_b32 v172, v117 offset:9920
	ds_write_b32 v172, v119 offset:9924
	ds_write_b32 v172, v120 offset:10880
	ds_write_b32 v172, v122 offset:10884
	ds_write_b32 v172, v121 offset:11008
	ds_write_b32 v172, v123 offset:11012
	ds_write_b32 v172, v124 offset:11968
	ds_write_b32 v172, v126 offset:11972
	ds_write_b32 v172, v125 offset:12096
	ds_write_b32 v172, v127 offset:12100
	ds_write_b32 v172, v128 offset:13056
	ds_write_b32 v172, v130 offset:13060
	ds_write_b32 v172, v129 offset:13184
	ds_write_b32 v172, v131 offset:13188
	ds_write_b32 v172, v132 offset:14144
	ds_write_b32 v172, v134 offset:14148
	ds_write_b32 v172, v133 offset:14272
	ds_write_b32 v172, v135 offset:14276
	ds_write_b32 v172, v136 offset:15232
	ds_write_b32 v172, v138 offset:15236
	ds_write_b32 v172, v137 offset:15360
	ds_write_b32 v172, v139 offset:15364
	ds_write_b32 v172, v140 offset:16320
	ds_write_b32 v172, v142 offset:16324
	ds_write_b32 v172, v141 offset:16448
	ds_write_b32 v172, v143 offset:16452
	s_waitcnt lgkmcnt(0)
; #define LAS __attribute__((address_space(3)))
; __device__ __forceinline__ void rw_post(Frame& F) {
;     ...
;         const float* cp = k > 0 ? C + (size_t)(rb0 - SEGLEN) * DH + col : yp;
;         float y[8], vv[8], rk[8], cc[8]; bf16 gg[8];
;     ...
;             if (k > 0) {
;                 LAS float* cs = (LAS float*)(F.lds + 131072 + F.wave * 1024);
; #pragma unroll
;                 for (int hf = 0; hf < 2; ++hf) {
; #pragma unroll
;                     for (int q = 0; q < 4; ++q) cs[q * 64 + lane] = cc[4 * hf + q];
;                     asm volatile("s_waitcnt lgkmcnt(0)" ::: "memory");
; #pragma unroll
;                     for (int q = 0; q < 4; ++q) { f32x4 a = (f32x4){0.f, 0.f, 0.f, 0.f};
; #pragma unroll
;                         for (int i = 0; i < 16; ++i) a = __builtin_elementwise_fma(Sr[i], *(const LAS f32x4*)(cs + q * 64 + 4 * i), a);
	ds_read_b128 v[184:187], v173 offset:0
	ds_read_b128 v[188:191], v173 offset:16
	ds_read_b128 v[192:195], v173 offset:32
	ds_read_b128 v[196:199], v173 offset:48
	ds_read_b128 v[200:203], v173 offset:64
	ds_read_b128 v[204:207], v173 offset:80
	ds_read_b128 v[208:211], v173 offset:96
	ds_read_b128 v[212:215], v173 offset:112
	ds_read_b128 v[216:219], v173 offset:8704
	ds_read_b128 v[220:223], v173 offset:8720
	ds_read_b128 v[224:227], v173 offset:8736
	ds_read_b128 v[228:231], v173 offset:8752
	ds_read_b128 v[232:235], v173 offset:8768
	ds_read_b128 v[244:247], v173 offset:8784
	ds_read_b128 v[248:251], v173 offset:8800
	ds_read_b128 v[252:255], v173 offset:8816
	s_waitcnt lgkmcnt(0)
	global_load_dwordx4 v[80:83], v171, s[34:35]
	s_add_u32 s34, s34, 0x8000
	s_addc_u32 s35, s35, 0
	global_load_dwordx4 v[84:87], v171, s[34:35]
	s_add_u32 s34, s34, 0x8000
	s_addc_u32 s35, s35, 0
	global_load_dwordx4 v[88:91], v171, s[34:35]
	s_add_u32 s34, s34, 0x8000
	s_addc_u32 s35, s35, 0
	global_load_dwordx4 v[92:95], v171, s[34:35]
	s_add_u32 s34, s34, 0x8000
	s_addc_u32 s35, s35, 0
	global_load_dwordx4 v[96:99], v171, s[34:35]
	s_add_u32 s34, s34, 0x8000
	s_addc_u32 s35, s35, 0
	global_load_dwordx4 v[100:103], v171, s[34:35]
	s_add_u32 s34, s34, 0x8000
	s_addc_u32 s35, s35, 0
	global_load_dwordx4 v[104:107], v171, s[34:35]
	s_add_u32 s34, s34, 0x8000
	s_addc_u32 s35, s35, 0
	global_load_dwordx4 v[108:111], v171, s[34:35]
	s_add_u32 s34, s34, 0x8000
	s_addc_u32 s35, s35, 0
	global_load_dwordx4 v[112:115], v171, s[34:35]
	s_add_u32 s34, s34, 0x8000
	s_addc_u32 s35, s35, 0
	global_load_dwordx4 v[116:119], v171, s[34:35]
	s_add_u32 s34, s34, 0x8000
	s_addc_u32 s35, s35, 0
	global_load_dwordx4 v[120:123], v171, s[34:35]
	s_add_u32 s34, s34, 0x8000
	s_addc_u32 s35, s35, 0
	global_load_dwordx4 v[124:127], v171, s[34:35]
	s_add_u32 s34, s34, 0x8000
	s_addc_u32 s35, s35, 0
	global_load_dwordx4 v[128:131], v171, s[34:35]
	s_add_u32 s34, s34, 0x8000
	s_addc_u32 s35, s35, 0
	global_load_dwordx4 v[132:135], v171, s[34:35]
	s_add_u32 s34, s34, 0x8000
	s_addc_u32 s35, s35, 0
	global_load_dwordx4 v[136:139], v171, s[34:35]
	s_add_u32 s34, s34, 0x8000
	s_addc_u32 s35, s35, 0
	global_load_dwordx4 v[140:143], v171, s[34:35]
	s_waitcnt vmcnt(0)
	ds_write_b32 v172, v80 offset:0
	ds_write_b32 v172, v82 offset:4
	ds_write_b32 v172, v81 offset:128
	ds_write_b32 v172, v83 offset:132
	ds_write_b32 v172, v84 offset:1088
	ds_write_b32 v172, v86 offset:1092
	ds_write_b32 v172, v85 offset:1216
	ds_write_b32 v172, v87 offset:1220
	ds_write_b32 v172, v88 offset:2176
	ds_write_b32 v172, v90 offset:2180
	ds_write_b32 v172, v89 offset:2304
	ds_write_b32 v172, v91 offset:2308
	ds_write_b32 v172, v92 offset:3264
	ds_write_b32 v172, v94 offset:3268
	ds_write_b32 v172, v93 offset:3392
	ds_write_b32 v172, v95 offset:3396
	ds_write_b32 v172, v96 offset:4352
	ds_write_b32 v172, v98 offset:4356
	ds_write_b32 v172, v97 offset:4480
	ds_write_b32 v172, v99 offset:4484
	ds_write_b32 v172, v100 offset:5440
	ds_write_b32 v172, v102 offset:5444
	ds_write_b32 v172, v101 offset:5568
	ds_write_b32 v172, v103 offset:5572
	ds_write_b32 v172, v104 offset:6528
	ds_write_b32 v172, v106 offset:6532
	ds_write_b32 v172, v105 offset:6656
	ds_write_b32 v172, v107 offset:6660
	ds_write_b32 v172, v108 offset:7616
	ds_write_b32 v172, v110 offset:7620
	ds_write_b32 v172, v109 offset:7744
	ds_write_b32 v172, v111 offset:7748
	ds_write_b32 v172, v112 offset:8704
	ds_write_b32 v172, v114 offset:8708
	ds_write_b32 v172, v113 offset:8832
	ds_write_b32 v172, v115 offset:8836
	ds_write_b32 v172, v116 offset:9792
	ds_write_b32 v172, v118 offset:9796
	ds_write_b32 v172, v117 offset:9920
	ds_write_b32 v172, v119 offset:9924
	ds_write_b32 v172, v120 offset:10880
	ds_write_b32 v172, v122 offset:10884
	ds_write_b32 v172, v121 offset:11008
	ds_write_b32 v172, v123 offset:11012
	ds_write_b32 v172, v124 offset:11968
	ds_write_b32 v172, v126 offset:11972
	ds_write_b32 v172, v125 offset:12096
	ds_write_b32 v172, v127 offset:12100
	ds_write_b32 v172, v128 offset:13056
	ds_write_b32 v172, v130 offset:13060
	ds_write_b32 v172, v129 offset:13184
	ds_write_b32 v172, v131 offset:13188
	ds_write_b32 v172, v132 offset:14144
	ds_write_b32 v172, v134 offset:14148
	ds_write_b32 v172, v133 offset:14272
	ds_write_b32 v172, v135 offset:14276
	ds_write_b32 v172, v136 offset:15232
	ds_write_b32 v172, v138 offset:15236
	ds_write_b32 v172, v137 offset:15360
	ds_write_b32 v172, v139 offset:15364
	ds_write_b32 v172, v140 offset:16320
	ds_write_b32 v172, v142 offset:16324
	ds_write_b32 v172, v141 offset:16448
	ds_write_b32 v172, v143 offset:16452
	s_waitcnt lgkmcnt(0)
	ds_read_b128 v[80:83], v173 offset:0
	ds_read_b128 v[84:87], v173 offset:16
	ds_read_b128 v[88:91], v173 offset:32
	ds_read_b128 v[92:95], v173 offset:48
	ds_read_b128 v[96:99], v173 offset:64
	ds_read_b128 v[100:103], v173 offset:80
	ds_read_b128 v[104:107], v173 offset:96
	ds_read_b128 v[108:111], v173 offset:112
	ds_read_b128 v[112:115], v173 offset:8704
	ds_read_b128 v[116:119], v173 offset:8720
	ds_read_b128 v[120:123], v173 offset:8736
	ds_read_b128 v[124:127], v173 offset:8752
	ds_read_b128 v[128:131], v173 offset:8768
	ds_read_b128 v[132:135], v173 offset:8784
	ds_read_b128 v[136:139], v173 offset:8800
	ds_read_b128 v[140:143], v173 offset:8816
	s_waitcnt lgkmcnt(0)
; #define LAS __attribute__((address_space(3)))
; __device__ __forceinline__ void rw_post(Frame& F) {
;     ...
;                     for (int q = 0; q < 4; ++q) { f32x4 a = (f32x4){0.f, 0.f, 0.f, 0.f};
; #pragma unroll
;                         for (int i = 0; i < 16; ++i) a = __builtin_elementwise_fma(Sr[i], *(const LAS f32x4*)(cs + q * 64 + 4 * i), a);
;                         y[4 * hf + q] += (a[0] + a[1]) + (a[2] + a[3]); }
	v_mfma_f32_32x32x2_f32 v[16:31], v80, v184, 0
	v_mfma_f32_32x32x2_f32 v[32:47], v80, v216, 0
	v_mfma_f32_32x32x2_f32 v[48:63], v112, v184, 0
	v_mfma_f32_32x32x2_f32 v[64:79], v112, v216, 0
	v_mfma_f32_32x32x2_f32 v[16:31], v81, v185, v[16:31]
	v_mfma_f32_32x32x2_f32 v[32:47], v81, v217, v[32:47]
	v_mfma_f32_32x32x2_f32 v[48:63], v113, v185, v[48:63]
	v_mfma_f32_32x32x2_f32 v[64:79], v113, v217, v[64:79]
	v_mfma_f32_32x32x2_f32 v[16:31], v82, v186, v[16:31]
	v_mfma_f32_32x32x2_f32 v[32:47], v82, v218, v[32:47]
	v_mfma_f32_32x32x2_f32 v[48:63], v114, v186, v[48:63]
	v_mfma_f32_32x32x2_f32 v[64:79], v114, v218, v[64:79]
	v_mfma_f32_32x32x2_f32 v[16:31], v83, v187, v[16:31]
	v_mfma_f32_32x32x2_f32 v[32:47], v83, v219, v[32:47]
	v_mfma_f32_32x32x2_f32 v[48:63], v115, v187, v[48:63]
	v_mfma_f32_32x32x2_f32 v[64:79], v115, v219, v[64:79]
	v_mfma_f32_32x32x2_f32 v[16:31], v84, v188, v[16:31]
	v_mfma_f32_32x32x2_f32 v[32:47], v84, v220, v[32:47]
	v_mfma_f32_32x32x2_f32 v[48:63], v116, v188, v[48:63]
	v_mfma_f32_32x32x2_f32 v[64:79], v116, v220, v[64:79]
	v_mfma_f32_32x32x2_f32 v[16:31], v85, v189, v[16:31]
	v_mfma_f32_32x32x2_f32 v[32:47], v85, v221, v[32:47]
	v_mfma_f32_32x32x2_f32 v[48:63], v117, v189, v[48:63]
	v_mfma_f32_32x32x2_f32 v[64:79], v117, v221, v[64:79]
	v_mfma_f32_32x32x2_f32 v[16:31], v86, v190, v[16:31]
	v_mfma_f32_32x32x2_f32 v[32:47], v86, v222, v[32:47]
	v_mfma_f32_32x32x2_f32 v[48:63], v118, v190, v[48:63]
	v_mfma_f32_32x32x2_f32 v[64:79], v118, v222, v[64:79]
	v_mfma_f32_32x32x2_f32 v[16:31], v87, v191, v[16:31]
	v_mfma_f32_32x32x2_f32 v[32:47], v87, v223, v[32:47]
	v_mfma_f32_32x32x2_f32 v[48:63], v119, v191, v[48:63]
	v_mfma_f32_32x32x2_f32 v[64:79], v119, v223, v[64:79]
	v_mfma_f32_32x32x2_f32 v[16:31], v88, v192, v[16:31]
	v_mfma_f32_32x32x2_f32 v[32:47], v88, v224, v[32:47]
	v_mfma_f32_32x32x2_f32 v[48:63], v120, v192, v[48:63]
	v_mfma_f32_32x32x2_f32 v[64:79], v120, v224, v[64:79]
	v_mfma_f32_32x32x2_f32 v[16:31], v89, v193, v[16:31]
	v_mfma_f32_32x32x2_f32 v[32:47], v89, v225, v[32:47]
	v_mfma_f32_32x32x2_f32 v[48:63], v121, v193, v[48:63]
	v_mfma_f32_32x32x2_f32 v[64:79], v121, v225, v[64:79]
	v_mfma_f32_32x32x2_f32 v[16:31], v90, v194, v[16:31]
	v_mfma_f32_32x32x2_f32 v[32:47], v90, v226, v[32:47]
	v_mfma_f32_32x32x2_f32 v[48:63], v122, v194, v[48:63]
	v_mfma_f32_32x32x2_f32 v[64:79], v122, v226, v[64:79]
	v_mfma_f32_32x32x2_f32 v[16:31], v91, v195, v[16:31]
	v_mfma_f32_32x32x2_f32 v[32:47], v91, v227, v[32:47]
	v_mfma_f32_32x32x2_f32 v[48:63], v123, v195, v[48:63]
	v_mfma_f32_32x32x2_f32 v[64:79], v123, v227, v[64:79]
	v_mfma_f32_32x32x2_f32 v[16:31], v92, v196, v[16:31]
	v_mfma_f32_32x32x2_f32 v[32:47], v92, v228, v[32:47]
	v_mfma_f32_32x32x2_f32 v[48:63], v124, v196, v[48:63]
	v_mfma_f32_32x32x2_f32 v[64:79], v124, v228, v[64:79]
	v_mfma_f32_32x32x2_f32 v[16:31], v93, v197, v[16:31]
	v_mfma_f32_32x32x2_f32 v[32:47], v93, v229, v[32:47]
	v_mfma_f32_32x32x2_f32 v[48:63], v125, v197, v[48:63]
	v_mfma_f32_32x32x2_f32 v[64:79], v125, v229, v[64:79]
	v_mfma_f32_32x32x2_f32 v[16:31], v94, v198, v[16:31]
	v_mfma_f32_32x32x2_f32 v[32:47], v94, v230, v[32:47]
	v_mfma_f32_32x32x2_f32 v[48:63], v126, v198, v[48:63]
	v_mfma_f32_32x32x2_f32 v[64:79], v126, v230, v[64:79]
	v_mfma_f32_32x32x2_f32 v[16:31], v95, v199, v[16:31]
	v_mfma_f32_32x32x2_f32 v[32:47], v95, v231, v[32:47]
	v_mfma_f32_32x32x2_f32 v[48:63], v127, v199, v[48:63]
	v_mfma_f32_32x32x2_f32 v[64:79], v127, v231, v[64:79]
	v_mfma_f32_32x32x2_f32 v[16:31], v96, v200, v[16:31]
	v_mfma_f32_32x32x2_f32 v[32:47], v96, v232, v[32:47]
	v_mfma_f32_32x32x2_f32 v[48:63], v128, v200, v[48:63]
	v_mfma_f32_32x32x2_f32 v[64:79], v128, v232, v[64:79]
	v_mfma_f32_32x32x2_f32 v[16:31], v97, v201, v[16:31]
	v_mfma_f32_32x32x2_f32 v[32:47], v97, v233, v[32:47]
	v_mfma_f32_32x32x2_f32 v[48:63], v129, v201, v[48:63]
	v_mfma_f32_32x32x2_f32 v[64:79], v129, v233, v[64:79]
	v_mfma_f32_32x32x2_f32 v[16:31], v98, v202, v[16:31]
	v_mfma_f32_32x32x2_f32 v[32:47], v98, v234, v[32:47]
	v_mfma_f32_32x32x2_f32 v[48:63], v130, v202, v[48:63]
	v_mfma_f32_32x32x2_f32 v[64:79], v130, v234, v[64:79]
	v_mfma_f32_32x32x2_f32 v[16:31], v99, v203, v[16:31]
	v_mfma_f32_32x32x2_f32 v[32:47], v99, v235, v[32:47]
	v_mfma_f32_32x32x2_f32 v[48:63], v131, v203, v[48:63]
	v_mfma_f32_32x32x2_f32 v[64:79], v131, v235, v[64:79]
	v_mfma_f32_32x32x2_f32 v[16:31], v100, v204, v[16:31]
	v_mfma_f32_32x32x2_f32 v[32:47], v100, v244, v[32:47]
	v_mfma_f32_32x32x2_f32 v[48:63], v132, v204, v[48:63]
	v_mfma_f32_32x32x2_f32 v[64:79], v132, v244, v[64:79]
	v_mfma_f32_32x32x2_f32 v[16:31], v101, v205, v[16:31]
	v_mfma_f32_32x32x2_f32 v[32:47], v101, v245, v[32:47]
	v_mfma_f32_32x32x2_f32 v[48:63], v133, v205, v[48:63]
	v_mfma_f32_32x32x2_f32 v[64:79], v133, v245, v[64:79]
	v_mfma_f32_32x32x2_f32 v[16:31], v102, v206, v[16:31]
	v_mfma_f32_32x32x2_f32 v[32:47], v102, v246, v[32:47]
	v_mfma_f32_32x32x2_f32 v[48:63], v134, v206, v[48:63]
	v_mfma_f32_32x32x2_f32 v[64:79], v134, v246, v[64:79]
	v_mfma_f32_32x32x2_f32 v[16:31], v103, v207, v[16:31]
	v_mfma_f32_32x32x2_f32 v[32:47], v103, v247, v[32:47]
	v_mfma_f32_32x32x2_f32 v[48:63], v135, v207, v[48:63]
	v_mfma_f32_32x32x2_f32 v[64:79], v135, v247, v[64:79]
	v_mfma_f32_32x32x2_f32 v[16:31], v104, v208, v[16:31]
	v_mfma_f32_32x32x2_f32 v[32:47], v104, v248, v[32:47]
	v_mfma_f32_32x32x2_f32 v[48:63], v136, v208, v[48:63]
	v_mfma_f32_32x32x2_f32 v[64:79], v136, v248, v[64:79]
	v_mfma_f32_32x32x2_f32 v[16:31], v105, v209, v[16:31]
	v_mfma_f32_32x32x2_f32 v[32:47], v105, v249, v[32:47]
	v_mfma_f32_32x32x2_f32 v[48:63], v137, v209, v[48:63]
	v_mfma_f32_32x32x2_f32 v[64:79], v137, v249, v[64:79]
; #define LAS __attribute__((address_space(3)))
; #define POST_LD(Y_, V_, G_, R_, C_, t) do { _Pragma("unroll") for (int q = 0; q < 8; ++q) { const size_t o_ = (size_t)((t) + q) * DH; Y_[q] = yp[o_]; V_[q] = vp[o_]; G_[q] = gp[o_]; R_[q] = rp[((t) + q) * 32]; C_[q] = cp[o_]; } } while (0)
; __device__ __forceinline__ void rw_post(Frame& F) {
;     ...
;         POST_LD(y, vv, gg, rk, cc, 0);
;         for (int t0 = 0; t0 < 64; t0 += 8) {
;             float ny[8], nv[8], nr[8], nc[8]; bf16 ng[8];
;             const int tn = t0 + 8 < 64 ? t0 + 8 : t0;
;             POST_LD(ny, nv, ng, nr, nc, tn);
;     ...
;                     for (int q = 0; q < 4; ++q) { f32x4 a = (f32x4){0.f, 0.f, 0.f, 0.f};
; #pragma unroll
;                         for (int i = 0; i < 16; ++i) a = __builtin_elementwise_fma(Sr[i], *(const LAS f32x4*)(cs + q * 64 + 4 * i), a);
;                         y[4 * hf + q] += (a[0] + a[1]) + (a[2] + a[3]); }
;                     asm volatile("s_waitcnt lgkmcnt(0)" ::: "memory"); }
;             }
	v_mfma_f32_32x32x2_f32 v[16:31], v106, v210, v[16:31]
	v_mfma_f32_32x32x2_f32 v[32:47], v106, v250, v[32:47]
	v_mfma_f32_32x32x2_f32 v[48:63], v138, v210, v[48:63]
	v_mfma_f32_32x32x2_f32 v[64:79], v138, v250, v[64:79]
	v_mfma_f32_32x32x2_f32 v[16:31], v107, v211, v[16:31]
	v_mfma_f32_32x32x2_f32 v[32:47], v107, v251, v[32:47]
	v_mfma_f32_32x32x2_f32 v[48:63], v139, v211, v[48:63]
	v_mfma_f32_32x32x2_f32 v[64:79], v139, v251, v[64:79]
	v_mfma_f32_32x32x2_f32 v[16:31], v108, v212, v[16:31]
	v_mfma_f32_32x32x2_f32 v[32:47], v108, v252, v[32:47]
	v_mfma_f32_32x32x2_f32 v[48:63], v140, v212, v[48:63]
	v_mfma_f32_32x32x2_f32 v[64:79], v140, v252, v[64:79]
	v_mfma_f32_32x32x2_f32 v[16:31], v109, v213, v[16:31]
	v_mfma_f32_32x32x2_f32 v[32:47], v109, v253, v[32:47]
	v_mfma_f32_32x32x2_f32 v[48:63], v141, v213, v[48:63]
	v_mfma_f32_32x32x2_f32 v[64:79], v141, v253, v[64:79]
	v_mfma_f32_32x32x2_f32 v[16:31], v110, v214, v[16:31]
	v_mfma_f32_32x32x2_f32 v[32:47], v110, v254, v[32:47]
	v_mfma_f32_32x32x2_f32 v[48:63], v142, v214, v[48:63]
	v_mfma_f32_32x32x2_f32 v[64:79], v142, v254, v[64:79]
	v_mfma_f32_32x32x2_f32 v[16:31], v111, v215, v[16:31]
	v_mfma_f32_32x32x2_f32 v[32:47], v111, v255, v[32:47]
	v_mfma_f32_32x32x2_f32 v[48:63], v143, v215, v[48:63]
	v_mfma_f32_32x32x2_f32 v[64:79], v143, v255, v[64:79]
	s_nop 15
	s_nop 15
	s_nop 15
	v_permlane32_swap_b32 v16, v32
	v_permlane32_swap_b32 v17, v33
	v_permlane32_swap_b32 v18, v34
	v_permlane32_swap_b32 v19, v35
	v_permlane32_swap_b32 v20, v36
	v_permlane32_swap_b32 v21, v37
	v_permlane32_swap_b32 v22, v38
	v_permlane32_swap_b32 v23, v39
	v_permlane32_swap_b32 v24, v40
	v_permlane32_swap_b32 v25, v41
	v_permlane32_swap_b32 v26, v42
	v_permlane32_swap_b32 v27, v43
	v_permlane32_swap_b32 v28, v44
	v_permlane32_swap_b32 v29, v45
	v_permlane32_swap_b32 v30, v46
	v_permlane32_swap_b32 v31, v47
	v_permlane32_swap_b32 v48, v64
	v_permlane32_swap_b32 v49, v65
	v_permlane32_swap_b32 v50, v66
	v_permlane32_swap_b32 v51, v67
	v_permlane32_swap_b32 v52, v68
	v_permlane32_swap_b32 v53, v69
	v_permlane32_swap_b32 v54, v70
	v_permlane32_swap_b32 v55, v71
	v_permlane32_swap_b32 v56, v72
	v_permlane32_swap_b32 v57, v73
	v_permlane32_swap_b32 v58, v74
	v_permlane32_swap_b32 v59, v75
	v_permlane32_swap_b32 v60, v76
	v_permlane32_swap_b32 v61, v77
	v_permlane32_swap_b32 v62, v78
	v_permlane32_swap_b32 v63, v79
	s_branch .Lpo_s1done
.Lpo_zero:
	v_mov_b32_e32 v16, 0
	v_mov_b32_e32 v17, 0
	v_mov_b32_e32 v18, 0
	v_mov_b32_e32 v19, 0
	v_mov_b32_e32 v20, 0
	v_mov_b32_e32 v21, 0
	v_mov_b32_e32 v22, 0
	v_mov_b32_e32 v23, 0
	v_mov_b32_e32 v24, 0
	v_mov_b32_e32 v25, 0
	v_mov_b32_e32 v26, 0
	v_mov_b32_e32 v27, 0
	v_mov_b32_e32 v28, 0
	v_mov_b32_e32 v29, 0
	v_mov_b32_e32 v30, 0
	v_mov_b32_e32 v31, 0
	v_mov_b32_e32 v32, 0
	v_mov_b32_e32 v33, 0
	v_mov_b32_e32 v34, 0
	v_mov_b32_e32 v35, 0
	v_mov_b32_e32 v36, 0
	v_mov_b32_e32 v37, 0
	v_mov_b32_e32 v38, 0
	v_mov_b32_e32 v39, 0
	v_mov_b32_e32 v40, 0
	v_mov_b32_e32 v41, 0
	v_mov_b32_e32 v42, 0
	v_mov_b32_e32 v43, 0
	v_mov_b32_e32 v44, 0
	v_mov_b32_e32 v45, 0
	v_mov_b32_e32 v46, 0
	v_mov_b32_e32 v47, 0
	v_mov_b32_e32 v48, 0
	v_mov_b32_e32 v49, 0
	v_mov_b32_e32 v50, 0
	v_mov_b32_e32 v51, 0
	v_mov_b32_e32 v52, 0
	v_mov_b32_e32 v53, 0
	v_mov_b32_e32 v54, 0
	v_mov_b32_e32 v55, 0
	v_mov_b32_e32 v56, 0
	v_mov_b32_e32 v57, 0
	v_mov_b32_e32 v58, 0
	v_mov_b32_e32 v59, 0
	v_mov_b32_e32 v60, 0
	v_mov_b32_e32 v61, 0
	v_mov_b32_e32 v62, 0
	v_mov_b32_e32 v63, 0
	v_mov_b32_e32 v64, 0
	v_mov_b32_e32 v65, 0
	v_mov_b32_e32 v66, 0
	v_mov_b32_e32 v67, 0
	v_mov_b32_e32 v68, 0
	v_mov_b32_e32 v69, 0
	v_mov_b32_e32 v70, 0
	v_mov_b32_e32 v71, 0
	v_mov_b32_e32 v72, 0
	v_mov_b32_e32 v73, 0
	v_mov_b32_e32 v74, 0
	v_mov_b32_e32 v75, 0
	v_mov_b32_e32 v76, 0
	v_mov_b32_e32 v77, 0
	v_mov_b32_e32 v78, 0
	v_mov_b32_e32 v79, 0
.Lpo_s1done:
	s_barrier
	global_load_dwordx4 v[120:123], v11, s[6:7]
	global_load_dwordx4 v[124:127], v11, s[6:7] offset:1024
	global_load_dwordx4 v[128:131], v11, s[8:9]
	global_load_dwordx4 v[132:135], v11, s[8:9] offset:1024
	global_load_dwordx4 v[136:139], v11, s[10:11]
	global_load_dword v159, v158, s[12:13]
	s_add_u32 s6, s6, 0x10000
	s_addc_u32 s7, s7, 0
	s_add_u32 s8, s8, 0x10000
	s_addc_u32 s9, s9, 0
	s_add_u32 s10, s10, 0x8000
	s_addc_u32 s11, s11, 0
	s_add_u32 s12, s12, 0x400
	s_addc_u32 s13, s13, 0
	s_waitcnt vmcnt(0)
	s_waitcnt vmcnt(8)
	ds_write_b128 v12, v[120:123] offset:0
	ds_write_b128 v12, v[124:127] offset:1024
	ds_write_b128 v12, v[128:131] offset:16384
	ds_write_b128 v12, v[132:135] offset:17408
	ds_write_b128 v14, v[136:139]
	v_readlane_b32 s69, v159, 0
	v_readlane_b32 s70, v159, 1
	v_readlane_b32 s71, v159, 2
	v_readlane_b32 s72, v159, 3
	v_readlane_b32 s73, v159, 4
	v_readlane_b32 s26, v159, 5
	v_readlane_b32 s27, v159, 6
	v_readlane_b32 s32, v159, 7
	global_load_dwordx4 v[120:123], v11, s[6:7]
	global_load_dwordx4 v[124:127], v11, s[6:7] offset:1024
	global_load_dwordx4 v[128:131], v11, s[8:9]
	global_load_dwordx4 v[132:135], v11, s[8:9] offset:1024
	global_load_dwordx4 v[136:139], v11, s[10:11]
	global_load_dword v159, v158, s[12:13]
	s_add_u32 s6, s6, 0x10000
	s_addc_u32 s7, s7, 0
	s_add_u32 s8, s8, 0x10000
	s_addc_u32 s9, s9, 0
	s_add_u32 s10, s10, 0x8000
	s_addc_u32 s11, s11, 0
	s_add_u32 s12, s12, 0x400
	s_addc_u32 s13, s13, 0
	s_waitcnt lgkmcnt(0)
	s_barrier
; __device__ __forceinline__ float bf2f(bf16 x) { return __uint_as_float(((unsigned)x) << 16); }
; __device__ __forceinline__ unsigned f2bf(float f) { return cvt_pk_bf16(f, 0.f) & 0xffffu; }
; __device__ __forceinline__ void rw_post(Frame& F) {
;     ...
;                         y[4 * hf + q] += (a[0] + a[1]) + (a[2] + a[3]); }
;                     asm volatile("s_waitcnt lgkmcnt(0)" ::: "memory"); }
;             }
; #pragma unroll
;             for (int q = 0; q < 8; ++q) { const int row = rb0 + t0 + q;
;                 const float mean = wsum(y[q]) * (1.f / 64.f); const float dv = y[q] - mean; const float var = wsum(dv * dv) * (1.f / 64.f);
;                 const float yn = dv * (1.f / sqrtf(var + 64e-5f)) * g_ + b_;
;                 OB[(size_t)row * DH + col] = (bf16)f2bf((yn + rk[q] * vv[q]) * bf2f(gg[q])); }
	ds_read_b32 v80, v154 offset:0
	ds_read_b32 v81, v154 offset:16384
	ds_read_u16 v83, v156 offset:0
	ds_read_b32 v85, v154 offset:2048
	ds_read_b32 v86, v154 offset:18432
	ds_read_u16 v88, v156 offset:1024
	ds_read_b32 v90, v154 offset:4096
	ds_read_b32 v91, v154 offset:20480
	ds_read_u16 v93, v156 offset:2048
	ds_read_b32 v95, v154 offset:6144
	ds_read_b32 v96, v154 offset:22528
	ds_read_u16 v98, v156 offset:3072
	ds_read_b32 v100, v154 offset:8192
	ds_read_b32 v101, v154 offset:24576
	ds_read_u16 v103, v156 offset:4096
	ds_read_b32 v105, v154 offset:10240
	ds_read_b32 v106, v154 offset:26624
	ds_read_u16 v108, v156 offset:5120
	ds_read_b32 v110, v154 offset:12288
	ds_read_b32 v111, v154 offset:28672
	ds_read_u16 v113, v156 offset:6144
	ds_read_b32 v115, v154 offset:14336
	ds_read_b32 v116, v154 offset:30720
	ds_read_u16 v118, v156 offset:7168
	s_waitcnt lgkmcnt(0)
	v_add_f32_e32 v80, v80, v16
	v_add_f32_e32 v85, v85, v17
	v_add_f32_e32 v90, v90, v18
	v_add_f32_e32 v95, v95, v19
	v_add_f32_dpp v168, v80, v80 quad_perm:[1,0,3,2] row_mask:0xf bank_mask:0xf bound_ctrl:1
	v_add_f32_dpp v174, v85, v85 quad_perm:[1,0,3,2] row_mask:0xf bank_mask:0xf bound_ctrl:1
	v_add_f32_dpp v241, v90, v90 quad_perm:[1,0,3,2] row_mask:0xf bank_mask:0xf bound_ctrl:1
	v_add_f32_dpp v247, v95, v95 quad_perm:[1,0,3,2] row_mask:0xf bank_mask:0xf bound_ctrl:1
	v_add_f32_dpp v168, v168, v168 quad_perm:[2,3,0,1] row_mask:0xf bank_mask:0xf bound_ctrl:1
	v_add_f32_dpp v174, v174, v174 quad_perm:[2,3,0,1] row_mask:0xf bank_mask:0xf bound_ctrl:1
	v_add_f32_dpp v241, v241, v241 quad_perm:[2,3,0,1] row_mask:0xf bank_mask:0xf bound_ctrl:1
	v_add_f32_dpp v247, v247, v247 quad_perm:[2,3,0,1] row_mask:0xf bank_mask:0xf bound_ctrl:1
	v_add_f32_dpp v168, v168, v168 row_half_mirror row_mask:0xf bank_mask:0xf bound_ctrl:1
	v_add_f32_dpp v174, v174, v174 row_half_mirror row_mask:0xf bank_mask:0xf bound_ctrl:1
	v_add_f32_dpp v241, v241, v241 row_half_mirror row_mask:0xf bank_mask:0xf bound_ctrl:1
	v_add_f32_dpp v247, v247, v247 row_half_mirror row_mask:0xf bank_mask:0xf bound_ctrl:1
	v_add_f32_dpp v168, v168, v168 row_mirror row_mask:0xf bank_mask:0xf bound_ctrl:1
	v_add_f32_dpp v174, v174, v174 row_mirror row_mask:0xf bank_mask:0xf bound_ctrl:1
	v_add_f32_dpp v241, v241, v241 row_mirror row_mask:0xf bank_mask:0xf bound_ctrl:1
	v_add_f32_dpp v247, v247, v247 row_mirror row_mask:0xf bank_mask:0xf bound_ctrl:1
	v_readlane_b32 s36, v168, 16
	v_readlane_b32 s40, v174, 16
	v_readlane_b32 s44, v241, 16
	v_readlane_b32 s48, v247, 16
	v_readlane_b32 s37, v168, 48
	v_readlane_b32 s41, v174, 48
	v_readlane_b32 s45, v241, 48
	v_readlane_b32 s49, v247, 48
	v_readlane_b32 s38, v168, 0
	v_readlane_b32 s42, v174, 0
	v_readlane_b32 s46, v241, 0
	v_readlane_b32 s50, v247, 0
	v_readlane_b32 s39, v168, 32
	v_readlane_b32 s43, v174, 32
	v_readlane_b32 s47, v241, 32
	v_readlane_b32 s51, v247, 32
	v_mov_b32_e32 v168, s36
	v_mov_b32_e32 v174, s40
	v_mov_b32_e32 v241, s44
	v_mov_b32_e32 v247, s48
	v_mov_b32_e32 v169, s37
	v_mov_b32_e32 v175, s41
	v_mov_b32_e32 v242, s45
	v_mov_b32_e32 v248, s49
	v_add_f32_e32 v168, s38, v168
	v_add_f32_e32 v174, s42, v174
	v_add_f32_e32 v241, s46, v241
	v_add_f32_e32 v247, s50, v247
	v_add_f32_e32 v169, s39, v169
	v_add_f32_e32 v175, s43, v175
	v_add_f32_e32 v242, s47, v242
	v_add_f32_e32 v248, s51, v248
	v_add_f32_e32 v168, v168, v169
	v_add_f32_e32 v174, v174, v175
	v_add_f32_e32 v241, v241, v242
	v_add_f32_e32 v247, v247, v248
	v_fmamk_f32 v80, v168, 0xbc800000, v80
	v_fmamk_f32 v85, v174, 0xbc800000, v85
	v_fmamk_f32 v90, v241, 0xbc800000, v90
	v_fmamk_f32 v95, v247, 0xbc800000, v95
	v_mul_f32_e32 v168, v80, v80
	v_mul_f32_e32 v174, v85, v85
	v_mul_f32_e32 v241, v90, v90
	v_mul_f32_e32 v247, v95, v95
	v_mov_b32_dpp v168, v168 quad_perm:[1,0,3,2] row_mask:0xf bank_mask:0xf bound_ctrl:1
	v_mov_b32_dpp v174, v174 quad_perm:[1,0,3,2] row_mask:0xf bank_mask:0xf bound_ctrl:1
	v_mov_b32_dpp v241, v241 quad_perm:[1,0,3,2] row_mask:0xf bank_mask:0xf bound_ctrl:1
	v_mov_b32_dpp v247, v247 quad_perm:[1,0,3,2] row_mask:0xf bank_mask:0xf bound_ctrl:1
	v_fmac_f32_e32 v168, v80, v80
	v_fmac_f32_e32 v174, v85, v85
	v_fmac_f32_e32 v241, v90, v90
	v_fmac_f32_e32 v247, v95, v95
	v_add_f32_dpp v168, v168, v168 quad_perm:[2,3,0,1] row_mask:0xf bank_mask:0xf bound_ctrl:1
	v_add_f32_dpp v174, v174, v174 quad_perm:[2,3,0,1] row_mask:0xf bank_mask:0xf bound_ctrl:1
	v_add_f32_dpp v241, v241, v241 quad_perm:[2,3,0,1] row_mask:0xf bank_mask:0xf bound_ctrl:1
	v_add_f32_dpp v247, v247, v247 quad_perm:[2,3,0,1] row_mask:0xf bank_mask:0xf bound_ctrl:1
	v_add_f32_dpp v168, v168, v168 row_half_mirror row_mask:0xf bank_mask:0xf bound_ctrl:1
	v_add_f32_dpp v174, v174, v174 row_half_mirror row_mask:0xf bank_mask:0xf bound_ctrl:1
	v_add_f32_dpp v241, v241, v241 row_half_mirror row_mask:0xf bank_mask:0xf bound_ctrl:1
	v_add_f32_dpp v247, v247, v247 row_half_mirror row_mask:0xf bank_mask:0xf bound_ctrl:1
	v_add_f32_dpp v168, v168, v168 row_mirror row_mask:0xf bank_mask:0xf bound_ctrl:1
	v_add_f32_dpp v174, v174, v174 row_mirror row_mask:0xf bank_mask:0xf bound_ctrl:1
	v_add_f32_dpp v241, v241, v241 row_mirror row_mask:0xf bank_mask:0xf bound_ctrl:1
	v_add_f32_dpp v247, v247, v247 row_mirror row_mask:0xf bank_mask:0xf bound_ctrl:1
	v_readlane_b32 s36, v168, 16
	v_readlane_b32 s40, v174, 16
	v_readlane_b32 s44, v241, 16
	v_readlane_b32 s48, v247, 16
	v_readlane_b32 s37, v168, 48
	v_readlane_b32 s41, v174, 48
	v_readlane_b32 s45, v241, 48
	v_readlane_b32 s49, v247, 48
	v_readlane_b32 s38, v168, 0
	v_readlane_b32 s42, v174, 0
	v_readlane_b32 s46, v241, 0
	v_readlane_b32 s50, v247, 0
	v_readlane_b32 s39, v168, 32
; __device__ __forceinline__ float bf2f(bf16 x) { return __uint_as_float(((unsigned)x) << 16); }
; __device__ __forceinline__ unsigned f2bf(float f) { return cvt_pk_bf16(f, 0.f) & 0xffffu; }
; __device__ __forceinline__ void rw_post(Frame& F) {
;     ...
;                 const float mean = wsum(y[q]) * (1.f / 64.f); const float dv = y[q] - mean; const float var = wsum(dv * dv) * (1.f / 64.f);
;                 const float yn = dv * (1.f / sqrtf(var + 64e-5f)) * g_ + b_;
;                 OB[(size_t)row * DH + col] = (bf16)f2bf((yn + rk[q] * vv[q]) * bf2f(gg[q])); }
	v_readlane_b32 s43, v174, 32
	v_readlane_b32 s47, v241, 32
	v_readlane_b32 s51, v247, 32
	v_mov_b32_e32 v168, s36
	v_mov_b32_e32 v174, s40
	v_mov_b32_e32 v241, s44
	v_mov_b32_e32 v247, s48
	v_mov_b32_e32 v169, s37
	v_mov_b32_e32 v175, s41
	v_mov_b32_e32 v242, s45
	v_mov_b32_e32 v248, s49
	v_add_f32_e32 v168, s38, v168
	v_add_f32_e32 v174, s42, v174
	v_add_f32_e32 v241, s46, v241
	v_add_f32_e32 v247, s50, v247
	v_add_f32_e32 v169, s39, v169
	v_add_f32_e32 v175, s43, v175
	v_add_f32_e32 v242, s47, v242
	v_add_f32_e32 v248, s51, v248
	v_add_f32_e32 v168, v168, v169
	v_add_f32_e32 v174, v174, v175
	v_add_f32_e32 v241, v241, v242
	v_add_f32_e32 v247, v247, v248
	v_fmamk_f32 v168, v168, 0x3c800000, v9
	v_fmamk_f32 v174, v174, 0x3c800000, v9
	v_fmamk_f32 v241, v241, 0x3c800000, v9
	v_fmamk_f32 v247, v247, 0x3c800000, v9
	v_mul_f32_e32 v169, 0x4f800000, v168
	v_mul_f32_e32 v175, 0x4f800000, v174
	v_mul_f32_e32 v242, 0x4f800000, v241
	v_mul_f32_e32 v248, 0x4f800000, v247
	v_cmp_gt_f32_e64 s[52:53], s68, v168
	v_cmp_gt_f32_e64 s[54:55], s68, v174
	v_cmp_gt_f32_e64 s[56:57], s68, v241
	v_cmp_gt_f32_e64 s[58:59], s68, v247
	v_mov_b32_e32 v170, v168
	v_mov_b32_e32 v176, v174
	v_mov_b32_e32 v243, v241
	v_mov_b32_e32 v249, v247
	v_cndmask_b32_e64 v168, v170, v169, s[52:53]
	v_cndmask_b32_e64 v174, v176, v175, s[54:55]
	v_cndmask_b32_e64 v241, v243, v242, s[56:57]
	v_cndmask_b32_e64 v247, v249, v248, s[58:59]
	v_sqrt_f32_e32 v169, v168
	v_sqrt_f32_e32 v175, v174
	v_sqrt_f32_e32 v242, v241
	v_sqrt_f32_e32 v248, v247
	v_add_u32_e32 v170, -1, v169
	v_add_u32_e32 v176, -1, v175
	v_add_u32_e32 v243, -1, v242
	v_add_u32_e32 v249, -1, v248
	v_fma_f32 v171, -v170, v169, v168
	v_fma_f32 v177, -v176, v175, v174
	v_fma_f32 v244, -v243, v242, v241
	v_fma_f32 v250, -v249, v248, v247
	v_cmp_ge_f32_e64 s[60:61], 0, v171
	v_cmp_ge_f32_e64 s[62:63], 0, v177
	v_cmp_ge_f32_e64 s[64:65], 0, v244
	v_cmp_ge_f32_e64 s[66:67], 0, v250
	v_add_u32_e32 v171, 1, v169
	v_add_u32_e32 v177, 1, v175
	v_add_u32_e32 v244, 1, v242
	v_add_u32_e32 v250, 1, v248
	v_cndmask_b32_e64 v170, v169, v170, s[60:61]
	v_cndmask_b32_e64 v176, v175, v176, s[62:63]
	v_cndmask_b32_e64 v243, v242, v243, s[64:65]
	v_cndmask_b32_e64 v249, v248, v249, s[66:67]
	v_fma_f32 v169, -v171, v169, v168
	v_fma_f32 v175, -v177, v175, v174
	v_fma_f32 v242, -v244, v242, v241
	v_fma_f32 v248, -v250, v248, v247
	v_cmp_lt_f32_e64 s[60:61], 0, v169
	v_cmp_lt_f32_e64 s[62:63], 0, v175
	v_cmp_lt_f32_e64 s[64:65], 0, v242
	v_cmp_lt_f32_e64 s[66:67], 0, v248
	v_cndmask_b32_e64 v169, v170, v171, s[60:61]
	v_cndmask_b32_e64 v175, v176, v177, s[62:63]
	v_cndmask_b32_e64 v242, v243, v244, s[64:65]
	v_cndmask_b32_e64 v248, v249, v250, s[66:67]
	v_mul_f32_e32 v170, 0x37800000, v169
	v_mul_f32_e32 v176, 0x37800000, v175
	v_mul_f32_e32 v243, 0x37800000, v242
	v_mul_f32_e32 v249, 0x37800000, v248
	v_cndmask_b32_e64 v169, v169, v170, s[52:53]
	v_cndmask_b32_e64 v175, v175, v176, s[54:55]
	v_cndmask_b32_e64 v242, v242, v243, s[56:57]
	v_cndmask_b32_e64 v248, v248, v249, s[58:59]
	v_cmp_class_f32_e64 s[60:61], v168, v8
	v_cmp_class_f32_e64 s[62:63], v174, v8
	v_cmp_class_f32_e64 s[64:65], v241, v8
	v_cmp_class_f32_e64 s[66:67], v247, v8
	v_cndmask_b32_e64 v168, v169, v168, s[60:61]
	v_cndmask_b32_e64 v174, v175, v174, s[62:63]
	v_cndmask_b32_e64 v241, v242, v241, s[64:65]
	v_cndmask_b32_e64 v247, v248, v247, s[66:67]
	v_div_scale_f32 v169, s[60:61], v168, v168, 1.0
	v_rcp_f32_e32 v170, v169
	s_nop 0
	v_fma_f32 v171, -v169, v170, 1.0
	v_fmac_f32_e32 v170, v171, v170
	v_div_scale_f32 v171, vcc, 1.0, v168, 1.0
	v_mul_f32_e32 v172, v171, v170
	v_fma_f32 v173, -v169, v172, v171
	v_fmac_f32_e32 v172, v173, v170
	v_fma_f32 v169, -v169, v172, v171
	v_div_fmas_f32 v169, v169, v170, v172
	v_div_fixup_f32 v168, v169, v168, 1.0
	v_div_scale_f32 v175, s[62:63], v174, v174, 1.0
	v_rcp_f32_e32 v176, v175
	s_nop 0
	v_fma_f32 v177, -v175, v176, 1.0
	v_fmac_f32_e32 v176, v177, v176
	v_div_scale_f32 v177, vcc, 1.0, v174, 1.0
	v_mul_f32_e32 v236, v177, v176
	v_fma_f32 v237, -v175, v236, v177
	v_fmac_f32_e32 v236, v237, v176
	v_fma_f32 v175, -v175, v236, v177
	v_div_fmas_f32 v175, v175, v176, v236
	v_div_fixup_f32 v174, v175, v174, 1.0
	v_div_scale_f32 v242, s[64:65], v241, v241, 1.0
	v_rcp_f32_e32 v243, v242
	s_nop 0
	v_fma_f32 v244, -v242, v243, 1.0
	v_fmac_f32_e32 v243, v244, v243
	v_div_scale_f32 v244, vcc, 1.0, v241, 1.0
	v_mul_f32_e32 v245, v244, v243
	v_fma_f32 v246, -v242, v245, v244
	v_fmac_f32_e32 v245, v246, v243
	v_fma_f32 v242, -v242, v245, v244
	v_div_fmas_f32 v242, v242, v243, v245
	v_div_fixup_f32 v241, v242, v241, 1.0
	v_div_scale_f32 v248, s[66:67], v247, v247, 1.0
	v_rcp_f32_e32 v249, v248
	s_nop 0
	v_fma_f32 v250, -v248, v249, 1.0
	v_fmac_f32_e32 v249, v250, v249
	v_div_scale_f32 v250, vcc, 1.0, v247, 1.0
	v_mul_f32_e32 v251, v250, v249
	v_fma_f32 v252, -v248, v251, v250
	v_fmac_f32_e32 v251, v252, v249
	v_fma_f32 v248, -v248, v251, v250
	v_div_fmas_f32 v248, v248, v249, v251
	v_div_fixup_f32 v247, v248, v247, 1.0
	v_mul_f32_e32 v80, v80, v168
	v_mul_f32_e32 v85, v85, v174
	v_mul_f32_e32 v90, v90, v241
	v_mul_f32_e32 v95, v95, v247
	v_lshlrev_b32_e32 v83, 16, v83
	v_lshlrev_b32_e32 v88, 16, v88
	v_lshlrev_b32_e32 v93, 16, v93
	v_lshlrev_b32_e32 v98, 16, v98
	v_fma_f32 v80, v6, v80, v7
	v_fma_f32 v85, v6, v85, v7
	v_fma_f32 v90, v6, v90, v7
	v_fma_f32 v95, v6, v95, v7
	v_fmac_f32_e32 v80, s69, v81
	v_fmac_f32_e32 v85, s70, v86
	v_fmac_f32_e32 v90, s71, v91
	v_fmac_f32_e32 v95, s72, v96
	v_mul_f32_e32 v80, v80, v83
	v_mul_f32_e32 v85, v85, v88
	v_mul_f32_e32 v90, v90, v93
	v_mul_f32_e32 v95, v95, v98
	v_cvt_pk_bf16_f32 v169, v80, v80
; __device__ __forceinline__ float bf2f(bf16 x) { return __uint_as_float(((unsigned)x) << 16); }
; __device__ __forceinline__ unsigned f2bf(float f) { return cvt_pk_bf16(f, 0.f) & 0xffffu; }
; __device__ __forceinline__ void rw_post(Frame& F) {
;     ...
;             for (int q = 0; q < 8; ++q) { const int row = rb0 + t0 + q;
;                 const float mean = wsum(y[q]) * (1.f / 64.f); const float dv = y[q] - mean; const float var = wsum(dv * dv) * (1.f / 64.f);
;                 const float yn = dv * (1.f / sqrtf(var + 64e-5f)) * g_ + b_;
;                 OB[(size_t)row * DH + col] = (bf16)f2bf((yn + rk[q] * vv[q]) * bf2f(gg[q])); }
	v_cvt_pk_bf16_f32 v175, v85, v85
	v_cvt_pk_bf16_f32 v242, v90, v90
	v_cvt_pk_bf16_f32 v248, v95, v95
	global_store_short v2, v169, s[28:29]
	s_add_u32 s28, s28, 0x1000
	s_addc_u32 s29, s29, 0
	global_store_short v2, v175, s[28:29]
	s_add_u32 s28, s28, 0x1000
	s_addc_u32 s29, s29, 0
	global_store_short v2, v242, s[28:29]
	s_add_u32 s28, s28, 0x1000
	s_addc_u32 s29, s29, 0
	global_store_short v2, v248, s[28:29]
	s_add_u32 s28, s28, 0x1000
	s_addc_u32 s29, s29, 0
	v_add_f32_e32 v100, v100, v32
	v_add_f32_e32 v105, v105, v33
	v_add_f32_e32 v110, v110, v34
	v_add_f32_e32 v115, v115, v35
	v_add_f32_dpp v168, v100, v100 quad_perm:[1,0,3,2] row_mask:0xf bank_mask:0xf bound_ctrl:1
	v_add_f32_dpp v174, v105, v105 quad_perm:[1,0,3,2] row_mask:0xf bank_mask:0xf bound_ctrl:1
	v_add_f32_dpp v241, v110, v110 quad_perm:[1,0,3,2] row_mask:0xf bank_mask:0xf bound_ctrl:1
	v_add_f32_dpp v247, v115, v115 quad_perm:[1,0,3,2] row_mask:0xf bank_mask:0xf bound_ctrl:1
	v_add_f32_dpp v168, v168, v168 quad_perm:[2,3,0,1] row_mask:0xf bank_mask:0xf bound_ctrl:1
	v_add_f32_dpp v174, v174, v174 quad_perm:[2,3,0,1] row_mask:0xf bank_mask:0xf bound_ctrl:1
	v_add_f32_dpp v241, v241, v241 quad_perm:[2,3,0,1] row_mask:0xf bank_mask:0xf bound_ctrl:1
	v_add_f32_dpp v247, v247, v247 quad_perm:[2,3,0,1] row_mask:0xf bank_mask:0xf bound_ctrl:1
	v_add_f32_dpp v168, v168, v168 row_half_mirror row_mask:0xf bank_mask:0xf bound_ctrl:1
	v_add_f32_dpp v174, v174, v174 row_half_mirror row_mask:0xf bank_mask:0xf bound_ctrl:1
	v_add_f32_dpp v241, v241, v241 row_half_mirror row_mask:0xf bank_mask:0xf bound_ctrl:1
	v_add_f32_dpp v247, v247, v247 row_half_mirror row_mask:0xf bank_mask:0xf bound_ctrl:1
	v_add_f32_dpp v168, v168, v168 row_mirror row_mask:0xf bank_mask:0xf bound_ctrl:1
	v_add_f32_dpp v174, v174, v174 row_mirror row_mask:0xf bank_mask:0xf bound_ctrl:1
	v_add_f32_dpp v241, v241, v241 row_mirror row_mask:0xf bank_mask:0xf bound_ctrl:1
	v_add_f32_dpp v247, v247, v247 row_mirror row_mask:0xf bank_mask:0xf bound_ctrl:1
	v_readlane_b32 s36, v168, 16
	v_readlane_b32 s40, v174, 16
	v_readlane_b32 s44, v241, 16
	v_readlane_b32 s48, v247, 16
	v_readlane_b32 s37, v168, 48
	v_readlane_b32 s41, v174, 48
	v_readlane_b32 s45, v241, 48
	v_readlane_b32 s49, v247, 48
	v_readlane_b32 s38, v168, 0
	v_readlane_b32 s42, v174, 0
	v_readlane_b32 s46, v241, 0
	v_readlane_b32 s50, v247, 0
	v_readlane_b32 s39, v168, 32
	v_readlane_b32 s43, v174, 32
	v_readlane_b32 s47, v241, 32
	v_readlane_b32 s51, v247, 32
	v_mov_b32_e32 v168, s36
	v_mov_b32_e32 v174, s40
	v_mov_b32_e32 v241, s44
	v_mov_b32_e32 v247, s48
	v_mov_b32_e32 v169, s37
	v_mov_b32_e32 v175, s41
	v_mov_b32_e32 v242, s45
	v_mov_b32_e32 v248, s49
	v_add_f32_e32 v168, s38, v168
	v_add_f32_e32 v174, s42, v174
	v_add_f32_e32 v241, s46, v241
	v_add_f32_e32 v247, s50, v247
	v_add_f32_e32 v169, s39, v169
	v_add_f32_e32 v175, s43, v175
	v_add_f32_e32 v242, s47, v242
	v_add_f32_e32 v248, s51, v248
	v_add_f32_e32 v168, v168, v169
	v_add_f32_e32 v174, v174, v175
	v_add_f32_e32 v241, v241, v242
	v_add_f32_e32 v247, v247, v248
	v_fmamk_f32 v100, v168, 0xbc800000, v100
	v_fmamk_f32 v105, v174, 0xbc800000, v105
	v_fmamk_f32 v110, v241, 0xbc800000, v110
	v_fmamk_f32 v115, v247, 0xbc800000, v115
	v_mul_f32_e32 v168, v100, v100
	v_mul_f32_e32 v174, v105, v105
	v_mul_f32_e32 v241, v110, v110
	v_mul_f32_e32 v247, v115, v115
	v_mov_b32_dpp v168, v168 quad_perm:[1,0,3,2] row_mask:0xf bank_mask:0xf bound_ctrl:1
	v_mov_b32_dpp v174, v174 quad_perm:[1,0,3,2] row_mask:0xf bank_mask:0xf bound_ctrl:1
	v_mov_b32_dpp v241, v241 quad_perm:[1,0,3,2] row_mask:0xf bank_mask:0xf bound_ctrl:1
	v_mov_b32_dpp v247, v247 quad_perm:[1,0,3,2] row_mask:0xf bank_mask:0xf bound_ctrl:1
	v_fmac_f32_e32 v168, v100, v100
	v_fmac_f32_e32 v174, v105, v105
	v_fmac_f32_e32 v241, v110, v110
	v_fmac_f32_e32 v247, v115, v115
	v_add_f32_dpp v168, v168, v168 quad_perm:[2,3,0,1] row_mask:0xf bank_mask:0xf bound_ctrl:1
	v_add_f32_dpp v174, v174, v174 quad_perm:[2,3,0,1] row_mask:0xf bank_mask:0xf bound_ctrl:1
	v_add_f32_dpp v241, v241, v241 quad_perm:[2,3,0,1] row_mask:0xf bank_mask:0xf bound_ctrl:1
	v_add_f32_dpp v247, v247, v247 quad_perm:[2,3,0,1] row_mask:0xf bank_mask:0xf bound_ctrl:1
	v_add_f32_dpp v168, v168, v168 row_half_mirror row_mask:0xf bank_mask:0xf bound_ctrl:1
	v_add_f32_dpp v174, v174, v174 row_half_mirror row_mask:0xf bank_mask:0xf bound_ctrl:1
	v_add_f32_dpp v241, v241, v241 row_half_mirror row_mask:0xf bank_mask:0xf bound_ctrl:1
	v_add_f32_dpp v247, v247, v247 row_half_mirror row_mask:0xf bank_mask:0xf bound_ctrl:1
	v_add_f32_dpp v168, v168, v168 row_mirror row_mask:0xf bank_mask:0xf bound_ctrl:1
	v_add_f32_dpp v174, v174, v174 row_mirror row_mask:0xf bank_mask:0xf bound_ctrl:1
	v_add_f32_dpp v241, v241, v241 row_mirror row_mask:0xf bank_mask:0xf bound_ctrl:1
	v_add_f32_dpp v247, v247, v247 row_mirror row_mask:0xf bank_mask:0xf bound_ctrl:1
	v_readlane_b32 s36, v168, 16
	v_readlane_b32 s40, v174, 16
	v_readlane_b32 s44, v241, 16
	v_readlane_b32 s48, v247, 16
	v_readlane_b32 s37, v168, 48
	v_readlane_b32 s41, v174, 48
	v_readlane_b32 s45, v241, 48
	v_readlane_b32 s49, v247, 48
	v_readlane_b32 s38, v168, 0
	v_readlane_b32 s42, v174, 0
	v_readlane_b32 s46, v241, 0
	v_readlane_b32 s50, v247, 0
	v_readlane_b32 s39, v168, 32
	v_readlane_b32 s43, v174, 32
	v_readlane_b32 s47, v241, 32
	v_readlane_b32 s51, v247, 32
	v_mov_b32_e32 v168, s36
	v_mov_b32_e32 v174, s40
	v_mov_b32_e32 v241, s44
	v_mov_b32_e32 v247, s48
	v_mov_b32_e32 v169, s37
	v_mov_b32_e32 v175, s41
	v_mov_b32_e32 v242, s45
	v_mov_b32_e32 v248, s49
	v_add_f32_e32 v168, s38, v168
	v_add_f32_e32 v174, s42, v174
	v_add_f32_e32 v241, s46, v241
; __device__ __forceinline__ float bf2f(bf16 x) { return __uint_as_float(((unsigned)x) << 16); }
; __device__ __forceinline__ unsigned f2bf(float f) { return cvt_pk_bf16(f, 0.f) & 0xffffu; }
; #define POST_LD(Y_, V_, G_, R_, C_, t) do { _Pragma("unroll") for (int q = 0; q < 8; ++q) { const size_t o_ = (size_t)((t) + q) * DH; Y_[q] = yp[o_]; V_[q] = vp[o_]; G_[q] = gp[o_]; R_[q] = rp[((t) + q) * 32]; C_[q] = cp[o_]; } } while (0)
; __device__ __forceinline__ void rw_post(Frame& F) {
;     ...
;             POST_LD(ny, nv, ng, nr, nc, tn);
;     ...
;                 const float mean = wsum(y[q]) * (1.f / 64.f); const float dv = y[q] - mean; const float var = wsum(dv * dv) * (1.f / 64.f);
;                 const float yn = dv * (1.f / sqrtf(var + 64e-5f)) * g_ + b_;
;                 OB[(size_t)row * DH + col] = (bf16)f2bf((yn + rk[q] * vv[q]) * bf2f(gg[q])); }
; #pragma unroll
;             for (int q = 0; q < 8; ++q) { y[q] = ny[q]; vv[q] = nv[q]; gg[q] = ng[q]; rk[q] = nr[q]; cc[q] = nc[q]; }
	v_add_f32_e32 v247, s50, v247
	v_add_f32_e32 v169, s39, v169
	v_add_f32_e32 v175, s43, v175
	v_add_f32_e32 v242, s47, v242
	v_add_f32_e32 v248, s51, v248
	v_add_f32_e32 v168, v168, v169
	v_add_f32_e32 v174, v174, v175
	v_add_f32_e32 v241, v241, v242
	v_add_f32_e32 v247, v247, v248
	v_fmamk_f32 v168, v168, 0x3c800000, v9
	v_fmamk_f32 v174, v174, 0x3c800000, v9
	v_fmamk_f32 v241, v241, 0x3c800000, v9
	v_fmamk_f32 v247, v247, 0x3c800000, v9
	v_mul_f32_e32 v169, 0x4f800000, v168
	v_mul_f32_e32 v175, 0x4f800000, v174
	v_mul_f32_e32 v242, 0x4f800000, v241
	v_mul_f32_e32 v248, 0x4f800000, v247
	v_cmp_gt_f32_e64 s[52:53], s68, v168
	v_cmp_gt_f32_e64 s[54:55], s68, v174
	v_cmp_gt_f32_e64 s[56:57], s68, v241
	v_cmp_gt_f32_e64 s[58:59], s68, v247
	v_mov_b32_e32 v170, v168
	v_mov_b32_e32 v176, v174
	v_mov_b32_e32 v243, v241
	v_mov_b32_e32 v249, v247
	v_cndmask_b32_e64 v168, v170, v169, s[52:53]
	v_cndmask_b32_e64 v174, v176, v175, s[54:55]
	v_cndmask_b32_e64 v241, v243, v242, s[56:57]
	v_cndmask_b32_e64 v247, v249, v248, s[58:59]
	v_sqrt_f32_e32 v169, v168
	v_sqrt_f32_e32 v175, v174
	v_sqrt_f32_e32 v242, v241
	v_sqrt_f32_e32 v248, v247
	v_add_u32_e32 v170, -1, v169
	v_add_u32_e32 v176, -1, v175
	v_add_u32_e32 v243, -1, v242
	v_add_u32_e32 v249, -1, v248
	v_fma_f32 v171, -v170, v169, v168
	v_fma_f32 v177, -v176, v175, v174
	v_fma_f32 v244, -v243, v242, v241
	v_fma_f32 v250, -v249, v248, v247
	v_cmp_ge_f32_e64 s[60:61], 0, v171
	v_cmp_ge_f32_e64 s[62:63], 0, v177
	v_cmp_ge_f32_e64 s[64:65], 0, v244
	v_cmp_ge_f32_e64 s[66:67], 0, v250
	v_add_u32_e32 v171, 1, v169
	v_add_u32_e32 v177, 1, v175
	v_add_u32_e32 v244, 1, v242
	v_add_u32_e32 v250, 1, v248
	v_cndmask_b32_e64 v170, v169, v170, s[60:61]
	v_cndmask_b32_e64 v176, v175, v176, s[62:63]
	v_cndmask_b32_e64 v243, v242, v243, s[64:65]
	v_cndmask_b32_e64 v249, v248, v249, s[66:67]
	v_fma_f32 v169, -v171, v169, v168
	v_fma_f32 v175, -v177, v175, v174
	v_fma_f32 v242, -v244, v242, v241
	v_fma_f32 v248, -v250, v248, v247
	v_cmp_lt_f32_e64 s[60:61], 0, v169
	v_cmp_lt_f32_e64 s[62:63], 0, v175
	v_cmp_lt_f32_e64 s[64:65], 0, v242
	v_cmp_lt_f32_e64 s[66:67], 0, v248
	v_cndmask_b32_e64 v169, v170, v171, s[60:61]
	v_cndmask_b32_e64 v175, v176, v177, s[62:63]
	v_cndmask_b32_e64 v242, v243, v244, s[64:65]
	v_cndmask_b32_e64 v248, v249, v250, s[66:67]
	v_mul_f32_e32 v170, 0x37800000, v169
	v_mul_f32_e32 v176, 0x37800000, v175
	v_mul_f32_e32 v243, 0x37800000, v242
	v_mul_f32_e32 v249, 0x37800000, v248
	v_cndmask_b32_e64 v169, v169, v170, s[52:53]
	v_cndmask_b32_e64 v175, v175, v176, s[54:55]
	v_cndmask_b32_e64 v242, v242, v243, s[56:57]
	v_cndmask_b32_e64 v248, v248, v249, s[58:59]
	v_cmp_class_f32_e64 s[60:61], v168, v8
	v_cmp_class_f32_e64 s[62:63], v174, v8
	v_cmp_class_f32_e64 s[64:65], v241, v8
	v_cmp_class_f32_e64 s[66:67], v247, v8
	v_cndmask_b32_e64 v168, v169, v168, s[60:61]
	v_cndmask_b32_e64 v174, v175, v174, s[62:63]
	v_cndmask_b32_e64 v241, v242, v241, s[64:65]
	v_cndmask_b32_e64 v247, v248, v247, s[66:67]
	v_div_scale_f32 v169, s[60:61], v168, v168, 1.0
	v_rcp_f32_e32 v170, v169
	s_nop 0
	v_fma_f32 v171, -v169, v170, 1.0
	v_fmac_f32_e32 v170, v171, v170
	v_div_scale_f32 v171, vcc, 1.0, v168, 1.0
	v_mul_f32_e32 v172, v171, v170
	v_fma_f32 v173, -v169, v172, v171
	v_fmac_f32_e32 v172, v173, v170
	v_fma_f32 v169, -v169, v172, v171
	v_div_fmas_f32 v169, v169, v170, v172
	v_div_fixup_f32 v168, v169, v168, 1.0
	v_div_scale_f32 v175, s[62:63], v174, v174, 1.0
	v_rcp_f32_e32 v176, v175
	s_nop 0
	v_fma_f32 v177, -v175, v176, 1.0
	v_fmac_f32_e32 v176, v177, v176
	v_div_scale_f32 v177, vcc, 1.0, v174, 1.0
	v_mul_f32_e32 v236, v177, v176
	v_fma_f32 v237, -v175, v236, v177
	v_fmac_f32_e32 v236, v237, v176
	v_fma_f32 v175, -v175, v236, v177
	v_div_fmas_f32 v175, v175, v176, v236
	v_div_fixup_f32 v174, v175, v174, 1.0
	v_div_scale_f32 v242, s[64:65], v241, v241, 1.0
	v_rcp_f32_e32 v243, v242
	s_nop 0
	v_fma_f32 v244, -v242, v243, 1.0
	v_fmac_f32_e32 v243, v244, v243
	v_div_scale_f32 v244, vcc, 1.0, v241, 1.0
	v_mul_f32_e32 v245, v244, v243
	v_fma_f32 v246, -v242, v245, v244
	v_fmac_f32_e32 v245, v246, v243
	v_fma_f32 v242, -v242, v245, v244
	v_div_fmas_f32 v242, v242, v243, v245
	v_div_fixup_f32 v241, v242, v241, 1.0
	v_div_scale_f32 v248, s[66:67], v247, v247, 1.0
	v_rcp_f32_e32 v249, v248
	s_nop 0
	v_fma_f32 v250, -v248, v249, 1.0
	v_fmac_f32_e32 v249, v250, v249
	v_div_scale_f32 v250, vcc, 1.0, v247, 1.0
	v_mul_f32_e32 v251, v250, v249
	v_fma_f32 v252, -v248, v251, v250
	v_fmac_f32_e32 v251, v252, v249
	v_fma_f32 v248, -v248, v251, v250
	v_div_fmas_f32 v248, v248, v249, v251
	v_div_fixup_f32 v247, v248, v247, 1.0
	v_mul_f32_e32 v100, v100, v168
	v_mul_f32_e32 v105, v105, v174
	v_mul_f32_e32 v110, v110, v241
	v_mul_f32_e32 v115, v115, v247
	v_lshlrev_b32_e32 v103, 16, v103
	v_lshlrev_b32_e32 v108, 16, v108
	v_lshlrev_b32_e32 v113, 16, v113
	v_lshlrev_b32_e32 v118, 16, v118
	v_fma_f32 v100, v6, v100, v7
	v_fma_f32 v105, v6, v105, v7
	v_fma_f32 v110, v6, v110, v7
	v_fma_f32 v115, v6, v115, v7
	v_fmac_f32_e32 v100, s73, v101
	v_fmac_f32_e32 v105, s26, v106
	v_fmac_f32_e32 v110, s27, v111
	v_fmac_f32_e32 v115, s32, v116
	v_mul_f32_e32 v100, v100, v103
	v_mul_f32_e32 v105, v105, v108
	v_mul_f32_e32 v110, v110, v113
	v_mul_f32_e32 v115, v115, v118
	v_cvt_pk_bf16_f32 v169, v100, v100
	v_cvt_pk_bf16_f32 v175, v105, v105
	v_cvt_pk_bf16_f32 v242, v110, v110
	v_cvt_pk_bf16_f32 v248, v115, v115
	global_store_short v2, v169, s[28:29]
	s_add_u32 s28, s28, 0x1000
	s_addc_u32 s29, s29, 0
	global_store_short v2, v175, s[28:29]
	s_add_u32 s28, s28, 0x1000
	s_addc_u32 s29, s29, 0
	global_store_short v2, v242, s[28:29]
	s_add_u32 s28, s28, 0x1000
	s_addc_u32 s29, s29, 0
	global_store_short v2, v248, s[28:29]
	s_add_u32 s28, s28, 0x1000
	s_addc_u32 s29, s29, 0
	s_waitcnt vmcnt(8)
	ds_write_b128 v13, v[120:123] offset:0
	ds_write_b128 v13, v[124:127] offset:1024
	ds_write_b128 v13, v[128:131] offset:16384
	ds_write_b128 v13, v[132:135] offset:17408
	ds_write_b128 v15, v[136:139]
	v_readlane_b32 s69, v159, 0
	v_readlane_b32 s70, v159, 1
	v_readlane_b32 s71, v159, 2
	v_readlane_b32 s72, v159, 3
	v_readlane_b32 s73, v159, 4
	v_readlane_b32 s26, v159, 5
	v_readlane_b32 s27, v159, 6
	v_readlane_b32 s32, v159, 7
	global_load_dwordx4 v[120:123], v11, s[6:7]
	global_load_dwordx4 v[124:127], v11, s[6:7] offset:1024
	global_load_dwordx4 v[128:131], v11, s[8:9]
	global_load_dwordx4 v[132:135], v11, s[8:9] offset:1024
	global_load_dwordx4 v[136:139], v11, s[10:11]
	global_load_dword v159, v158, s[12:13]
	s_add_u32 s6, s6, 0x10000
	s_addc_u32 s7, s7, 0
	s_add_u32 s8, s8, 0x10000
	s_addc_u32 s9, s9, 0
	s_add_u32 s10, s10, 0x8000
	s_addc_u32 s11, s11, 0
	s_add_u32 s12, s12, 0x400
	s_addc_u32 s13, s13, 0
	s_waitcnt lgkmcnt(0)
	s_barrier
; __device__ __forceinline__ float bf2f(bf16 x) { return __uint_as_float(((unsigned)x) << 16); }
; __device__ __forceinline__ unsigned f2bf(float f) { return cvt_pk_bf16(f, 0.f) & 0xffffu; }
; __device__ __forceinline__ void rw_post(Frame& F) {
;     ...
;                         y[4 * hf + q] += (a[0] + a[1]) + (a[2] + a[3]); }
;                     asm volatile("s_waitcnt lgkmcnt(0)" ::: "memory"); }
;             }
; #pragma unroll
;             for (int q = 0; q < 8; ++q) { const int row = rb0 + t0 + q;
;                 const float mean = wsum(y[q]) * (1.f / 64.f); const float dv = y[q] - mean; const float var = wsum(dv * dv) * (1.f / 64.f);
;                 const float yn = dv * (1.f / sqrtf(var + 64e-5f)) * g_ + b_;
;                 OB[(size_t)row * DH + col] = (bf16)f2bf((yn + rk[q] * vv[q]) * bf2f(gg[q])); }
	ds_read_b32 v80, v155 offset:0
	ds_read_b32 v81, v155 offset:16384
	ds_read_u16 v83, v157 offset:0
	ds_read_b32 v85, v155 offset:2048
	ds_read_b32 v86, v155 offset:18432
	ds_read_u16 v88, v157 offset:1024
	ds_read_b32 v90, v155 offset:4096
	ds_read_b32 v91, v155 offset:20480
	ds_read_u16 v93, v157 offset:2048
	ds_read_b32 v95, v155 offset:6144
	ds_read_b32 v96, v155 offset:22528
	ds_read_u16 v98, v157 offset:3072
	ds_read_b32 v100, v155 offset:8192
	ds_read_b32 v101, v155 offset:24576
	ds_read_u16 v103, v157 offset:4096
	ds_read_b32 v105, v155 offset:10240
	ds_read_b32 v106, v155 offset:26624
	ds_read_u16 v108, v157 offset:5120
	ds_read_b32 v110, v155 offset:12288
	ds_read_b32 v111, v155 offset:28672
	ds_read_u16 v113, v157 offset:6144
	ds_read_b32 v115, v155 offset:14336
	ds_read_b32 v116, v155 offset:30720
	ds_read_u16 v118, v157 offset:7168
	s_waitcnt lgkmcnt(0)
	v_add_f32_e32 v80, v80, v20
	v_add_f32_e32 v85, v85, v21
	v_add_f32_e32 v90, v90, v22
	v_add_f32_e32 v95, v95, v23
	v_add_f32_dpp v168, v80, v80 quad_perm:[1,0,3,2] row_mask:0xf bank_mask:0xf bound_ctrl:1
	v_add_f32_dpp v174, v85, v85 quad_perm:[1,0,3,2] row_mask:0xf bank_mask:0xf bound_ctrl:1
	v_add_f32_dpp v241, v90, v90 quad_perm:[1,0,3,2] row_mask:0xf bank_mask:0xf bound_ctrl:1
	v_add_f32_dpp v247, v95, v95 quad_perm:[1,0,3,2] row_mask:0xf bank_mask:0xf bound_ctrl:1
	v_add_f32_dpp v168, v168, v168 quad_perm:[2,3,0,1] row_mask:0xf bank_mask:0xf bound_ctrl:1
	v_add_f32_dpp v174, v174, v174 quad_perm:[2,3,0,1] row_mask:0xf bank_mask:0xf bound_ctrl:1
	v_add_f32_dpp v241, v241, v241 quad_perm:[2,3,0,1] row_mask:0xf bank_mask:0xf bound_ctrl:1
	v_add_f32_dpp v247, v247, v247 quad_perm:[2,3,0,1] row_mask:0xf bank_mask:0xf bound_ctrl:1
	v_add_f32_dpp v168, v168, v168 row_half_mirror row_mask:0xf bank_mask:0xf bound_ctrl:1
	v_add_f32_dpp v174, v174, v174 row_half_mirror row_mask:0xf bank_mask:0xf bound_ctrl:1
	v_add_f32_dpp v241, v241, v241 row_half_mirror row_mask:0xf bank_mask:0xf bound_ctrl:1
	v_add_f32_dpp v247, v247, v247 row_half_mirror row_mask:0xf bank_mask:0xf bound_ctrl:1
	v_add_f32_dpp v168, v168, v168 row_mirror row_mask:0xf bank_mask:0xf bound_ctrl:1
	v_add_f32_dpp v174, v174, v174 row_mirror row_mask:0xf bank_mask:0xf bound_ctrl:1
	v_add_f32_dpp v241, v241, v241 row_mirror row_mask:0xf bank_mask:0xf bound_ctrl:1
	v_add_f32_dpp v247, v247, v247 row_mirror row_mask:0xf bank_mask:0xf bound_ctrl:1
	v_readlane_b32 s36, v168, 16
	v_readlane_b32 s40, v174, 16
	v_readlane_b32 s44, v241, 16
	v_readlane_b32 s48, v247, 16
	v_readlane_b32 s37, v168, 48
	v_readlane_b32 s41, v174, 48
	v_readlane_b32 s45, v241, 48
	v_readlane_b32 s49, v247, 48
	v_readlane_b32 s38, v168, 0
	v_readlane_b32 s42, v174, 0
	v_readlane_b32 s46, v241, 0
	v_readlane_b32 s50, v247, 0
	v_readlane_b32 s39, v168, 32
	v_readlane_b32 s43, v174, 32
	v_readlane_b32 s47, v241, 32
	v_readlane_b32 s51, v247, 32
	v_mov_b32_e32 v168, s36
	v_mov_b32_e32 v174, s40
	v_mov_b32_e32 v241, s44
	v_mov_b32_e32 v247, s48
	v_mov_b32_e32 v169, s37
	v_mov_b32_e32 v175, s41
	v_mov_b32_e32 v242, s45
	v_mov_b32_e32 v248, s49
	v_add_f32_e32 v168, s38, v168
	v_add_f32_e32 v174, s42, v174
	v_add_f32_e32 v241, s46, v241
	v_add_f32_e32 v247, s50, v247
	v_add_f32_e32 v169, s39, v169
	v_add_f32_e32 v175, s43, v175
	v_add_f32_e32 v242, s47, v242
	v_add_f32_e32 v248, s51, v248
	v_add_f32_e32 v168, v168, v169
	v_add_f32_e32 v174, v174, v175
	v_add_f32_e32 v241, v241, v242
	v_add_f32_e32 v247, v247, v248
	v_fmamk_f32 v80, v168, 0xbc800000, v80
	v_fmamk_f32 v85, v174, 0xbc800000, v85
	v_fmamk_f32 v90, v241, 0xbc800000, v90
	v_fmamk_f32 v95, v247, 0xbc800000, v95
	v_mul_f32_e32 v168, v80, v80
	v_mul_f32_e32 v174, v85, v85
	v_mul_f32_e32 v241, v90, v90
	v_mul_f32_e32 v247, v95, v95
	v_mov_b32_dpp v168, v168 quad_perm:[1,0,3,2] row_mask:0xf bank_mask:0xf bound_ctrl:1
	v_mov_b32_dpp v174, v174 quad_perm:[1,0,3,2] row_mask:0xf bank_mask:0xf bound_ctrl:1
	v_mov_b32_dpp v241, v241 quad_perm:[1,0,3,2] row_mask:0xf bank_mask:0xf bound_ctrl:1
	v_mov_b32_dpp v247, v247 quad_perm:[1,0,3,2] row_mask:0xf bank_mask:0xf bound_ctrl:1
	v_fmac_f32_e32 v168, v80, v80
	v_fmac_f32_e32 v174, v85, v85
	v_fmac_f32_e32 v241, v90, v90
	v_fmac_f32_e32 v247, v95, v95
	v_add_f32_dpp v168, v168, v168 quad_perm:[2,3,0,1] row_mask:0xf bank_mask:0xf bound_ctrl:1
	v_add_f32_dpp v174, v174, v174 quad_perm:[2,3,0,1] row_mask:0xf bank_mask:0xf bound_ctrl:1
	v_add_f32_dpp v241, v241, v241 quad_perm:[2,3,0,1] row_mask:0xf bank_mask:0xf bound_ctrl:1
	v_add_f32_dpp v247, v247, v247 quad_perm:[2,3,0,1] row_mask:0xf bank_mask:0xf bound_ctrl:1
	v_add_f32_dpp v168, v168, v168 row_half_mirror row_mask:0xf bank_mask:0xf bound_ctrl:1
	v_add_f32_dpp v174, v174, v174 row_half_mirror row_mask:0xf bank_mask:0xf bound_ctrl:1
	v_add_f32_dpp v241, v241, v241 row_half_mirror row_mask:0xf bank_mask:0xf bound_ctrl:1
	v_add_f32_dpp v247, v247, v247 row_half_mirror row_mask:0xf bank_mask:0xf bound_ctrl:1
	v_add_f32_dpp v168, v168, v168 row_mirror row_mask:0xf bank_mask:0xf bound_ctrl:1
	v_add_f32_dpp v174, v174, v174 row_mirror row_mask:0xf bank_mask:0xf bound_ctrl:1
	v_add_f32_dpp v241, v241, v241 row_mirror row_mask:0xf bank_mask:0xf bound_ctrl:1
	v_add_f32_dpp v247, v247, v247 row_mirror row_mask:0xf bank_mask:0xf bound_ctrl:1
	v_readlane_b32 s36, v168, 16
	v_readlane_b32 s40, v174, 16
	v_readlane_b32 s44, v241, 16
	v_readlane_b32 s48, v247, 16
	v_readlane_b32 s37, v168, 48
	v_readlane_b32 s41, v174, 48
	v_readlane_b32 s45, v241, 48
	v_readlane_b32 s49, v247, 48
	v_readlane_b32 s38, v168, 0
	v_readlane_b32 s42, v174, 0
	v_readlane_b32 s46, v241, 0
	v_readlane_b32 s50, v247, 0
	v_readlane_b32 s39, v168, 32
; __device__ __forceinline__ float bf2f(bf16 x) { return __uint_as_float(((unsigned)x) << 16); }
; __device__ __forceinline__ unsigned f2bf(float f) { return cvt_pk_bf16(f, 0.f) & 0xffffu; }
; __device__ __forceinline__ void rw_post(Frame& F) {
;     ...
;                 const float mean = wsum(y[q]) * (1.f / 64.f); const float dv = y[q] - mean; const float var = wsum(dv * dv) * (1.f / 64.f);
;                 const float yn = dv * (1.f / sqrtf(var + 64e-5f)) * g_ + b_;
;                 OB[(size_t)row * DH + col] = (bf16)f2bf((yn + rk[q] * vv[q]) * bf2f(gg[q])); }
	v_readlane_b32 s43, v174, 32
	v_readlane_b32 s47, v241, 32
	v_readlane_b32 s51, v247, 32
	v_mov_b32_e32 v168, s36
	v_mov_b32_e32 v174, s40
	v_mov_b32_e32 v241, s44
	v_mov_b32_e32 v247, s48
	v_mov_b32_e32 v169, s37
	v_mov_b32_e32 v175, s41
	v_mov_b32_e32 v242, s45
	v_mov_b32_e32 v248, s49
	v_add_f32_e32 v168, s38, v168
	v_add_f32_e32 v174, s42, v174
	v_add_f32_e32 v241, s46, v241
	v_add_f32_e32 v247, s50, v247
	v_add_f32_e32 v169, s39, v169
	v_add_f32_e32 v175, s43, v175
	v_add_f32_e32 v242, s47, v242
	v_add_f32_e32 v248, s51, v248
	v_add_f32_e32 v168, v168, v169
	v_add_f32_e32 v174, v174, v175
	v_add_f32_e32 v241, v241, v242
	v_add_f32_e32 v247, v247, v248
	v_fmamk_f32 v168, v168, 0x3c800000, v9
	v_fmamk_f32 v174, v174, 0x3c800000, v9
	v_fmamk_f32 v241, v241, 0x3c800000, v9
	v_fmamk_f32 v247, v247, 0x3c800000, v9
	v_mul_f32_e32 v169, 0x4f800000, v168
	v_mul_f32_e32 v175, 0x4f800000, v174
	v_mul_f32_e32 v242, 0x4f800000, v241
	v_mul_f32_e32 v248, 0x4f800000, v247
	v_cmp_gt_f32_e64 s[52:53], s68, v168
	v_cmp_gt_f32_e64 s[54:55], s68, v174
	v_cmp_gt_f32_e64 s[56:57], s68, v241
	v_cmp_gt_f32_e64 s[58:59], s68, v247
	v_mov_b32_e32 v170, v168
	v_mov_b32_e32 v176, v174
	v_mov_b32_e32 v243, v241
	v_mov_b32_e32 v249, v247
	v_cndmask_b32_e64 v168, v170, v169, s[52:53]
	v_cndmask_b32_e64 v174, v176, v175, s[54:55]
	v_cndmask_b32_e64 v241, v243, v242, s[56:57]
	v_cndmask_b32_e64 v247, v249, v248, s[58:59]
	v_sqrt_f32_e32 v169, v168
	v_sqrt_f32_e32 v175, v174
	v_sqrt_f32_e32 v242, v241
	v_sqrt_f32_e32 v248, v247
	v_add_u32_e32 v170, -1, v169
	v_add_u32_e32 v176, -1, v175
	v_add_u32_e32 v243, -1, v242
	v_add_u32_e32 v249, -1, v248
	v_fma_f32 v171, -v170, v169, v168
	v_fma_f32 v177, -v176, v175, v174
	v_fma_f32 v244, -v243, v242, v241
	v_fma_f32 v250, -v249, v248, v247
	v_cmp_ge_f32_e64 s[60:61], 0, v171
	v_cmp_ge_f32_e64 s[62:63], 0, v177
	v_cmp_ge_f32_e64 s[64:65], 0, v244
	v_cmp_ge_f32_e64 s[66:67], 0, v250
	v_add_u32_e32 v171, 1, v169
	v_add_u32_e32 v177, 1, v175
	v_add_u32_e32 v244, 1, v242
	v_add_u32_e32 v250, 1, v248
	v_cndmask_b32_e64 v170, v169, v170, s[60:61]
	v_cndmask_b32_e64 v176, v175, v176, s[62:63]
	v_cndmask_b32_e64 v243, v242, v243, s[64:65]
	v_cndmask_b32_e64 v249, v248, v249, s[66:67]
	v_fma_f32 v169, -v171, v169, v168
	v_fma_f32 v175, -v177, v175, v174
	v_fma_f32 v242, -v244, v242, v241
	v_fma_f32 v248, -v250, v248, v247
	v_cmp_lt_f32_e64 s[60:61], 0, v169
	v_cmp_lt_f32_e64 s[62:63], 0, v175
	v_cmp_lt_f32_e64 s[64:65], 0, v242
	v_cmp_lt_f32_e64 s[66:67], 0, v248
	v_cndmask_b32_e64 v169, v170, v171, s[60:61]
	v_cndmask_b32_e64 v175, v176, v177, s[62:63]
	v_cndmask_b32_e64 v242, v243, v244, s[64:65]
	v_cndmask_b32_e64 v248, v249, v250, s[66:67]
	v_mul_f32_e32 v170, 0x37800000, v169
	v_mul_f32_e32 v176, 0x37800000, v175
	v_mul_f32_e32 v243, 0x37800000, v242
	v_mul_f32_e32 v249, 0x37800000, v248
	v_cndmask_b32_e64 v169, v169, v170, s[52:53]
	v_cndmask_b32_e64 v175, v175, v176, s[54:55]
	v_cndmask_b32_e64 v242, v242, v243, s[56:57]
	v_cndmask_b32_e64 v248, v248, v249, s[58:59]
	v_cmp_class_f32_e64 s[60:61], v168, v8
	v_cmp_class_f32_e64 s[62:63], v174, v8
	v_cmp_class_f32_e64 s[64:65], v241, v8
	v_cmp_class_f32_e64 s[66:67], v247, v8
	v_cndmask_b32_e64 v168, v169, v168, s[60:61]
	v_cndmask_b32_e64 v174, v175, v174, s[62:63]
	v_cndmask_b32_e64 v241, v242, v241, s[64:65]
	v_cndmask_b32_e64 v247, v248, v247, s[66:67]
	v_div_scale_f32 v169, s[60:61], v168, v168, 1.0
	v_rcp_f32_e32 v170, v169
	s_nop 0
	v_fma_f32 v171, -v169, v170, 1.0
	v_fmac_f32_e32 v170, v171, v170
	v_div_scale_f32 v171, vcc, 1.0, v168, 1.0
	v_mul_f32_e32 v172, v171, v170
	v_fma_f32 v173, -v169, v172, v171
	v_fmac_f32_e32 v172, v173, v170
	v_fma_f32 v169, -v169, v172, v171
	v_div_fmas_f32 v169, v169, v170, v172
	v_div_fixup_f32 v168, v169, v168, 1.0
	v_div_scale_f32 v175, s[62:63], v174, v174, 1.0
	v_rcp_f32_e32 v176, v175
	s_nop 0
	v_fma_f32 v177, -v175, v176, 1.0
	v_fmac_f32_e32 v176, v177, v176
	v_div_scale_f32 v177, vcc, 1.0, v174, 1.0
	v_mul_f32_e32 v236, v177, v176
	v_fma_f32 v237, -v175, v236, v177
	v_fmac_f32_e32 v236, v237, v176
	v_fma_f32 v175, -v175, v236, v177
	v_div_fmas_f32 v175, v175, v176, v236
	v_div_fixup_f32 v174, v175, v174, 1.0
	v_div_scale_f32 v242, s[64:65], v241, v241, 1.0
	v_rcp_f32_e32 v243, v242
	s_nop 0
	v_fma_f32 v244, -v242, v243, 1.0
	v_fmac_f32_e32 v243, v244, v243
	v_div_scale_f32 v244, vcc, 1.0, v241, 1.0
	v_mul_f32_e32 v245, v244, v243
	v_fma_f32 v246, -v242, v245, v244
	v_fmac_f32_e32 v245, v246, v243
	v_fma_f32 v242, -v242, v245, v244
	v_div_fmas_f32 v242, v242, v243, v245
	v_div_fixup_f32 v241, v242, v241, 1.0
	v_div_scale_f32 v248, s[66:67], v247, v247, 1.0
	v_rcp_f32_e32 v249, v248
	s_nop 0
	v_fma_f32 v250, -v248, v249, 1.0
	v_fmac_f32_e32 v249, v250, v249
	v_div_scale_f32 v250, vcc, 1.0, v247, 1.0
	v_mul_f32_e32 v251, v250, v249
	v_fma_f32 v252, -v248, v251, v250
	v_fmac_f32_e32 v251, v252, v249
	v_fma_f32 v248, -v248, v251, v250
	v_div_fmas_f32 v248, v248, v249, v251
	v_div_fixup_f32 v247, v248, v247, 1.0
	v_mul_f32_e32 v80, v80, v168
	v_mul_f32_e32 v85, v85, v174
	v_mul_f32_e32 v90, v90, v241
	v_mul_f32_e32 v95, v95, v247
	v_lshlrev_b32_e32 v83, 16, v83
	v_lshlrev_b32_e32 v88, 16, v88
	v_lshlrev_b32_e32 v93, 16, v93
	v_lshlrev_b32_e32 v98, 16, v98
	v_fma_f32 v80, v6, v80, v7
	v_fma_f32 v85, v6, v85, v7
	v_fma_f32 v90, v6, v90, v7
	v_fma_f32 v95, v6, v95, v7
	v_fmac_f32_e32 v80, s69, v81
	v_fmac_f32_e32 v85, s70, v86
	v_fmac_f32_e32 v90, s71, v91
	v_fmac_f32_e32 v95, s72, v96
	v_mul_f32_e32 v80, v80, v83
	v_mul_f32_e32 v85, v85, v88
	v_mul_f32_e32 v90, v90, v93
	v_mul_f32_e32 v95, v95, v98
	v_cvt_pk_bf16_f32 v169, v80, v80
; __device__ __forceinline__ float bf2f(bf16 x) { return __uint_as_float(((unsigned)x) << 16); }
; __device__ __forceinline__ unsigned f2bf(float f) { return cvt_pk_bf16(f, 0.f) & 0xffffu; }
; __device__ __forceinline__ void rw_post(Frame& F) {
;     ...
;             for (int q = 0; q < 8; ++q) { const int row = rb0 + t0 + q;
;                 const float mean = wsum(y[q]) * (1.f / 64.f); const float dv = y[q] - mean; const float var = wsum(dv * dv) * (1.f / 64.f);
;                 const float yn = dv * (1.f / sqrtf(var + 64e-5f)) * g_ + b_;
;                 OB[(size_t)row * DH + col] = (bf16)f2bf((yn + rk[q] * vv[q]) * bf2f(gg[q])); }
	v_cvt_pk_bf16_f32 v175, v85, v85
	v_cvt_pk_bf16_f32 v242, v90, v90
	v_cvt_pk_bf16_f32 v248, v95, v95
	global_store_short v2, v169, s[28:29]
	s_add_u32 s28, s28, 0x1000
	s_addc_u32 s29, s29, 0
	global_store_short v2, v175, s[28:29]
	s_add_u32 s28, s28, 0x1000
	s_addc_u32 s29, s29, 0
	global_store_short v2, v242, s[28:29]
	s_add_u32 s28, s28, 0x1000
	s_addc_u32 s29, s29, 0
	global_store_short v2, v248, s[28:29]
	s_add_u32 s28, s28, 0x1000
	s_addc_u32 s29, s29, 0
	v_add_f32_e32 v100, v100, v36
	v_add_f32_e32 v105, v105, v37
	v_add_f32_e32 v110, v110, v38
	v_add_f32_e32 v115, v115, v39
	v_add_f32_dpp v168, v100, v100 quad_perm:[1,0,3,2] row_mask:0xf bank_mask:0xf bound_ctrl:1
	v_add_f32_dpp v174, v105, v105 quad_perm:[1,0,3,2] row_mask:0xf bank_mask:0xf bound_ctrl:1
	v_add_f32_dpp v241, v110, v110 quad_perm:[1,0,3,2] row_mask:0xf bank_mask:0xf bound_ctrl:1
	v_add_f32_dpp v247, v115, v115 quad_perm:[1,0,3,2] row_mask:0xf bank_mask:0xf bound_ctrl:1
	v_add_f32_dpp v168, v168, v168 quad_perm:[2,3,0,1] row_mask:0xf bank_mask:0xf bound_ctrl:1
	v_add_f32_dpp v174, v174, v174 quad_perm:[2,3,0,1] row_mask:0xf bank_mask:0xf bound_ctrl:1
	v_add_f32_dpp v241, v241, v241 quad_perm:[2,3,0,1] row_mask:0xf bank_mask:0xf bound_ctrl:1
	v_add_f32_dpp v247, v247, v247 quad_perm:[2,3,0,1] row_mask:0xf bank_mask:0xf bound_ctrl:1
	v_add_f32_dpp v168, v168, v168 row_half_mirror row_mask:0xf bank_mask:0xf bound_ctrl:1
	v_add_f32_dpp v174, v174, v174 row_half_mirror row_mask:0xf bank_mask:0xf bound_ctrl:1
	v_add_f32_dpp v241, v241, v241 row_half_mirror row_mask:0xf bank_mask:0xf bound_ctrl:1
	v_add_f32_dpp v247, v247, v247 row_half_mirror row_mask:0xf bank_mask:0xf bound_ctrl:1
	v_add_f32_dpp v168, v168, v168 row_mirror row_mask:0xf bank_mask:0xf bound_ctrl:1
	v_add_f32_dpp v174, v174, v174 row_mirror row_mask:0xf bank_mask:0xf bound_ctrl:1
	v_add_f32_dpp v241, v241, v241 row_mirror row_mask:0xf bank_mask:0xf bound_ctrl:1
	v_add_f32_dpp v247, v247, v247 row_mirror row_mask:0xf bank_mask:0xf bound_ctrl:1
	v_readlane_b32 s36, v168, 16
	v_readlane_b32 s40, v174, 16
	v_readlane_b32 s44, v241, 16
	v_readlane_b32 s48, v247, 16
	v_readlane_b32 s37, v168, 48
	v_readlane_b32 s41, v174, 48
	v_readlane_b32 s45, v241, 48
	v_readlane_b32 s49, v247, 48
	v_readlane_b32 s38, v168, 0
	v_readlane_b32 s42, v174, 0
	v_readlane_b32 s46, v241, 0
	v_readlane_b32 s50, v247, 0
	v_readlane_b32 s39, v168, 32
	v_readlane_b32 s43, v174, 32
	v_readlane_b32 s47, v241, 32
	v_readlane_b32 s51, v247, 32
	v_mov_b32_e32 v168, s36
	v_mov_b32_e32 v174, s40
	v_mov_b32_e32 v241, s44
	v_mov_b32_e32 v247, s48
	v_mov_b32_e32 v169, s37
	v_mov_b32_e32 v175, s41
	v_mov_b32_e32 v242, s45
	v_mov_b32_e32 v248, s49
	v_add_f32_e32 v168, s38, v168
	v_add_f32_e32 v174, s42, v174
	v_add_f32_e32 v241, s46, v241
	v_add_f32_e32 v247, s50, v247
	v_add_f32_e32 v169, s39, v169
	v_add_f32_e32 v175, s43, v175
	v_add_f32_e32 v242, s47, v242
	v_add_f32_e32 v248, s51, v248
	v_add_f32_e32 v168, v168, v169
	v_add_f32_e32 v174, v174, v175
	v_add_f32_e32 v241, v241, v242
	v_add_f32_e32 v247, v247, v248
	v_fmamk_f32 v100, v168, 0xbc800000, v100
	v_fmamk_f32 v105, v174, 0xbc800000, v105
	v_fmamk_f32 v110, v241, 0xbc800000, v110
	v_fmamk_f32 v115, v247, 0xbc800000, v115
	v_mul_f32_e32 v168, v100, v100
	v_mul_f32_e32 v174, v105, v105
	v_mul_f32_e32 v241, v110, v110
	v_mul_f32_e32 v247, v115, v115
	v_mov_b32_dpp v168, v168 quad_perm:[1,0,3,2] row_mask:0xf bank_mask:0xf bound_ctrl:1
	v_mov_b32_dpp v174, v174 quad_perm:[1,0,3,2] row_mask:0xf bank_mask:0xf bound_ctrl:1
	v_mov_b32_dpp v241, v241 quad_perm:[1,0,3,2] row_mask:0xf bank_mask:0xf bound_ctrl:1
	v_mov_b32_dpp v247, v247 quad_perm:[1,0,3,2] row_mask:0xf bank_mask:0xf bound_ctrl:1
	v_fmac_f32_e32 v168, v100, v100
	v_fmac_f32_e32 v174, v105, v105
	v_fmac_f32_e32 v241, v110, v110
	v_fmac_f32_e32 v247, v115, v115
	v_add_f32_dpp v168, v168, v168 quad_perm:[2,3,0,1] row_mask:0xf bank_mask:0xf bound_ctrl:1
	v_add_f32_dpp v174, v174, v174 quad_perm:[2,3,0,1] row_mask:0xf bank_mask:0xf bound_ctrl:1
	v_add_f32_dpp v241, v241, v241 quad_perm:[2,3,0,1] row_mask:0xf bank_mask:0xf bound_ctrl:1
	v_add_f32_dpp v247, v247, v247 quad_perm:[2,3,0,1] row_mask:0xf bank_mask:0xf bound_ctrl:1
	v_add_f32_dpp v168, v168, v168 row_half_mirror row_mask:0xf bank_mask:0xf bound_ctrl:1
	v_add_f32_dpp v174, v174, v174 row_half_mirror row_mask:0xf bank_mask:0xf bound_ctrl:1
	v_add_f32_dpp v241, v241, v241 row_half_mirror row_mask:0xf bank_mask:0xf bound_ctrl:1
	v_add_f32_dpp v247, v247, v247 row_half_mirror row_mask:0xf bank_mask:0xf bound_ctrl:1
	v_add_f32_dpp v168, v168, v168 row_mirror row_mask:0xf bank_mask:0xf bound_ctrl:1
	v_add_f32_dpp v174, v174, v174 row_mirror row_mask:0xf bank_mask:0xf bound_ctrl:1
	v_add_f32_dpp v241, v241, v241 row_mirror row_mask:0xf bank_mask:0xf bound_ctrl:1
	v_add_f32_dpp v247, v247, v247 row_mirror row_mask:0xf bank_mask:0xf bound_ctrl:1
	v_readlane_b32 s36, v168, 16
	v_readlane_b32 s40, v174, 16
	v_readlane_b32 s44, v241, 16
	v_readlane_b32 s48, v247, 16
	v_readlane_b32 s37, v168, 48
	v_readlane_b32 s41, v174, 48
	v_readlane_b32 s45, v241, 48
	v_readlane_b32 s49, v247, 48
	v_readlane_b32 s38, v168, 0
	v_readlane_b32 s42, v174, 0
	v_readlane_b32 s46, v241, 0
	v_readlane_b32 s50, v247, 0
	v_readlane_b32 s39, v168, 32
	v_readlane_b32 s43, v174, 32
	v_readlane_b32 s47, v241, 32
	v_readlane_b32 s51, v247, 32
	v_mov_b32_e32 v168, s36
	v_mov_b32_e32 v174, s40
	v_mov_b32_e32 v241, s44
	v_mov_b32_e32 v247, s48
	v_mov_b32_e32 v169, s37
	v_mov_b32_e32 v175, s41
	v_mov_b32_e32 v242, s45
	v_mov_b32_e32 v248, s49
	v_add_f32_e32 v168, s38, v168
	v_add_f32_e32 v174, s42, v174
	v_add_f32_e32 v241, s46, v241
; __device__ __forceinline__ float bf2f(bf16 x) { return __uint_as_float(((unsigned)x) << 16); }
; __device__ __forceinline__ unsigned f2bf(float f) { return cvt_pk_bf16(f, 0.f) & 0xffffu; }
; #define POST_LD(Y_, V_, G_, R_, C_, t) do { _Pragma("unroll") for (int q = 0; q < 8; ++q) { const size_t o_ = (size_t)((t) + q) * DH; Y_[q] = yp[o_]; V_[q] = vp[o_]; G_[q] = gp[o_]; R_[q] = rp[((t) + q) * 32]; C_[q] = cp[o_]; } } while (0)
; __device__ __forceinline__ void rw_post(Frame& F) {
;     ...
;         POST_LD(y, vv, gg, rk, cc, 0);
;         for (int t0 = 0; t0 < 64; t0 += 8) {
;             float ny[8], nv[8], nr[8], nc[8]; bf16 ng[8];
;             const int tn = t0 + 8 < 64 ? t0 + 8 : t0;
;             POST_LD(ny, nv, ng, nr, nc, tn);
;     ...
;                 const float mean = wsum(y[q]) * (1.f / 64.f); const float dv = y[q] - mean; const float var = wsum(dv * dv) * (1.f / 64.f);
;                 const float yn = dv * (1.f / sqrtf(var + 64e-5f)) * g_ + b_;
;                 OB[(size_t)row * DH + col] = (bf16)f2bf((yn + rk[q] * vv[q]) * bf2f(gg[q])); }
; #pragma unroll
;             for (int q = 0; q < 8; ++q) { y[q] = ny[q]; vv[q] = nv[q]; gg[q] = ng[q]; rk[q] = nr[q]; cc[q] = nc[q]; }
	v_add_f32_e32 v247, s50, v247
	v_add_f32_e32 v169, s39, v169
	v_add_f32_e32 v175, s43, v175
	v_add_f32_e32 v242, s47, v242
	v_add_f32_e32 v248, s51, v248
	v_add_f32_e32 v168, v168, v169
	v_add_f32_e32 v174, v174, v175
	v_add_f32_e32 v241, v241, v242
	v_add_f32_e32 v247, v247, v248
	v_fmamk_f32 v168, v168, 0x3c800000, v9
	v_fmamk_f32 v174, v174, 0x3c800000, v9
	v_fmamk_f32 v241, v241, 0x3c800000, v9
	v_fmamk_f32 v247, v247, 0x3c800000, v9
	v_mul_f32_e32 v169, 0x4f800000, v168
	v_mul_f32_e32 v175, 0x4f800000, v174
	v_mul_f32_e32 v242, 0x4f800000, v241
	v_mul_f32_e32 v248, 0x4f800000, v247
	v_cmp_gt_f32_e64 s[52:53], s68, v168
	v_cmp_gt_f32_e64 s[54:55], s68, v174
	v_cmp_gt_f32_e64 s[56:57], s68, v241
	v_cmp_gt_f32_e64 s[58:59], s68, v247
	v_mov_b32_e32 v170, v168
	v_mov_b32_e32 v176, v174
	v_mov_b32_e32 v243, v241
	v_mov_b32_e32 v249, v247
	v_cndmask_b32_e64 v168, v170, v169, s[52:53]
	v_cndmask_b32_e64 v174, v176, v175, s[54:55]
	v_cndmask_b32_e64 v241, v243, v242, s[56:57]
	v_cndmask_b32_e64 v247, v249, v248, s[58:59]
	v_sqrt_f32_e32 v169, v168
	v_sqrt_f32_e32 v175, v174
	v_sqrt_f32_e32 v242, v241
	v_sqrt_f32_e32 v248, v247
	v_add_u32_e32 v170, -1, v169
	v_add_u32_e32 v176, -1, v175
	v_add_u32_e32 v243, -1, v242
	v_add_u32_e32 v249, -1, v248
	v_fma_f32 v171, -v170, v169, v168
	v_fma_f32 v177, -v176, v175, v174
	v_fma_f32 v244, -v243, v242, v241
	v_fma_f32 v250, -v249, v248, v247
	v_cmp_ge_f32_e64 s[60:61], 0, v171
	v_cmp_ge_f32_e64 s[62:63], 0, v177
	v_cmp_ge_f32_e64 s[64:65], 0, v244
	v_cmp_ge_f32_e64 s[66:67], 0, v250
	v_add_u32_e32 v171, 1, v169
	v_add_u32_e32 v177, 1, v175
	v_add_u32_e32 v244, 1, v242
	v_add_u32_e32 v250, 1, v248
	v_cndmask_b32_e64 v170, v169, v170, s[60:61]
	v_cndmask_b32_e64 v176, v175, v176, s[62:63]
	v_cndmask_b32_e64 v243, v242, v243, s[64:65]
	v_cndmask_b32_e64 v249, v248, v249, s[66:67]
	v_fma_f32 v169, -v171, v169, v168
	v_fma_f32 v175, -v177, v175, v174
	v_fma_f32 v242, -v244, v242, v241
	v_fma_f32 v248, -v250, v248, v247
	v_cmp_lt_f32_e64 s[60:61], 0, v169
	v_cmp_lt_f32_e64 s[62:63], 0, v175
	v_cmp_lt_f32_e64 s[64:65], 0, v242
	v_cmp_lt_f32_e64 s[66:67], 0, v248
	v_cndmask_b32_e64 v169, v170, v171, s[60:61]
	v_cndmask_b32_e64 v175, v176, v177, s[62:63]
	v_cndmask_b32_e64 v242, v243, v244, s[64:65]
	v_cndmask_b32_e64 v248, v249, v250, s[66:67]
	v_mul_f32_e32 v170, 0x37800000, v169
	v_mul_f32_e32 v176, 0x37800000, v175
	v_mul_f32_e32 v243, 0x37800000, v242
	v_mul_f32_e32 v249, 0x37800000, v248
	v_cndmask_b32_e64 v169, v169, v170, s[52:53]
	v_cndmask_b32_e64 v175, v175, v176, s[54:55]
	v_cndmask_b32_e64 v242, v242, v243, s[56:57]
	v_cndmask_b32_e64 v248, v248, v249, s[58:59]
	v_cmp_class_f32_e64 s[60:61], v168, v8
	v_cmp_class_f32_e64 s[62:63], v174, v8
	v_cmp_class_f32_e64 s[64:65], v241, v8
	v_cmp_class_f32_e64 s[66:67], v247, v8
	v_cndmask_b32_e64 v168, v169, v168, s[60:61]
	v_cndmask_b32_e64 v174, v175, v174, s[62:63]
	v_cndmask_b32_e64 v241, v242, v241, s[64:65]
	v_cndmask_b32_e64 v247, v248, v247, s[66:67]
	v_div_scale_f32 v169, s[60:61], v168, v168, 1.0
	v_rcp_f32_e32 v170, v169
	s_nop 0
	v_fma_f32 v171, -v169, v170, 1.0
	v_fmac_f32_e32 v170, v171, v170
	v_div_scale_f32 v171, vcc, 1.0, v168, 1.0
	v_mul_f32_e32 v172, v171, v170
	v_fma_f32 v173, -v169, v172, v171
	v_fmac_f32_e32 v172, v173, v170
	v_fma_f32 v169, -v169, v172, v171
	v_div_fmas_f32 v169, v169, v170, v172
	v_div_fixup_f32 v168, v169, v168, 1.0
	v_div_scale_f32 v175, s[62:63], v174, v174, 1.0
	v_rcp_f32_e32 v176, v175
	s_nop 0
	v_fma_f32 v177, -v175, v176, 1.0
	v_fmac_f32_e32 v176, v177, v176
	v_div_scale_f32 v177, vcc, 1.0, v174, 1.0
	v_mul_f32_e32 v236, v177, v176
	v_fma_f32 v237, -v175, v236, v177
	v_fmac_f32_e32 v236, v237, v176
	v_fma_f32 v175, -v175, v236, v177
	v_div_fmas_f32 v175, v175, v176, v236
	v_div_fixup_f32 v174, v175, v174, 1.0
	v_div_scale_f32 v242, s[64:65], v241, v241, 1.0
	v_rcp_f32_e32 v243, v242
	s_nop 0
	v_fma_f32 v244, -v242, v243, 1.0
	v_fmac_f32_e32 v243, v244, v243
	v_div_scale_f32 v244, vcc, 1.0, v241, 1.0
	v_mul_f32_e32 v245, v244, v243
	v_fma_f32 v246, -v242, v245, v244
	v_fmac_f32_e32 v245, v246, v243
	v_fma_f32 v242, -v242, v245, v244
	v_div_fmas_f32 v242, v242, v243, v245
	v_div_fixup_f32 v241, v242, v241, 1.0
	v_div_scale_f32 v248, s[66:67], v247, v247, 1.0
	v_rcp_f32_e32 v249, v248
	s_nop 0
	v_fma_f32 v250, -v248, v249, 1.0
	v_fmac_f32_e32 v249, v250, v249
	v_div_scale_f32 v250, vcc, 1.0, v247, 1.0
	v_mul_f32_e32 v251, v250, v249
	v_fma_f32 v252, -v248, v251, v250
	v_fmac_f32_e32 v251, v252, v249
	v_fma_f32 v248, -v248, v251, v250
	v_div_fmas_f32 v248, v248, v249, v251
	v_div_fixup_f32 v247, v248, v247, 1.0
	v_mul_f32_e32 v100, v100, v168
	v_mul_f32_e32 v105, v105, v174
	v_mul_f32_e32 v110, v110, v241
	v_mul_f32_e32 v115, v115, v247
	v_lshlrev_b32_e32 v103, 16, v103
	v_lshlrev_b32_e32 v108, 16, v108
	v_lshlrev_b32_e32 v113, 16, v113
	v_lshlrev_b32_e32 v118, 16, v118
	v_fma_f32 v100, v6, v100, v7
	v_fma_f32 v105, v6, v105, v7
	v_fma_f32 v110, v6, v110, v7
	v_fma_f32 v115, v6, v115, v7
	v_fmac_f32_e32 v100, s73, v101
	v_fmac_f32_e32 v105, s26, v106
	v_fmac_f32_e32 v110, s27, v111
	v_fmac_f32_e32 v115, s32, v116
	v_mul_f32_e32 v100, v100, v103
	v_mul_f32_e32 v105, v105, v108
	v_mul_f32_e32 v110, v110, v113
	v_mul_f32_e32 v115, v115, v118
	v_cvt_pk_bf16_f32 v169, v100, v100
	v_cvt_pk_bf16_f32 v175, v105, v105
	v_cvt_pk_bf16_f32 v242, v110, v110
	v_cvt_pk_bf16_f32 v248, v115, v115
	global_store_short v2, v169, s[28:29]
	s_add_u32 s28, s28, 0x1000
	s_addc_u32 s29, s29, 0
	global_store_short v2, v175, s[28:29]
	s_add_u32 s28, s28, 0x1000
	s_addc_u32 s29, s29, 0
	global_store_short v2, v242, s[28:29]
	s_add_u32 s28, s28, 0x1000
	s_addc_u32 s29, s29, 0
	global_store_short v2, v248, s[28:29]
	s_add_u32 s28, s28, 0x1000
	s_addc_u32 s29, s29, 0
	s_waitcnt vmcnt(8)
	ds_write_b128 v12, v[120:123] offset:0
	ds_write_b128 v12, v[124:127] offset:1024
	ds_write_b128 v12, v[128:131] offset:16384
	ds_write_b128 v12, v[132:135] offset:17408
	ds_write_b128 v14, v[136:139]
	v_readlane_b32 s69, v159, 0
	v_readlane_b32 s70, v159, 1
	v_readlane_b32 s71, v159, 2
	v_readlane_b32 s72, v159, 3
	v_readlane_b32 s73, v159, 4
	v_readlane_b32 s26, v159, 5
	v_readlane_b32 s27, v159, 6
	v_readlane_b32 s32, v159, 7
	global_load_dwordx4 v[120:123], v11, s[6:7]
	global_load_dwordx4 v[124:127], v11, s[6:7] offset:1024
	global_load_dwordx4 v[128:131], v11, s[8:9]
	global_load_dwordx4 v[132:135], v11, s[8:9] offset:1024
	global_load_dwordx4 v[136:139], v11, s[10:11]
	global_load_dword v159, v158, s[12:13]
	s_add_u32 s6, s6, 0x10000
	s_addc_u32 s7, s7, 0
	s_add_u32 s8, s8, 0x10000
	s_addc_u32 s9, s9, 0
	s_add_u32 s10, s10, 0x8000
	s_addc_u32 s11, s11, 0
	s_add_u32 s12, s12, 0x400
	s_addc_u32 s13, s13, 0
	s_waitcnt lgkmcnt(0)
	s_barrier
; __device__ __forceinline__ float bf2f(bf16 x) { return __uint_as_float(((unsigned)x) << 16); }
; __device__ __forceinline__ unsigned f2bf(float f) { return cvt_pk_bf16(f, 0.f) & 0xffffu; }
; __device__ __forceinline__ void rw_post(Frame& F) {
;     ...
;                         y[4 * hf + q] += (a[0] + a[1]) + (a[2] + a[3]); }
;                     asm volatile("s_waitcnt lgkmcnt(0)" ::: "memory"); }
;             }
; #pragma unroll
;             for (int q = 0; q < 8; ++q) { const int row = rb0 + t0 + q;
;                 const float mean = wsum(y[q]) * (1.f / 64.f); const float dv = y[q] - mean; const float var = wsum(dv * dv) * (1.f / 64.f);
;                 const float yn = dv * (1.f / sqrtf(var + 64e-5f)) * g_ + b_;
;                 OB[(size_t)row * DH + col] = (bf16)f2bf((yn + rk[q] * vv[q]) * bf2f(gg[q])); }
	ds_read_b32 v80, v154 offset:0
	ds_read_b32 v81, v154 offset:16384
	ds_read_u16 v83, v156 offset:0
	ds_read_b32 v85, v154 offset:2048
	ds_read_b32 v86, v154 offset:18432
	ds_read_u16 v88, v156 offset:1024
	ds_read_b32 v90, v154 offset:4096
	ds_read_b32 v91, v154 offset:20480
	ds_read_u16 v93, v156 offset:2048
	ds_read_b32 v95, v154 offset:6144
	ds_read_b32 v96, v154 offset:22528
	ds_read_u16 v98, v156 offset:3072
	ds_read_b32 v100, v154 offset:8192
	ds_read_b32 v101, v154 offset:24576
	ds_read_u16 v103, v156 offset:4096
	ds_read_b32 v105, v154 offset:10240
	ds_read_b32 v106, v154 offset:26624
	ds_read_u16 v108, v156 offset:5120
	ds_read_b32 v110, v154 offset:12288
	ds_read_b32 v111, v154 offset:28672
	ds_read_u16 v113, v156 offset:6144
	ds_read_b32 v115, v154 offset:14336
	ds_read_b32 v116, v154 offset:30720
	ds_read_u16 v118, v156 offset:7168
	s_waitcnt lgkmcnt(0)
	v_add_f32_e32 v80, v80, v24
	v_add_f32_e32 v85, v85, v25
	v_add_f32_e32 v90, v90, v26
	v_add_f32_e32 v95, v95, v27
	v_add_f32_dpp v168, v80, v80 quad_perm:[1,0,3,2] row_mask:0xf bank_mask:0xf bound_ctrl:1
	v_add_f32_dpp v174, v85, v85 quad_perm:[1,0,3,2] row_mask:0xf bank_mask:0xf bound_ctrl:1
	v_add_f32_dpp v241, v90, v90 quad_perm:[1,0,3,2] row_mask:0xf bank_mask:0xf bound_ctrl:1
	v_add_f32_dpp v247, v95, v95 quad_perm:[1,0,3,2] row_mask:0xf bank_mask:0xf bound_ctrl:1
	v_add_f32_dpp v168, v168, v168 quad_perm:[2,3,0,1] row_mask:0xf bank_mask:0xf bound_ctrl:1
	v_add_f32_dpp v174, v174, v174 quad_perm:[2,3,0,1] row_mask:0xf bank_mask:0xf bound_ctrl:1
	v_add_f32_dpp v241, v241, v241 quad_perm:[2,3,0,1] row_mask:0xf bank_mask:0xf bound_ctrl:1
	v_add_f32_dpp v247, v247, v247 quad_perm:[2,3,0,1] row_mask:0xf bank_mask:0xf bound_ctrl:1
	v_add_f32_dpp v168, v168, v168 row_half_mirror row_mask:0xf bank_mask:0xf bound_ctrl:1
	v_add_f32_dpp v174, v174, v174 row_half_mirror row_mask:0xf bank_mask:0xf bound_ctrl:1
	v_add_f32_dpp v241, v241, v241 row_half_mirror row_mask:0xf bank_mask:0xf bound_ctrl:1
	v_add_f32_dpp v247, v247, v247 row_half_mirror row_mask:0xf bank_mask:0xf bound_ctrl:1
	v_add_f32_dpp v168, v168, v168 row_mirror row_mask:0xf bank_mask:0xf bound_ctrl:1
	v_add_f32_dpp v174, v174, v174 row_mirror row_mask:0xf bank_mask:0xf bound_ctrl:1
	v_add_f32_dpp v241, v241, v241 row_mirror row_mask:0xf bank_mask:0xf bound_ctrl:1
	v_add_f32_dpp v247, v247, v247 row_mirror row_mask:0xf bank_mask:0xf bound_ctrl:1
	v_readlane_b32 s36, v168, 16
	v_readlane_b32 s40, v174, 16
	v_readlane_b32 s44, v241, 16
	v_readlane_b32 s48, v247, 16
	v_readlane_b32 s37, v168, 48
	v_readlane_b32 s41, v174, 48
	v_readlane_b32 s45, v241, 48
	v_readlane_b32 s49, v247, 48
	v_readlane_b32 s38, v168, 0
	v_readlane_b32 s42, v174, 0
	v_readlane_b32 s46, v241, 0
	v_readlane_b32 s50, v247, 0
	v_readlane_b32 s39, v168, 32
	v_readlane_b32 s43, v174, 32
	v_readlane_b32 s47, v241, 32
	v_readlane_b32 s51, v247, 32
	v_mov_b32_e32 v168, s36
	v_mov_b32_e32 v174, s40
	v_mov_b32_e32 v241, s44
	v_mov_b32_e32 v247, s48
	v_mov_b32_e32 v169, s37
	v_mov_b32_e32 v175, s41
	v_mov_b32_e32 v242, s45
	v_mov_b32_e32 v248, s49
	v_add_f32_e32 v168, s38, v168
	v_add_f32_e32 v174, s42, v174
	v_add_f32_e32 v241, s46, v241
	v_add_f32_e32 v247, s50, v247
	v_add_f32_e32 v169, s39, v169
	v_add_f32_e32 v175, s43, v175
	v_add_f32_e32 v242, s47, v242
	v_add_f32_e32 v248, s51, v248
	v_add_f32_e32 v168, v168, v169
	v_add_f32_e32 v174, v174, v175
	v_add_f32_e32 v241, v241, v242
	v_add_f32_e32 v247, v247, v248
	v_fmamk_f32 v80, v168, 0xbc800000, v80
	v_fmamk_f32 v85, v174, 0xbc800000, v85
	v_fmamk_f32 v90, v241, 0xbc800000, v90
	v_fmamk_f32 v95, v247, 0xbc800000, v95
	v_mul_f32_e32 v168, v80, v80
	v_mul_f32_e32 v174, v85, v85
	v_mul_f32_e32 v241, v90, v90
	v_mul_f32_e32 v247, v95, v95
	v_mov_b32_dpp v168, v168 quad_perm:[1,0,3,2] row_mask:0xf bank_mask:0xf bound_ctrl:1
	v_mov_b32_dpp v174, v174 quad_perm:[1,0,3,2] row_mask:0xf bank_mask:0xf bound_ctrl:1
	v_mov_b32_dpp v241, v241 quad_perm:[1,0,3,2] row_mask:0xf bank_mask:0xf bound_ctrl:1
	v_mov_b32_dpp v247, v247 quad_perm:[1,0,3,2] row_mask:0xf bank_mask:0xf bound_ctrl:1
	v_fmac_f32_e32 v168, v80, v80
	v_fmac_f32_e32 v174, v85, v85
	v_fmac_f32_e32 v241, v90, v90
	v_fmac_f32_e32 v247, v95, v95
	v_add_f32_dpp v168, v168, v168 quad_perm:[2,3,0,1] row_mask:0xf bank_mask:0xf bound_ctrl:1
	v_add_f32_dpp v174, v174, v174 quad_perm:[2,3,0,1] row_mask:0xf bank_mask:0xf bound_ctrl:1
	v_add_f32_dpp v241, v241, v241 quad_perm:[2,3,0,1] row_mask:0xf bank_mask:0xf bound_ctrl:1
	v_add_f32_dpp v247, v247, v247 quad_perm:[2,3,0,1] row_mask:0xf bank_mask:0xf bound_ctrl:1
	v_add_f32_dpp v168, v168, v168 row_half_mirror row_mask:0xf bank_mask:0xf bound_ctrl:1
	v_add_f32_dpp v174, v174, v174 row_half_mirror row_mask:0xf bank_mask:0xf bound_ctrl:1
	v_add_f32_dpp v241, v241, v241 row_half_mirror row_mask:0xf bank_mask:0xf bound_ctrl:1
	v_add_f32_dpp v247, v247, v247 row_half_mirror row_mask:0xf bank_mask:0xf bound_ctrl:1
	v_add_f32_dpp v168, v168, v168 row_mirror row_mask:0xf bank_mask:0xf bound_ctrl:1
	v_add_f32_dpp v174, v174, v174 row_mirror row_mask:0xf bank_mask:0xf bound_ctrl:1
	v_add_f32_dpp v241, v241, v241 row_mirror row_mask:0xf bank_mask:0xf bound_ctrl:1
	v_add_f32_dpp v247, v247, v247 row_mirror row_mask:0xf bank_mask:0xf bound_ctrl:1
	v_readlane_b32 s36, v168, 16
	v_readlane_b32 s40, v174, 16
	v_readlane_b32 s44, v241, 16
	v_readlane_b32 s48, v247, 16
	v_readlane_b32 s37, v168, 48
	v_readlane_b32 s41, v174, 48
	v_readlane_b32 s45, v241, 48
	v_readlane_b32 s49, v247, 48
	v_readlane_b32 s38, v168, 0
	v_readlane_b32 s42, v174, 0
	v_readlane_b32 s46, v241, 0
	v_readlane_b32 s50, v247, 0
	v_readlane_b32 s39, v168, 32
; __device__ __forceinline__ float bf2f(bf16 x) { return __uint_as_float(((unsigned)x) << 16); }
; __device__ __forceinline__ unsigned f2bf(float f) { return cvt_pk_bf16(f, 0.f) & 0xffffu; }
; __device__ __forceinline__ void rw_post(Frame& F) {
;     ...
;                 const float mean = wsum(y[q]) * (1.f / 64.f); const float dv = y[q] - mean; const float var = wsum(dv * dv) * (1.f / 64.f);
;                 const float yn = dv * (1.f / sqrtf(var + 64e-5f)) * g_ + b_;
;                 OB[(size_t)row * DH + col] = (bf16)f2bf((yn + rk[q] * vv[q]) * bf2f(gg[q])); }
	v_readlane_b32 s43, v174, 32
	v_readlane_b32 s47, v241, 32
	v_readlane_b32 s51, v247, 32
	v_mov_b32_e32 v168, s36
	v_mov_b32_e32 v174, s40
	v_mov_b32_e32 v241, s44
	v_mov_b32_e32 v247, s48
	v_mov_b32_e32 v169, s37
	v_mov_b32_e32 v175, s41
	v_mov_b32_e32 v242, s45
	v_mov_b32_e32 v248, s49
	v_add_f32_e32 v168, s38, v168
	v_add_f32_e32 v174, s42, v174
	v_add_f32_e32 v241, s46, v241
	v_add_f32_e32 v247, s50, v247
	v_add_f32_e32 v169, s39, v169
	v_add_f32_e32 v175, s43, v175
	v_add_f32_e32 v242, s47, v242
	v_add_f32_e32 v248, s51, v248
	v_add_f32_e32 v168, v168, v169
	v_add_f32_e32 v174, v174, v175
	v_add_f32_e32 v241, v241, v242
	v_add_f32_e32 v247, v247, v248
	v_fmamk_f32 v168, v168, 0x3c800000, v9
	v_fmamk_f32 v174, v174, 0x3c800000, v9
	v_fmamk_f32 v241, v241, 0x3c800000, v9
	v_fmamk_f32 v247, v247, 0x3c800000, v9
	v_mul_f32_e32 v169, 0x4f800000, v168
	v_mul_f32_e32 v175, 0x4f800000, v174
	v_mul_f32_e32 v242, 0x4f800000, v241
	v_mul_f32_e32 v248, 0x4f800000, v247
	v_cmp_gt_f32_e64 s[52:53], s68, v168
	v_cmp_gt_f32_e64 s[54:55], s68, v174
	v_cmp_gt_f32_e64 s[56:57], s68, v241
	v_cmp_gt_f32_e64 s[58:59], s68, v247
	v_mov_b32_e32 v170, v168
	v_mov_b32_e32 v176, v174
	v_mov_b32_e32 v243, v241
	v_mov_b32_e32 v249, v247
	v_cndmask_b32_e64 v168, v170, v169, s[52:53]
	v_cndmask_b32_e64 v174, v176, v175, s[54:55]
	v_cndmask_b32_e64 v241, v243, v242, s[56:57]
	v_cndmask_b32_e64 v247, v249, v248, s[58:59]
	v_sqrt_f32_e32 v169, v168
	v_sqrt_f32_e32 v175, v174
	v_sqrt_f32_e32 v242, v241
	v_sqrt_f32_e32 v248, v247
	v_add_u32_e32 v170, -1, v169
	v_add_u32_e32 v176, -1, v175
	v_add_u32_e32 v243, -1, v242
	v_add_u32_e32 v249, -1, v248
	v_fma_f32 v171, -v170, v169, v168
	v_fma_f32 v177, -v176, v175, v174
	v_fma_f32 v244, -v243, v242, v241
	v_fma_f32 v250, -v249, v248, v247
	v_cmp_ge_f32_e64 s[60:61], 0, v171
	v_cmp_ge_f32_e64 s[62:63], 0, v177
	v_cmp_ge_f32_e64 s[64:65], 0, v244
	v_cmp_ge_f32_e64 s[66:67], 0, v250
	v_add_u32_e32 v171, 1, v169
	v_add_u32_e32 v177, 1, v175
	v_add_u32_e32 v244, 1, v242
	v_add_u32_e32 v250, 1, v248
	v_cndmask_b32_e64 v170, v169, v170, s[60:61]
	v_cndmask_b32_e64 v176, v175, v176, s[62:63]
	v_cndmask_b32_e64 v243, v242, v243, s[64:65]
	v_cndmask_b32_e64 v249, v248, v249, s[66:67]
	v_fma_f32 v169, -v171, v169, v168
	v_fma_f32 v175, -v177, v175, v174
	v_fma_f32 v242, -v244, v242, v241
	v_fma_f32 v248, -v250, v248, v247
	v_cmp_lt_f32_e64 s[60:61], 0, v169
	v_cmp_lt_f32_e64 s[62:63], 0, v175
	v_cmp_lt_f32_e64 s[64:65], 0, v242
	v_cmp_lt_f32_e64 s[66:67], 0, v248
	v_cndmask_b32_e64 v169, v170, v171, s[60:61]
	v_cndmask_b32_e64 v175, v176, v177, s[62:63]
	v_cndmask_b32_e64 v242, v243, v244, s[64:65]
	v_cndmask_b32_e64 v248, v249, v250, s[66:67]
	v_mul_f32_e32 v170, 0x37800000, v169
	v_mul_f32_e32 v176, 0x37800000, v175
	v_mul_f32_e32 v243, 0x37800000, v242
	v_mul_f32_e32 v249, 0x37800000, v248
	v_cndmask_b32_e64 v169, v169, v170, s[52:53]
	v_cndmask_b32_e64 v175, v175, v176, s[54:55]
	v_cndmask_b32_e64 v242, v242, v243, s[56:57]
	v_cndmask_b32_e64 v248, v248, v249, s[58:59]
	v_cmp_class_f32_e64 s[60:61], v168, v8
	v_cmp_class_f32_e64 s[62:63], v174, v8
	v_cmp_class_f32_e64 s[64:65], v241, v8
	v_cmp_class_f32_e64 s[66:67], v247, v8
	v_cndmask_b32_e64 v168, v169, v168, s[60:61]
	v_cndmask_b32_e64 v174, v175, v174, s[62:63]
	v_cndmask_b32_e64 v241, v242, v241, s[64:65]
	v_cndmask_b32_e64 v247, v248, v247, s[66:67]
	v_div_scale_f32 v169, s[60:61], v168, v168, 1.0
	v_rcp_f32_e32 v170, v169
	s_nop 0
	v_fma_f32 v171, -v169, v170, 1.0
	v_fmac_f32_e32 v170, v171, v170
	v_div_scale_f32 v171, vcc, 1.0, v168, 1.0
	v_mul_f32_e32 v172, v171, v170
	v_fma_f32 v173, -v169, v172, v171
	v_fmac_f32_e32 v172, v173, v170
	v_fma_f32 v169, -v169, v172, v171
	v_div_fmas_f32 v169, v169, v170, v172
	v_div_fixup_f32 v168, v169, v168, 1.0
	v_div_scale_f32 v175, s[62:63], v174, v174, 1.0
	v_rcp_f32_e32 v176, v175
	s_nop 0
	v_fma_f32 v177, -v175, v176, 1.0
	v_fmac_f32_e32 v176, v177, v176
	v_div_scale_f32 v177, vcc, 1.0, v174, 1.0
	v_mul_f32_e32 v236, v177, v176
	v_fma_f32 v237, -v175, v236, v177
	v_fmac_f32_e32 v236, v237, v176
	v_fma_f32 v175, -v175, v236, v177
	v_div_fmas_f32 v175, v175, v176, v236
	v_div_fixup_f32 v174, v175, v174, 1.0
	v_div_scale_f32 v242, s[64:65], v241, v241, 1.0
	v_rcp_f32_e32 v243, v242
	s_nop 0
	v_fma_f32 v244, -v242, v243, 1.0
	v_fmac_f32_e32 v243, v244, v243
	v_div_scale_f32 v244, vcc, 1.0, v241, 1.0
	v_mul_f32_e32 v245, v244, v243
	v_fma_f32 v246, -v242, v245, v244
	v_fmac_f32_e32 v245, v246, v243
	v_fma_f32 v242, -v242, v245, v244
	v_div_fmas_f32 v242, v242, v243, v245
	v_div_fixup_f32 v241, v242, v241, 1.0
	v_div_scale_f32 v248, s[66:67], v247, v247, 1.0
	v_rcp_f32_e32 v249, v248
	s_nop 0
	v_fma_f32 v250, -v248, v249, 1.0
	v_fmac_f32_e32 v249, v250, v249
	v_div_scale_f32 v250, vcc, 1.0, v247, 1.0
	v_mul_f32_e32 v251, v250, v249
	v_fma_f32 v252, -v248, v251, v250
	v_fmac_f32_e32 v251, v252, v249
	v_fma_f32 v248, -v248, v251, v250
	v_div_fmas_f32 v248, v248, v249, v251
	v_div_fixup_f32 v247, v248, v247, 1.0
	v_mul_f32_e32 v80, v80, v168
	v_mul_f32_e32 v85, v85, v174
	v_mul_f32_e32 v90, v90, v241
	v_mul_f32_e32 v95, v95, v247
	v_lshlrev_b32_e32 v83, 16, v83
	v_lshlrev_b32_e32 v88, 16, v88
	v_lshlrev_b32_e32 v93, 16, v93
	v_lshlrev_b32_e32 v98, 16, v98
	v_fma_f32 v80, v6, v80, v7
	v_fma_f32 v85, v6, v85, v7
	v_fma_f32 v90, v6, v90, v7
	v_fma_f32 v95, v6, v95, v7
	v_fmac_f32_e32 v80, s69, v81
	v_fmac_f32_e32 v85, s70, v86
	v_fmac_f32_e32 v90, s71, v91
	v_fmac_f32_e32 v95, s72, v96
	v_mul_f32_e32 v80, v80, v83
	v_mul_f32_e32 v85, v85, v88
	v_mul_f32_e32 v90, v90, v93
	v_mul_f32_e32 v95, v95, v98
	v_cvt_pk_bf16_f32 v169, v80, v80
; __device__ __forceinline__ float bf2f(bf16 x) { return __uint_as_float(((unsigned)x) << 16); }
; __device__ __forceinline__ unsigned f2bf(float f) { return cvt_pk_bf16(f, 0.f) & 0xffffu; }
; __device__ __forceinline__ void rw_post(Frame& F) {
;     ...
;             for (int q = 0; q < 8; ++q) { const int row = rb0 + t0 + q;
;                 const float mean = wsum(y[q]) * (1.f / 64.f); const float dv = y[q] - mean; const float var = wsum(dv * dv) * (1.f / 64.f);
;                 const float yn = dv * (1.f / sqrtf(var + 64e-5f)) * g_ + b_;
;                 OB[(size_t)row * DH + col] = (bf16)f2bf((yn + rk[q] * vv[q]) * bf2f(gg[q])); }
	v_cvt_pk_bf16_f32 v175, v85, v85
	v_cvt_pk_bf16_f32 v242, v90, v90
	v_cvt_pk_bf16_f32 v248, v95, v95
	global_store_short v2, v169, s[28:29]
	s_add_u32 s28, s28, 0x1000
	s_addc_u32 s29, s29, 0
	global_store_short v2, v175, s[28:29]
	s_add_u32 s28, s28, 0x1000
	s_addc_u32 s29, s29, 0
	global_store_short v2, v242, s[28:29]
	s_add_u32 s28, s28, 0x1000
	s_addc_u32 s29, s29, 0
	global_store_short v2, v248, s[28:29]
	s_add_u32 s28, s28, 0x1000
	s_addc_u32 s29, s29, 0
	v_add_f32_e32 v100, v100, v40
	v_add_f32_e32 v105, v105, v41
	v_add_f32_e32 v110, v110, v42
	v_add_f32_e32 v115, v115, v43
	v_add_f32_dpp v168, v100, v100 quad_perm:[1,0,3,2] row_mask:0xf bank_mask:0xf bound_ctrl:1
	v_add_f32_dpp v174, v105, v105 quad_perm:[1,0,3,2] row_mask:0xf bank_mask:0xf bound_ctrl:1
	v_add_f32_dpp v241, v110, v110 quad_perm:[1,0,3,2] row_mask:0xf bank_mask:0xf bound_ctrl:1
	v_add_f32_dpp v247, v115, v115 quad_perm:[1,0,3,2] row_mask:0xf bank_mask:0xf bound_ctrl:1
	v_add_f32_dpp v168, v168, v168 quad_perm:[2,3,0,1] row_mask:0xf bank_mask:0xf bound_ctrl:1
	v_add_f32_dpp v174, v174, v174 quad_perm:[2,3,0,1] row_mask:0xf bank_mask:0xf bound_ctrl:1
	v_add_f32_dpp v241, v241, v241 quad_perm:[2,3,0,1] row_mask:0xf bank_mask:0xf bound_ctrl:1
	v_add_f32_dpp v247, v247, v247 quad_perm:[2,3,0,1] row_mask:0xf bank_mask:0xf bound_ctrl:1
	v_add_f32_dpp v168, v168, v168 row_half_mirror row_mask:0xf bank_mask:0xf bound_ctrl:1
	v_add_f32_dpp v174, v174, v174 row_half_mirror row_mask:0xf bank_mask:0xf bound_ctrl:1
	v_add_f32_dpp v241, v241, v241 row_half_mirror row_mask:0xf bank_mask:0xf bound_ctrl:1
	v_add_f32_dpp v247, v247, v247 row_half_mirror row_mask:0xf bank_mask:0xf bound_ctrl:1
	v_add_f32_dpp v168, v168, v168 row_mirror row_mask:0xf bank_mask:0xf bound_ctrl:1
	v_add_f32_dpp v174, v174, v174 row_mirror row_mask:0xf bank_mask:0xf bound_ctrl:1
	v_add_f32_dpp v241, v241, v241 row_mirror row_mask:0xf bank_mask:0xf bound_ctrl:1
	v_add_f32_dpp v247, v247, v247 row_mirror row_mask:0xf bank_mask:0xf bound_ctrl:1
	v_readlane_b32 s36, v168, 16
	v_readlane_b32 s40, v174, 16
	v_readlane_b32 s44, v241, 16
	v_readlane_b32 s48, v247, 16
	v_readlane_b32 s37, v168, 48
	v_readlane_b32 s41, v174, 48
	v_readlane_b32 s45, v241, 48
	v_readlane_b32 s49, v247, 48
	v_readlane_b32 s38, v168, 0
	v_readlane_b32 s42, v174, 0
	v_readlane_b32 s46, v241, 0
	v_readlane_b32 s50, v247, 0
	v_readlane_b32 s39, v168, 32
	v_readlane_b32 s43, v174, 32
	v_readlane_b32 s47, v241, 32
	v_readlane_b32 s51, v247, 32
	v_mov_b32_e32 v168, s36
	v_mov_b32_e32 v174, s40
	v_mov_b32_e32 v241, s44
	v_mov_b32_e32 v247, s48
	v_mov_b32_e32 v169, s37
	v_mov_b32_e32 v175, s41
	v_mov_b32_e32 v242, s45
	v_mov_b32_e32 v248, s49
	v_add_f32_e32 v168, s38, v168
	v_add_f32_e32 v174, s42, v174
	v_add_f32_e32 v241, s46, v241
	v_add_f32_e32 v247, s50, v247
	v_add_f32_e32 v169, s39, v169
	v_add_f32_e32 v175, s43, v175
	v_add_f32_e32 v242, s47, v242
	v_add_f32_e32 v248, s51, v248
	v_add_f32_e32 v168, v168, v169
	v_add_f32_e32 v174, v174, v175
	v_add_f32_e32 v241, v241, v242
	v_add_f32_e32 v247, v247, v248
	v_fmamk_f32 v100, v168, 0xbc800000, v100
	v_fmamk_f32 v105, v174, 0xbc800000, v105
	v_fmamk_f32 v110, v241, 0xbc800000, v110
	v_fmamk_f32 v115, v247, 0xbc800000, v115
	v_mul_f32_e32 v168, v100, v100
	v_mul_f32_e32 v174, v105, v105
	v_mul_f32_e32 v241, v110, v110
	v_mul_f32_e32 v247, v115, v115
	v_mov_b32_dpp v168, v168 quad_perm:[1,0,3,2] row_mask:0xf bank_mask:0xf bound_ctrl:1
	v_mov_b32_dpp v174, v174 quad_perm:[1,0,3,2] row_mask:0xf bank_mask:0xf bound_ctrl:1
	v_mov_b32_dpp v241, v241 quad_perm:[1,0,3,2] row_mask:0xf bank_mask:0xf bound_ctrl:1
	v_mov_b32_dpp v247, v247 quad_perm:[1,0,3,2] row_mask:0xf bank_mask:0xf bound_ctrl:1
	v_fmac_f32_e32 v168, v100, v100
	v_fmac_f32_e32 v174, v105, v105
	v_fmac_f32_e32 v241, v110, v110
	v_fmac_f32_e32 v247, v115, v115
	v_add_f32_dpp v168, v168, v168 quad_perm:[2,3,0,1] row_mask:0xf bank_mask:0xf bound_ctrl:1
	v_add_f32_dpp v174, v174, v174 quad_perm:[2,3,0,1] row_mask:0xf bank_mask:0xf bound_ctrl:1
	v_add_f32_dpp v241, v241, v241 quad_perm:[2,3,0,1] row_mask:0xf bank_mask:0xf bound_ctrl:1
	v_add_f32_dpp v247, v247, v247 quad_perm:[2,3,0,1] row_mask:0xf bank_mask:0xf bound_ctrl:1
	v_add_f32_dpp v168, v168, v168 row_half_mirror row_mask:0xf bank_mask:0xf bound_ctrl:1
	v_add_f32_dpp v174, v174, v174 row_half_mirror row_mask:0xf bank_mask:0xf bound_ctrl:1
	v_add_f32_dpp v241, v241, v241 row_half_mirror row_mask:0xf bank_mask:0xf bound_ctrl:1
	v_add_f32_dpp v247, v247, v247 row_half_mirror row_mask:0xf bank_mask:0xf bound_ctrl:1
	v_add_f32_dpp v168, v168, v168 row_mirror row_mask:0xf bank_mask:0xf bound_ctrl:1
	v_add_f32_dpp v174, v174, v174 row_mirror row_mask:0xf bank_mask:0xf bound_ctrl:1
	v_add_f32_dpp v241, v241, v241 row_mirror row_mask:0xf bank_mask:0xf bound_ctrl:1
	v_add_f32_dpp v247, v247, v247 row_mirror row_mask:0xf bank_mask:0xf bound_ctrl:1
	v_readlane_b32 s36, v168, 16
	v_readlane_b32 s40, v174, 16
	v_readlane_b32 s44, v241, 16
	v_readlane_b32 s48, v247, 16
	v_readlane_b32 s37, v168, 48
	v_readlane_b32 s41, v174, 48
	v_readlane_b32 s45, v241, 48
	v_readlane_b32 s49, v247, 48
	v_readlane_b32 s38, v168, 0
	v_readlane_b32 s42, v174, 0
	v_readlane_b32 s46, v241, 0
	v_readlane_b32 s50, v247, 0
	v_readlane_b32 s39, v168, 32
	v_readlane_b32 s43, v174, 32
	v_readlane_b32 s47, v241, 32
	v_readlane_b32 s51, v247, 32
	v_mov_b32_e32 v168, s36
	v_mov_b32_e32 v174, s40
	v_mov_b32_e32 v241, s44
	v_mov_b32_e32 v247, s48
	v_mov_b32_e32 v169, s37
	v_mov_b32_e32 v175, s41
	v_mov_b32_e32 v242, s45
	v_mov_b32_e32 v248, s49
	v_add_f32_e32 v168, s38, v168
	v_add_f32_e32 v174, s42, v174
	v_add_f32_e32 v241, s46, v241
; __device__ __forceinline__ float bf2f(bf16 x) { return __uint_as_float(((unsigned)x) << 16); }
; __device__ __forceinline__ unsigned f2bf(float f) { return cvt_pk_bf16(f, 0.f) & 0xffffu; }
; #define POST_LD(Y_, V_, G_, R_, C_, t) do { _Pragma("unroll") for (int q = 0; q < 8; ++q) { const size_t o_ = (size_t)((t) + q) * DH; Y_[q] = yp[o_]; V_[q] = vp[o_]; G_[q] = gp[o_]; R_[q] = rp[((t) + q) * 32]; C_[q] = cp[o_]; } } while (0)
; __device__ __forceinline__ void rw_post(Frame& F) {
;     ...
;         POST_LD(y, vv, gg, rk, cc, 0);
;         for (int t0 = 0; t0 < 64; t0 += 8) {
;             float ny[8], nv[8], nr[8], nc[8]; bf16 ng[8];
;             const int tn = t0 + 8 < 64 ? t0 + 8 : t0;
;             POST_LD(ny, nv, ng, nr, nc, tn);
;     ...
;                 const float mean = wsum(y[q]) * (1.f / 64.f); const float dv = y[q] - mean; const float var = wsum(dv * dv) * (1.f / 64.f);
;                 const float yn = dv * (1.f / sqrtf(var + 64e-5f)) * g_ + b_;
;                 OB[(size_t)row * DH + col] = (bf16)f2bf((yn + rk[q] * vv[q]) * bf2f(gg[q])); }
; #pragma unroll
;             for (int q = 0; q < 8; ++q) { y[q] = ny[q]; vv[q] = nv[q]; gg[q] = ng[q]; rk[q] = nr[q]; cc[q] = nc[q]; }
	v_add_f32_e32 v247, s50, v247
	v_add_f32_e32 v169, s39, v169
	v_add_f32_e32 v175, s43, v175
	v_add_f32_e32 v242, s47, v242
	v_add_f32_e32 v248, s51, v248
	v_add_f32_e32 v168, v168, v169
	v_add_f32_e32 v174, v174, v175
	v_add_f32_e32 v241, v241, v242
	v_add_f32_e32 v247, v247, v248
	v_fmamk_f32 v168, v168, 0x3c800000, v9
	v_fmamk_f32 v174, v174, 0x3c800000, v9
	v_fmamk_f32 v241, v241, 0x3c800000, v9
	v_fmamk_f32 v247, v247, 0x3c800000, v9
	v_mul_f32_e32 v169, 0x4f800000, v168
	v_mul_f32_e32 v175, 0x4f800000, v174
	v_mul_f32_e32 v242, 0x4f800000, v241
	v_mul_f32_e32 v248, 0x4f800000, v247
	v_cmp_gt_f32_e64 s[52:53], s68, v168
	v_cmp_gt_f32_e64 s[54:55], s68, v174
	v_cmp_gt_f32_e64 s[56:57], s68, v241
	v_cmp_gt_f32_e64 s[58:59], s68, v247
	v_mov_b32_e32 v170, v168
	v_mov_b32_e32 v176, v174
	v_mov_b32_e32 v243, v241
	v_mov_b32_e32 v249, v247
	v_cndmask_b32_e64 v168, v170, v169, s[52:53]
	v_cndmask_b32_e64 v174, v176, v175, s[54:55]
	v_cndmask_b32_e64 v241, v243, v242, s[56:57]
	v_cndmask_b32_e64 v247, v249, v248, s[58:59]
	v_sqrt_f32_e32 v169, v168
	v_sqrt_f32_e32 v175, v174
	v_sqrt_f32_e32 v242, v241
	v_sqrt_f32_e32 v248, v247
	v_add_u32_e32 v170, -1, v169
	v_add_u32_e32 v176, -1, v175
	v_add_u32_e32 v243, -1, v242
	v_add_u32_e32 v249, -1, v248
	v_fma_f32 v171, -v170, v169, v168
	v_fma_f32 v177, -v176, v175, v174
	v_fma_f32 v244, -v243, v242, v241
	v_fma_f32 v250, -v249, v248, v247
	v_cmp_ge_f32_e64 s[60:61], 0, v171
	v_cmp_ge_f32_e64 s[62:63], 0, v177
	v_cmp_ge_f32_e64 s[64:65], 0, v244
	v_cmp_ge_f32_e64 s[66:67], 0, v250
	v_add_u32_e32 v171, 1, v169
	v_add_u32_e32 v177, 1, v175
	v_add_u32_e32 v244, 1, v242
	v_add_u32_e32 v250, 1, v248
	v_cndmask_b32_e64 v170, v169, v170, s[60:61]
	v_cndmask_b32_e64 v176, v175, v176, s[62:63]
	v_cndmask_b32_e64 v243, v242, v243, s[64:65]
	v_cndmask_b32_e64 v249, v248, v249, s[66:67]
	v_fma_f32 v169, -v171, v169, v168
	v_fma_f32 v175, -v177, v175, v174
	v_fma_f32 v242, -v244, v242, v241
	v_fma_f32 v248, -v250, v248, v247
	v_cmp_lt_f32_e64 s[60:61], 0, v169
	v_cmp_lt_f32_e64 s[62:63], 0, v175
	v_cmp_lt_f32_e64 s[64:65], 0, v242
	v_cmp_lt_f32_e64 s[66:67], 0, v248
	v_cndmask_b32_e64 v169, v170, v171, s[60:61]
	v_cndmask_b32_e64 v175, v176, v177, s[62:63]
	v_cndmask_b32_e64 v242, v243, v244, s[64:65]
	v_cndmask_b32_e64 v248, v249, v250, s[66:67]
	v_mul_f32_e32 v170, 0x37800000, v169
	v_mul_f32_e32 v176, 0x37800000, v175
	v_mul_f32_e32 v243, 0x37800000, v242
	v_mul_f32_e32 v249, 0x37800000, v248
	v_cndmask_b32_e64 v169, v169, v170, s[52:53]
	v_cndmask_b32_e64 v175, v175, v176, s[54:55]
	v_cndmask_b32_e64 v242, v242, v243, s[56:57]
	v_cndmask_b32_e64 v248, v248, v249, s[58:59]
	v_cmp_class_f32_e64 s[60:61], v168, v8
	v_cmp_class_f32_e64 s[62:63], v174, v8
	v_cmp_class_f32_e64 s[64:65], v241, v8
	v_cmp_class_f32_e64 s[66:67], v247, v8
	v_cndmask_b32_e64 v168, v169, v168, s[60:61]
	v_cndmask_b32_e64 v174, v175, v174, s[62:63]
	v_cndmask_b32_e64 v241, v242, v241, s[64:65]
	v_cndmask_b32_e64 v247, v248, v247, s[66:67]
	v_div_scale_f32 v169, s[60:61], v168, v168, 1.0
	v_rcp_f32_e32 v170, v169
	s_nop 0
	v_fma_f32 v171, -v169, v170, 1.0
	v_fmac_f32_e32 v170, v171, v170
	v_div_scale_f32 v171, vcc, 1.0, v168, 1.0
	v_mul_f32_e32 v172, v171, v170
	v_fma_f32 v173, -v169, v172, v171
	v_fmac_f32_e32 v172, v173, v170
	v_fma_f32 v169, -v169, v172, v171
	v_div_fmas_f32 v169, v169, v170, v172
	v_div_fixup_f32 v168, v169, v168, 1.0
	v_div_scale_f32 v175, s[62:63], v174, v174, 1.0
	v_rcp_f32_e32 v176, v175
	s_nop 0
	v_fma_f32 v177, -v175, v176, 1.0
	v_fmac_f32_e32 v176, v177, v176
	v_div_scale_f32 v177, vcc, 1.0, v174, 1.0
	v_mul_f32_e32 v236, v177, v176
	v_fma_f32 v237, -v175, v236, v177
	v_fmac_f32_e32 v236, v237, v176
	v_fma_f32 v175, -v175, v236, v177
	v_div_fmas_f32 v175, v175, v176, v236
	v_div_fixup_f32 v174, v175, v174, 1.0
	v_div_scale_f32 v242, s[64:65], v241, v241, 1.0
	v_rcp_f32_e32 v243, v242
	s_nop 0
	v_fma_f32 v244, -v242, v243, 1.0
	v_fmac_f32_e32 v243, v244, v243
	v_div_scale_f32 v244, vcc, 1.0, v241, 1.0
	v_mul_f32_e32 v245, v244, v243
	v_fma_f32 v246, -v242, v245, v244
	v_fmac_f32_e32 v245, v246, v243
	v_fma_f32 v242, -v242, v245, v244
	v_div_fmas_f32 v242, v242, v243, v245
	v_div_fixup_f32 v241, v242, v241, 1.0
	v_div_scale_f32 v248, s[66:67], v247, v247, 1.0
	v_rcp_f32_e32 v249, v248
	s_nop 0
	v_fma_f32 v250, -v248, v249, 1.0
	v_fmac_f32_e32 v249, v250, v249
	v_div_scale_f32 v250, vcc, 1.0, v247, 1.0
	v_mul_f32_e32 v251, v250, v249
	v_fma_f32 v252, -v248, v251, v250
	v_fmac_f32_e32 v251, v252, v249
	v_fma_f32 v248, -v248, v251, v250
	v_div_fmas_f32 v248, v248, v249, v251
	v_div_fixup_f32 v247, v248, v247, 1.0
	v_mul_f32_e32 v100, v100, v168
	v_mul_f32_e32 v105, v105, v174
	v_mul_f32_e32 v110, v110, v241
	v_mul_f32_e32 v115, v115, v247
	v_lshlrev_b32_e32 v103, 16, v103
	v_lshlrev_b32_e32 v108, 16, v108
	v_lshlrev_b32_e32 v113, 16, v113
	v_lshlrev_b32_e32 v118, 16, v118
	v_fma_f32 v100, v6, v100, v7
	v_fma_f32 v105, v6, v105, v7
	v_fma_f32 v110, v6, v110, v7
	v_fma_f32 v115, v6, v115, v7
	v_fmac_f32_e32 v100, s73, v101
	v_fmac_f32_e32 v105, s26, v106
	v_fmac_f32_e32 v110, s27, v111
	v_fmac_f32_e32 v115, s32, v116
	v_mul_f32_e32 v100, v100, v103
	v_mul_f32_e32 v105, v105, v108
	v_mul_f32_e32 v110, v110, v113
	v_mul_f32_e32 v115, v115, v118
	v_cvt_pk_bf16_f32 v169, v100, v100
	v_cvt_pk_bf16_f32 v175, v105, v105
	v_cvt_pk_bf16_f32 v242, v110, v110
	v_cvt_pk_bf16_f32 v248, v115, v115
	global_store_short v2, v169, s[28:29]
	s_add_u32 s28, s28, 0x1000
	s_addc_u32 s29, s29, 0
	global_store_short v2, v175, s[28:29]
	s_add_u32 s28, s28, 0x1000
	s_addc_u32 s29, s29, 0
	global_store_short v2, v242, s[28:29]
	s_add_u32 s28, s28, 0x1000
	s_addc_u32 s29, s29, 0
	global_store_short v2, v248, s[28:29]
	s_add_u32 s28, s28, 0x1000
	s_addc_u32 s29, s29, 0
	s_waitcnt vmcnt(8)
	ds_write_b128 v13, v[120:123] offset:0
	ds_write_b128 v13, v[124:127] offset:1024
	ds_write_b128 v13, v[128:131] offset:16384
	ds_write_b128 v13, v[132:135] offset:17408
	ds_write_b128 v15, v[136:139]
	v_readlane_b32 s69, v159, 0
	v_readlane_b32 s70, v159, 1
	v_readlane_b32 s71, v159, 2
	v_readlane_b32 s72, v159, 3
	v_readlane_b32 s73, v159, 4
	v_readlane_b32 s26, v159, 5
	v_readlane_b32 s27, v159, 6
	v_readlane_b32 s32, v159, 7
	global_load_dwordx4 v[120:123], v11, s[6:7]
	global_load_dwordx4 v[124:127], v11, s[6:7] offset:1024
	global_load_dwordx4 v[128:131], v11, s[8:9]
	global_load_dwordx4 v[132:135], v11, s[8:9] offset:1024
	global_load_dwordx4 v[136:139], v11, s[10:11]
	global_load_dword v159, v158, s[12:13]
	s_add_u32 s6, s6, 0x10000
	s_addc_u32 s7, s7, 0
	s_add_u32 s8, s8, 0x10000
	s_addc_u32 s9, s9, 0
	s_add_u32 s10, s10, 0x8000
	s_addc_u32 s11, s11, 0
	s_add_u32 s12, s12, 0x400
	s_addc_u32 s13, s13, 0
	s_waitcnt lgkmcnt(0)
	s_barrier
; __device__ __forceinline__ float bf2f(bf16 x) { return __uint_as_float(((unsigned)x) << 16); }
; __device__ __forceinline__ unsigned f2bf(float f) { return cvt_pk_bf16(f, 0.f) & 0xffffu; }
; __device__ __forceinline__ void rw_post(Frame& F) {
;     ...
;                         y[4 * hf + q] += (a[0] + a[1]) + (a[2] + a[3]); }
;                     asm volatile("s_waitcnt lgkmcnt(0)" ::: "memory"); }
;             }
; #pragma unroll
;             for (int q = 0; q < 8; ++q) { const int row = rb0 + t0 + q;
;                 const float mean = wsum(y[q]) * (1.f / 64.f); const float dv = y[q] - mean; const float var = wsum(dv * dv) * (1.f / 64.f);
;                 const float yn = dv * (1.f / sqrtf(var + 64e-5f)) * g_ + b_;
;                 OB[(size_t)row * DH + col] = (bf16)f2bf((yn + rk[q] * vv[q]) * bf2f(gg[q])); }
	ds_read_b32 v80, v155 offset:0
	ds_read_b32 v81, v155 offset:16384
	ds_read_u16 v83, v157 offset:0
	ds_read_b32 v85, v155 offset:2048
	ds_read_b32 v86, v155 offset:18432
	ds_read_u16 v88, v157 offset:1024
	ds_read_b32 v90, v155 offset:4096
	ds_read_b32 v91, v155 offset:20480
	ds_read_u16 v93, v157 offset:2048
	ds_read_b32 v95, v155 offset:6144
	ds_read_b32 v96, v155 offset:22528
	ds_read_u16 v98, v157 offset:3072
	ds_read_b32 v100, v155 offset:8192
	ds_read_b32 v101, v155 offset:24576
	ds_read_u16 v103, v157 offset:4096
	ds_read_b32 v105, v155 offset:10240
	ds_read_b32 v106, v155 offset:26624
	ds_read_u16 v108, v157 offset:5120
	ds_read_b32 v110, v155 offset:12288
	ds_read_b32 v111, v155 offset:28672
	ds_read_u16 v113, v157 offset:6144
	ds_read_b32 v115, v155 offset:14336
	ds_read_b32 v116, v155 offset:30720
	ds_read_u16 v118, v157 offset:7168
	s_waitcnt lgkmcnt(0)
	v_add_f32_e32 v80, v80, v28
	v_add_f32_e32 v85, v85, v29
	v_add_f32_e32 v90, v90, v30
	v_add_f32_e32 v95, v95, v31
	v_add_f32_dpp v168, v80, v80 quad_perm:[1,0,3,2] row_mask:0xf bank_mask:0xf bound_ctrl:1
	v_add_f32_dpp v174, v85, v85 quad_perm:[1,0,3,2] row_mask:0xf bank_mask:0xf bound_ctrl:1
	v_add_f32_dpp v241, v90, v90 quad_perm:[1,0,3,2] row_mask:0xf bank_mask:0xf bound_ctrl:1
	v_add_f32_dpp v247, v95, v95 quad_perm:[1,0,3,2] row_mask:0xf bank_mask:0xf bound_ctrl:1
	v_add_f32_dpp v168, v168, v168 quad_perm:[2,3,0,1] row_mask:0xf bank_mask:0xf bound_ctrl:1
	v_add_f32_dpp v174, v174, v174 quad_perm:[2,3,0,1] row_mask:0xf bank_mask:0xf bound_ctrl:1
	v_add_f32_dpp v241, v241, v241 quad_perm:[2,3,0,1] row_mask:0xf bank_mask:0xf bound_ctrl:1
	v_add_f32_dpp v247, v247, v247 quad_perm:[2,3,0,1] row_mask:0xf bank_mask:0xf bound_ctrl:1
	v_add_f32_dpp v168, v168, v168 row_half_mirror row_mask:0xf bank_mask:0xf bound_ctrl:1
	v_add_f32_dpp v174, v174, v174 row_half_mirror row_mask:0xf bank_mask:0xf bound_ctrl:1
	v_add_f32_dpp v241, v241, v241 row_half_mirror row_mask:0xf bank_mask:0xf bound_ctrl:1
	v_add_f32_dpp v247, v247, v247 row_half_mirror row_mask:0xf bank_mask:0xf bound_ctrl:1
	v_add_f32_dpp v168, v168, v168 row_mirror row_mask:0xf bank_mask:0xf bound_ctrl:1
	v_add_f32_dpp v174, v174, v174 row_mirror row_mask:0xf bank_mask:0xf bound_ctrl:1
	v_add_f32_dpp v241, v241, v241 row_mirror row_mask:0xf bank_mask:0xf bound_ctrl:1
	v_add_f32_dpp v247, v247, v247 row_mirror row_mask:0xf bank_mask:0xf bound_ctrl:1
	v_readlane_b32 s36, v168, 16
	v_readlane_b32 s40, v174, 16
	v_readlane_b32 s44, v241, 16
	v_readlane_b32 s48, v247, 16
	v_readlane_b32 s37, v168, 48
	v_readlane_b32 s41, v174, 48
	v_readlane_b32 s45, v241, 48
	v_readlane_b32 s49, v247, 48
	v_readlane_b32 s38, v168, 0
	v_readlane_b32 s42, v174, 0
	v_readlane_b32 s46, v241, 0
	v_readlane_b32 s50, v247, 0
	v_readlane_b32 s39, v168, 32
	v_readlane_b32 s43, v174, 32
	v_readlane_b32 s47, v241, 32
	v_readlane_b32 s51, v247, 32
	v_mov_b32_e32 v168, s36
	v_mov_b32_e32 v174, s40
	v_mov_b32_e32 v241, s44
	v_mov_b32_e32 v247, s48
	v_mov_b32_e32 v169, s37
	v_mov_b32_e32 v175, s41
	v_mov_b32_e32 v242, s45
	v_mov_b32_e32 v248, s49
	v_add_f32_e32 v168, s38, v168
	v_add_f32_e32 v174, s42, v174
	v_add_f32_e32 v241, s46, v241
	v_add_f32_e32 v247, s50, v247
	v_add_f32_e32 v169, s39, v169
	v_add_f32_e32 v175, s43, v175
	v_add_f32_e32 v242, s47, v242
	v_add_f32_e32 v248, s51, v248
	v_add_f32_e32 v168, v168, v169
	v_add_f32_e32 v174, v174, v175
	v_add_f32_e32 v241, v241, v242
	v_add_f32_e32 v247, v247, v248
	v_fmamk_f32 v80, v168, 0xbc800000, v80
	v_fmamk_f32 v85, v174, 0xbc800000, v85
	v_fmamk_f32 v90, v241, 0xbc800000, v90
	v_fmamk_f32 v95, v247, 0xbc800000, v95
	v_mul_f32_e32 v168, v80, v80
	v_mul_f32_e32 v174, v85, v85
	v_mul_f32_e32 v241, v90, v90
	v_mul_f32_e32 v247, v95, v95
	v_mov_b32_dpp v168, v168 quad_perm:[1,0,3,2] row_mask:0xf bank_mask:0xf bound_ctrl:1
	v_mov_b32_dpp v174, v174 quad_perm:[1,0,3,2] row_mask:0xf bank_mask:0xf bound_ctrl:1
	v_mov_b32_dpp v241, v241 quad_perm:[1,0,3,2] row_mask:0xf bank_mask:0xf bound_ctrl:1
	v_mov_b32_dpp v247, v247 quad_perm:[1,0,3,2] row_mask:0xf bank_mask:0xf bound_ctrl:1
	v_fmac_f32_e32 v168, v80, v80
	v_fmac_f32_e32 v174, v85, v85
	v_fmac_f32_e32 v241, v90, v90
	v_fmac_f32_e32 v247, v95, v95
	v_add_f32_dpp v168, v168, v168 quad_perm:[2,3,0,1] row_mask:0xf bank_mask:0xf bound_ctrl:1
	v_add_f32_dpp v174, v174, v174 quad_perm:[2,3,0,1] row_mask:0xf bank_mask:0xf bound_ctrl:1
	v_add_f32_dpp v241, v241, v241 quad_perm:[2,3,0,1] row_mask:0xf bank_mask:0xf bound_ctrl:1
	v_add_f32_dpp v247, v247, v247 quad_perm:[2,3,0,1] row_mask:0xf bank_mask:0xf bound_ctrl:1
	v_add_f32_dpp v168, v168, v168 row_half_mirror row_mask:0xf bank_mask:0xf bound_ctrl:1
	v_add_f32_dpp v174, v174, v174 row_half_mirror row_mask:0xf bank_mask:0xf bound_ctrl:1
	v_add_f32_dpp v241, v241, v241 row_half_mirror row_mask:0xf bank_mask:0xf bound_ctrl:1
	v_add_f32_dpp v247, v247, v247 row_half_mirror row_mask:0xf bank_mask:0xf bound_ctrl:1
	v_add_f32_dpp v168, v168, v168 row_mirror row_mask:0xf bank_mask:0xf bound_ctrl:1
	v_add_f32_dpp v174, v174, v174 row_mirror row_mask:0xf bank_mask:0xf bound_ctrl:1
	v_add_f32_dpp v241, v241, v241 row_mirror row_mask:0xf bank_mask:0xf bound_ctrl:1
	v_add_f32_dpp v247, v247, v247 row_mirror row_mask:0xf bank_mask:0xf bound_ctrl:1
	v_readlane_b32 s36, v168, 16
	v_readlane_b32 s40, v174, 16
	v_readlane_b32 s44, v241, 16
	v_readlane_b32 s48, v247, 16
	v_readlane_b32 s37, v168, 48
	v_readlane_b32 s41, v174, 48
	v_readlane_b32 s45, v241, 48
	v_readlane_b32 s49, v247, 48
	v_readlane_b32 s38, v168, 0
	v_readlane_b32 s42, v174, 0
	v_readlane_b32 s46, v241, 0
	v_readlane_b32 s50, v247, 0
	v_readlane_b32 s39, v168, 32
; __device__ __forceinline__ float bf2f(bf16 x) { return __uint_as_float(((unsigned)x) << 16); }
; __device__ __forceinline__ unsigned f2bf(float f) { return cvt_pk_bf16(f, 0.f) & 0xffffu; }
; __device__ __forceinline__ void rw_post(Frame& F) {
;     ...
;                 const float mean = wsum(y[q]) * (1.f / 64.f); const float dv = y[q] - mean; const float var = wsum(dv * dv) * (1.f / 64.f);
;                 const float yn = dv * (1.f / sqrtf(var + 64e-5f)) * g_ + b_;
;                 OB[(size_t)row * DH + col] = (bf16)f2bf((yn + rk[q] * vv[q]) * bf2f(gg[q])); }
	v_readlane_b32 s43, v174, 32
	v_readlane_b32 s47, v241, 32
	v_readlane_b32 s51, v247, 32
	v_mov_b32_e32 v168, s36
	v_mov_b32_e32 v174, s40
	v_mov_b32_e32 v241, s44
	v_mov_b32_e32 v247, s48
	v_mov_b32_e32 v169, s37
	v_mov_b32_e32 v175, s41
	v_mov_b32_e32 v242, s45
	v_mov_b32_e32 v248, s49
	v_add_f32_e32 v168, s38, v168
	v_add_f32_e32 v174, s42, v174
	v_add_f32_e32 v241, s46, v241
	v_add_f32_e32 v247, s50, v247
	v_add_f32_e32 v169, s39, v169
	v_add_f32_e32 v175, s43, v175
	v_add_f32_e32 v242, s47, v242
	v_add_f32_e32 v248, s51, v248
	v_add_f32_e32 v168, v168, v169
	v_add_f32_e32 v174, v174, v175
	v_add_f32_e32 v241, v241, v242
	v_add_f32_e32 v247, v247, v248
	v_fmamk_f32 v168, v168, 0x3c800000, v9
	v_fmamk_f32 v174, v174, 0x3c800000, v9
	v_fmamk_f32 v241, v241, 0x3c800000, v9
	v_fmamk_f32 v247, v247, 0x3c800000, v9
	v_mul_f32_e32 v169, 0x4f800000, v168
	v_mul_f32_e32 v175, 0x4f800000, v174
	v_mul_f32_e32 v242, 0x4f800000, v241
	v_mul_f32_e32 v248, 0x4f800000, v247
	v_cmp_gt_f32_e64 s[52:53], s68, v168
	v_cmp_gt_f32_e64 s[54:55], s68, v174
	v_cmp_gt_f32_e64 s[56:57], s68, v241
	v_cmp_gt_f32_e64 s[58:59], s68, v247
	v_mov_b32_e32 v170, v168
	v_mov_b32_e32 v176, v174
	v_mov_b32_e32 v243, v241
	v_mov_b32_e32 v249, v247
	v_cndmask_b32_e64 v168, v170, v169, s[52:53]
	v_cndmask_b32_e64 v174, v176, v175, s[54:55]
	v_cndmask_b32_e64 v241, v243, v242, s[56:57]
	v_cndmask_b32_e64 v247, v249, v248, s[58:59]
	v_sqrt_f32_e32 v169, v168
	v_sqrt_f32_e32 v175, v174
	v_sqrt_f32_e32 v242, v241
	v_sqrt_f32_e32 v248, v247
	v_add_u32_e32 v170, -1, v169
	v_add_u32_e32 v176, -1, v175
	v_add_u32_e32 v243, -1, v242
	v_add_u32_e32 v249, -1, v248
	v_fma_f32 v171, -v170, v169, v168
	v_fma_f32 v177, -v176, v175, v174
	v_fma_f32 v244, -v243, v242, v241
	v_fma_f32 v250, -v249, v248, v247
	v_cmp_ge_f32_e64 s[60:61], 0, v171
	v_cmp_ge_f32_e64 s[62:63], 0, v177
	v_cmp_ge_f32_e64 s[64:65], 0, v244
	v_cmp_ge_f32_e64 s[66:67], 0, v250
	v_add_u32_e32 v171, 1, v169
	v_add_u32_e32 v177, 1, v175
	v_add_u32_e32 v244, 1, v242
	v_add_u32_e32 v250, 1, v248
	v_cndmask_b32_e64 v170, v169, v170, s[60:61]
	v_cndmask_b32_e64 v176, v175, v176, s[62:63]
	v_cndmask_b32_e64 v243, v242, v243, s[64:65]
	v_cndmask_b32_e64 v249, v248, v249, s[66:67]
	v_fma_f32 v169, -v171, v169, v168
	v_fma_f32 v175, -v177, v175, v174
	v_fma_f32 v242, -v244, v242, v241
	v_fma_f32 v248, -v250, v248, v247
	v_cmp_lt_f32_e64 s[60:61], 0, v169
	v_cmp_lt_f32_e64 s[62:63], 0, v175
	v_cmp_lt_f32_e64 s[64:65], 0, v242
	v_cmp_lt_f32_e64 s[66:67], 0, v248
	v_cndmask_b32_e64 v169, v170, v171, s[60:61]
	v_cndmask_b32_e64 v175, v176, v177, s[62:63]
	v_cndmask_b32_e64 v242, v243, v244, s[64:65]
	v_cndmask_b32_e64 v248, v249, v250, s[66:67]
	v_mul_f32_e32 v170, 0x37800000, v169
	v_mul_f32_e32 v176, 0x37800000, v175
	v_mul_f32_e32 v243, 0x37800000, v242
	v_mul_f32_e32 v249, 0x37800000, v248
	v_cndmask_b32_e64 v169, v169, v170, s[52:53]
	v_cndmask_b32_e64 v175, v175, v176, s[54:55]
	v_cndmask_b32_e64 v242, v242, v243, s[56:57]
	v_cndmask_b32_e64 v248, v248, v249, s[58:59]
	v_cmp_class_f32_e64 s[60:61], v168, v8
	v_cmp_class_f32_e64 s[62:63], v174, v8
	v_cmp_class_f32_e64 s[64:65], v241, v8
	v_cmp_class_f32_e64 s[66:67], v247, v8
	v_cndmask_b32_e64 v168, v169, v168, s[60:61]
	v_cndmask_b32_e64 v174, v175, v174, s[62:63]
	v_cndmask_b32_e64 v241, v242, v241, s[64:65]
	v_cndmask_b32_e64 v247, v248, v247, s[66:67]
	v_div_scale_f32 v169, s[60:61], v168, v168, 1.0
	v_rcp_f32_e32 v170, v169
	s_nop 0
	v_fma_f32 v171, -v169, v170, 1.0
	v_fmac_f32_e32 v170, v171, v170
	v_div_scale_f32 v171, vcc, 1.0, v168, 1.0
	v_mul_f32_e32 v172, v171, v170
	v_fma_f32 v173, -v169, v172, v171
	v_fmac_f32_e32 v172, v173, v170
	v_fma_f32 v169, -v169, v172, v171
	v_div_fmas_f32 v169, v169, v170, v172
	v_div_fixup_f32 v168, v169, v168, 1.0
	v_div_scale_f32 v175, s[62:63], v174, v174, 1.0
	v_rcp_f32_e32 v176, v175
	s_nop 0
	v_fma_f32 v177, -v175, v176, 1.0
	v_fmac_f32_e32 v176, v177, v176
	v_div_scale_f32 v177, vcc, 1.0, v174, 1.0
	v_mul_f32_e32 v236, v177, v176
	v_fma_f32 v237, -v175, v236, v177
	v_fmac_f32_e32 v236, v237, v176
	v_fma_f32 v175, -v175, v236, v177
	v_div_fmas_f32 v175, v175, v176, v236
	v_div_fixup_f32 v174, v175, v174, 1.0
	v_div_scale_f32 v242, s[64:65], v241, v241, 1.0
	v_rcp_f32_e32 v243, v242
	s_nop 0
	v_fma_f32 v244, -v242, v243, 1.0
	v_fmac_f32_e32 v243, v244, v243
	v_div_scale_f32 v244, vcc, 1.0, v241, 1.0
	v_mul_f32_e32 v245, v244, v243
	v_fma_f32 v246, -v242, v245, v244
	v_fmac_f32_e32 v245, v246, v243
	v_fma_f32 v242, -v242, v245, v244
	v_div_fmas_f32 v242, v242, v243, v245
	v_div_fixup_f32 v241, v242, v241, 1.0
	v_div_scale_f32 v248, s[66:67], v247, v247, 1.0
	v_rcp_f32_e32 v249, v248
	s_nop 0
	v_fma_f32 v250, -v248, v249, 1.0
	v_fmac_f32_e32 v249, v250, v249
	v_div_scale_f32 v250, vcc, 1.0, v247, 1.0
	v_mul_f32_e32 v251, v250, v249
	v_fma_f32 v252, -v248, v251, v250
	v_fmac_f32_e32 v251, v252, v249
	v_fma_f32 v248, -v248, v251, v250
	v_div_fmas_f32 v248, v248, v249, v251
	v_div_fixup_f32 v247, v248, v247, 1.0
	v_mul_f32_e32 v80, v80, v168
	v_mul_f32_e32 v85, v85, v174
	v_mul_f32_e32 v90, v90, v241
	v_mul_f32_e32 v95, v95, v247
	v_lshlrev_b32_e32 v83, 16, v83
	v_lshlrev_b32_e32 v88, 16, v88
	v_lshlrev_b32_e32 v93, 16, v93
	v_lshlrev_b32_e32 v98, 16, v98
	v_fma_f32 v80, v6, v80, v7
	v_fma_f32 v85, v6, v85, v7
	v_fma_f32 v90, v6, v90, v7
	v_fma_f32 v95, v6, v95, v7
	v_fmac_f32_e32 v80, s69, v81
	v_fmac_f32_e32 v85, s70, v86
	v_fmac_f32_e32 v90, s71, v91
	v_fmac_f32_e32 v95, s72, v96
	v_mul_f32_e32 v80, v80, v83
	v_mul_f32_e32 v85, v85, v88
	v_mul_f32_e32 v90, v90, v93
	v_mul_f32_e32 v95, v95, v98
	v_cvt_pk_bf16_f32 v169, v80, v80
; __device__ __forceinline__ float bf2f(bf16 x) { return __uint_as_float(((unsigned)x) << 16); }
; __device__ __forceinline__ unsigned f2bf(float f) { return cvt_pk_bf16(f, 0.f) & 0xffffu; }
; __device__ __forceinline__ void rw_post(Frame& F) {
;     ...
;             for (int q = 0; q < 8; ++q) { const int row = rb0 + t0 + q;
;                 const float mean = wsum(y[q]) * (1.f / 64.f); const float dv = y[q] - mean; const float var = wsum(dv * dv) * (1.f / 64.f);
;                 const float yn = dv * (1.f / sqrtf(var + 64e-5f)) * g_ + b_;
;                 OB[(size_t)row * DH + col] = (bf16)f2bf((yn + rk[q] * vv[q]) * bf2f(gg[q])); }
	v_cvt_pk_bf16_f32 v175, v85, v85
	v_cvt_pk_bf16_f32 v242, v90, v90
	v_cvt_pk_bf16_f32 v248, v95, v95
	global_store_short v2, v169, s[28:29]
	s_add_u32 s28, s28, 0x1000
	s_addc_u32 s29, s29, 0
	global_store_short v2, v175, s[28:29]
	s_add_u32 s28, s28, 0x1000
	s_addc_u32 s29, s29, 0
	global_store_short v2, v242, s[28:29]
	s_add_u32 s28, s28, 0x1000
	s_addc_u32 s29, s29, 0
	global_store_short v2, v248, s[28:29]
	s_add_u32 s28, s28, 0x1000
	s_addc_u32 s29, s29, 0
	v_add_f32_e32 v100, v100, v44
	v_add_f32_e32 v105, v105, v45
	v_add_f32_e32 v110, v110, v46
	v_add_f32_e32 v115, v115, v47
	v_add_f32_dpp v168, v100, v100 quad_perm:[1,0,3,2] row_mask:0xf bank_mask:0xf bound_ctrl:1
	v_add_f32_dpp v174, v105, v105 quad_perm:[1,0,3,2] row_mask:0xf bank_mask:0xf bound_ctrl:1
	v_add_f32_dpp v241, v110, v110 quad_perm:[1,0,3,2] row_mask:0xf bank_mask:0xf bound_ctrl:1
	v_add_f32_dpp v247, v115, v115 quad_perm:[1,0,3,2] row_mask:0xf bank_mask:0xf bound_ctrl:1
	v_add_f32_dpp v168, v168, v168 quad_perm:[2,3,0,1] row_mask:0xf bank_mask:0xf bound_ctrl:1
	v_add_f32_dpp v174, v174, v174 quad_perm:[2,3,0,1] row_mask:0xf bank_mask:0xf bound_ctrl:1
	v_add_f32_dpp v241, v241, v241 quad_perm:[2,3,0,1] row_mask:0xf bank_mask:0xf bound_ctrl:1
	v_add_f32_dpp v247, v247, v247 quad_perm:[2,3,0,1] row_mask:0xf bank_mask:0xf bound_ctrl:1
	v_add_f32_dpp v168, v168, v168 row_half_mirror row_mask:0xf bank_mask:0xf bound_ctrl:1
	v_add_f32_dpp v174, v174, v174 row_half_mirror row_mask:0xf bank_mask:0xf bound_ctrl:1
	v_add_f32_dpp v241, v241, v241 row_half_mirror row_mask:0xf bank_mask:0xf bound_ctrl:1
	v_add_f32_dpp v247, v247, v247 row_half_mirror row_mask:0xf bank_mask:0xf bound_ctrl:1
	v_add_f32_dpp v168, v168, v168 row_mirror row_mask:0xf bank_mask:0xf bound_ctrl:1
	v_add_f32_dpp v174, v174, v174 row_mirror row_mask:0xf bank_mask:0xf bound_ctrl:1
	v_add_f32_dpp v241, v241, v241 row_mirror row_mask:0xf bank_mask:0xf bound_ctrl:1
	v_add_f32_dpp v247, v247, v247 row_mirror row_mask:0xf bank_mask:0xf bound_ctrl:1
	v_readlane_b32 s36, v168, 16
	v_readlane_b32 s40, v174, 16
	v_readlane_b32 s44, v241, 16
	v_readlane_b32 s48, v247, 16
	v_readlane_b32 s37, v168, 48
	v_readlane_b32 s41, v174, 48
	v_readlane_b32 s45, v241, 48
	v_readlane_b32 s49, v247, 48
	v_readlane_b32 s38, v168, 0
	v_readlane_b32 s42, v174, 0
	v_readlane_b32 s46, v241, 0
	v_readlane_b32 s50, v247, 0
	v_readlane_b32 s39, v168, 32
	v_readlane_b32 s43, v174, 32
	v_readlane_b32 s47, v241, 32
	v_readlane_b32 s51, v247, 32
	v_mov_b32_e32 v168, s36
	v_mov_b32_e32 v174, s40
	v_mov_b32_e32 v241, s44
	v_mov_b32_e32 v247, s48
	v_mov_b32_e32 v169, s37
	v_mov_b32_e32 v175, s41
	v_mov_b32_e32 v242, s45
	v_mov_b32_e32 v248, s49
	v_add_f32_e32 v168, s38, v168
	v_add_f32_e32 v174, s42, v174
	v_add_f32_e32 v241, s46, v241
	v_add_f32_e32 v247, s50, v247
	v_add_f32_e32 v169, s39, v169
	v_add_f32_e32 v175, s43, v175
	v_add_f32_e32 v242, s47, v242
	v_add_f32_e32 v248, s51, v248
	v_add_f32_e32 v168, v168, v169
	v_add_f32_e32 v174, v174, v175
	v_add_f32_e32 v241, v241, v242
	v_add_f32_e32 v247, v247, v248
	v_fmamk_f32 v100, v168, 0xbc800000, v100
	v_fmamk_f32 v105, v174, 0xbc800000, v105
	v_fmamk_f32 v110, v241, 0xbc800000, v110
	v_fmamk_f32 v115, v247, 0xbc800000, v115
	v_mul_f32_e32 v168, v100, v100
	v_mul_f32_e32 v174, v105, v105
	v_mul_f32_e32 v241, v110, v110
	v_mul_f32_e32 v247, v115, v115
	v_mov_b32_dpp v168, v168 quad_perm:[1,0,3,2] row_mask:0xf bank_mask:0xf bound_ctrl:1
	v_mov_b32_dpp v174, v174 quad_perm:[1,0,3,2] row_mask:0xf bank_mask:0xf bound_ctrl:1
	v_mov_b32_dpp v241, v241 quad_perm:[1,0,3,2] row_mask:0xf bank_mask:0xf bound_ctrl:1
	v_mov_b32_dpp v247, v247 quad_perm:[1,0,3,2] row_mask:0xf bank_mask:0xf bound_ctrl:1
	v_fmac_f32_e32 v168, v100, v100
	v_fmac_f32_e32 v174, v105, v105
	v_fmac_f32_e32 v241, v110, v110
	v_fmac_f32_e32 v247, v115, v115
	v_add_f32_dpp v168, v168, v168 quad_perm:[2,3,0,1] row_mask:0xf bank_mask:0xf bound_ctrl:1
	v_add_f32_dpp v174, v174, v174 quad_perm:[2,3,0,1] row_mask:0xf bank_mask:0xf bound_ctrl:1
	v_add_f32_dpp v241, v241, v241 quad_perm:[2,3,0,1] row_mask:0xf bank_mask:0xf bound_ctrl:1
	v_add_f32_dpp v247, v247, v247 quad_perm:[2,3,0,1] row_mask:0xf bank_mask:0xf bound_ctrl:1
	v_add_f32_dpp v168, v168, v168 row_half_mirror row_mask:0xf bank_mask:0xf bound_ctrl:1
	v_add_f32_dpp v174, v174, v174 row_half_mirror row_mask:0xf bank_mask:0xf bound_ctrl:1
	v_add_f32_dpp v241, v241, v241 row_half_mirror row_mask:0xf bank_mask:0xf bound_ctrl:1
	v_add_f32_dpp v247, v247, v247 row_half_mirror row_mask:0xf bank_mask:0xf bound_ctrl:1
	v_add_f32_dpp v168, v168, v168 row_mirror row_mask:0xf bank_mask:0xf bound_ctrl:1
	v_add_f32_dpp v174, v174, v174 row_mirror row_mask:0xf bank_mask:0xf bound_ctrl:1
	v_add_f32_dpp v241, v241, v241 row_mirror row_mask:0xf bank_mask:0xf bound_ctrl:1
	v_add_f32_dpp v247, v247, v247 row_mirror row_mask:0xf bank_mask:0xf bound_ctrl:1
	v_readlane_b32 s36, v168, 16
	v_readlane_b32 s40, v174, 16
	v_readlane_b32 s44, v241, 16
	v_readlane_b32 s48, v247, 16
	v_readlane_b32 s37, v168, 48
	v_readlane_b32 s41, v174, 48
	v_readlane_b32 s45, v241, 48
	v_readlane_b32 s49, v247, 48
	v_readlane_b32 s38, v168, 0
	v_readlane_b32 s42, v174, 0
	v_readlane_b32 s46, v241, 0
	v_readlane_b32 s50, v247, 0
	v_readlane_b32 s39, v168, 32
	v_readlane_b32 s43, v174, 32
	v_readlane_b32 s47, v241, 32
	v_readlane_b32 s51, v247, 32
	v_mov_b32_e32 v168, s36
	v_mov_b32_e32 v174, s40
	v_mov_b32_e32 v241, s44
	v_mov_b32_e32 v247, s48
	v_mov_b32_e32 v169, s37
	v_mov_b32_e32 v175, s41
	v_mov_b32_e32 v242, s45
	v_mov_b32_e32 v248, s49
	v_add_f32_e32 v168, s38, v168
	v_add_f32_e32 v174, s42, v174
	v_add_f32_e32 v241, s46, v241
; __device__ __forceinline__ float bf2f(bf16 x) { return __uint_as_float(((unsigned)x) << 16); }
; __device__ __forceinline__ unsigned f2bf(float f) { return cvt_pk_bf16(f, 0.f) & 0xffffu; }
; #define POST_LD(Y_, V_, G_, R_, C_, t) do { _Pragma("unroll") for (int q = 0; q < 8; ++q) { const size_t o_ = (size_t)((t) + q) * DH; Y_[q] = yp[o_]; V_[q] = vp[o_]; G_[q] = gp[o_]; R_[q] = rp[((t) + q) * 32]; C_[q] = cp[o_]; } } while (0)
; __device__ __forceinline__ void rw_post(Frame& F) {
;     ...
;         POST_LD(y, vv, gg, rk, cc, 0);
;         for (int t0 = 0; t0 < 64; t0 += 8) {
;             float ny[8], nv[8], nr[8], nc[8]; bf16 ng[8];
;             const int tn = t0 + 8 < 64 ? t0 + 8 : t0;
;             POST_LD(ny, nv, ng, nr, nc, tn);
;     ...
;             for (int q = 0; q < 8; ++q) { const int row = rb0 + t0 + q;
;                 const float mean = wsum(y[q]) * (1.f / 64.f); const float dv = y[q] - mean; const float var = wsum(dv * dv) * (1.f / 64.f);
;                 const float yn = dv * (1.f / sqrtf(var + 64e-5f)) * g_ + b_;
;                 OB[(size_t)row * DH + col] = (bf16)f2bf((yn + rk[q] * vv[q]) * bf2f(gg[q])); }
	v_add_f32_e32 v247, s50, v247
	v_add_f32_e32 v169, s39, v169
	v_add_f32_e32 v175, s43, v175
	v_add_f32_e32 v242, s47, v242
	v_add_f32_e32 v248, s51, v248
	v_add_f32_e32 v168, v168, v169
	v_add_f32_e32 v174, v174, v175
	v_add_f32_e32 v241, v241, v242
	v_add_f32_e32 v247, v247, v248
	v_fmamk_f32 v168, v168, 0x3c800000, v9
	v_fmamk_f32 v174, v174, 0x3c800000, v9
	v_fmamk_f32 v241, v241, 0x3c800000, v9
	v_fmamk_f32 v247, v247, 0x3c800000, v9
	v_mul_f32_e32 v169, 0x4f800000, v168
	v_mul_f32_e32 v175, 0x4f800000, v174
	v_mul_f32_e32 v242, 0x4f800000, v241
	v_mul_f32_e32 v248, 0x4f800000, v247
	v_cmp_gt_f32_e64 s[52:53], s68, v168
	v_cmp_gt_f32_e64 s[54:55], s68, v174
	v_cmp_gt_f32_e64 s[56:57], s68, v241
	v_cmp_gt_f32_e64 s[58:59], s68, v247
	v_mov_b32_e32 v170, v168
	v_mov_b32_e32 v176, v174
	v_mov_b32_e32 v243, v241
	v_mov_b32_e32 v249, v247
	v_cndmask_b32_e64 v168, v170, v169, s[52:53]
	v_cndmask_b32_e64 v174, v176, v175, s[54:55]
	v_cndmask_b32_e64 v241, v243, v242, s[56:57]
	v_cndmask_b32_e64 v247, v249, v248, s[58:59]
	v_sqrt_f32_e32 v169, v168
	v_sqrt_f32_e32 v175, v174
	v_sqrt_f32_e32 v242, v241
	v_sqrt_f32_e32 v248, v247
	v_add_u32_e32 v170, -1, v169
	v_add_u32_e32 v176, -1, v175
	v_add_u32_e32 v243, -1, v242
	v_add_u32_e32 v249, -1, v248
	v_fma_f32 v171, -v170, v169, v168
	v_fma_f32 v177, -v176, v175, v174
	v_fma_f32 v244, -v243, v242, v241
	v_fma_f32 v250, -v249, v248, v247
	v_cmp_ge_f32_e64 s[60:61], 0, v171
	v_cmp_ge_f32_e64 s[62:63], 0, v177
	v_cmp_ge_f32_e64 s[64:65], 0, v244
	v_cmp_ge_f32_e64 s[66:67], 0, v250
	v_add_u32_e32 v171, 1, v169
	v_add_u32_e32 v177, 1, v175
	v_add_u32_e32 v244, 1, v242
	v_add_u32_e32 v250, 1, v248
	v_cndmask_b32_e64 v170, v169, v170, s[60:61]
	v_cndmask_b32_e64 v176, v175, v176, s[62:63]
	v_cndmask_b32_e64 v243, v242, v243, s[64:65]
	v_cndmask_b32_e64 v249, v248, v249, s[66:67]
	v_fma_f32 v169, -v171, v169, v168
	v_fma_f32 v175, -v177, v175, v174
	v_fma_f32 v242, -v244, v242, v241
	v_fma_f32 v248, -v250, v248, v247
	v_cmp_lt_f32_e64 s[60:61], 0, v169
	v_cmp_lt_f32_e64 s[62:63], 0, v175
	v_cmp_lt_f32_e64 s[64:65], 0, v242
	v_cmp_lt_f32_e64 s[66:67], 0, v248
	v_cndmask_b32_e64 v169, v170, v171, s[60:61]
	v_cndmask_b32_e64 v175, v176, v177, s[62:63]
	v_cndmask_b32_e64 v242, v243, v244, s[64:65]
	v_cndmask_b32_e64 v248, v249, v250, s[66:67]
	v_mul_f32_e32 v170, 0x37800000, v169
	v_mul_f32_e32 v176, 0x37800000, v175
	v_mul_f32_e32 v243, 0x37800000, v242
	v_mul_f32_e32 v249, 0x37800000, v248
	v_cndmask_b32_e64 v169, v169, v170, s[52:53]
	v_cndmask_b32_e64 v175, v175, v176, s[54:55]
	v_cndmask_b32_e64 v242, v242, v243, s[56:57]
	v_cndmask_b32_e64 v248, v248, v249, s[58:59]
	v_cmp_class_f32_e64 s[60:61], v168, v8
	v_cmp_class_f32_e64 s[62:63], v174, v8
	v_cmp_class_f32_e64 s[64:65], v241, v8
	v_cmp_class_f32_e64 s[66:67], v247, v8
	v_cndmask_b32_e64 v168, v169, v168, s[60:61]
	v_cndmask_b32_e64 v174, v175, v174, s[62:63]
	v_cndmask_b32_e64 v241, v242, v241, s[64:65]
	v_cndmask_b32_e64 v247, v248, v247, s[66:67]
	v_div_scale_f32 v169, s[60:61], v168, v168, 1.0
	v_rcp_f32_e32 v170, v169
	s_nop 0
	v_fma_f32 v171, -v169, v170, 1.0
	v_fmac_f32_e32 v170, v171, v170
	v_div_scale_f32 v171, vcc, 1.0, v168, 1.0
	v_mul_f32_e32 v172, v171, v170
	v_fma_f32 v173, -v169, v172, v171
	v_fmac_f32_e32 v172, v173, v170
	v_fma_f32 v169, -v169, v172, v171
	v_div_fmas_f32 v169, v169, v170, v172
	v_div_fixup_f32 v168, v169, v168, 1.0
	v_div_scale_f32 v175, s[62:63], v174, v174, 1.0
	v_rcp_f32_e32 v176, v175
	s_nop 0
	v_fma_f32 v177, -v175, v176, 1.0
	v_fmac_f32_e32 v176, v177, v176
	v_div_scale_f32 v177, vcc, 1.0, v174, 1.0
	v_mul_f32_e32 v236, v177, v176
	v_fma_f32 v237, -v175, v236, v177
	v_fmac_f32_e32 v236, v237, v176
	v_fma_f32 v175, -v175, v236, v177
	v_div_fmas_f32 v175, v175, v176, v236
	v_div_fixup_f32 v174, v175, v174, 1.0
	v_div_scale_f32 v242, s[64:65], v241, v241, 1.0
	v_rcp_f32_e32 v243, v242
	s_nop 0
	v_fma_f32 v244, -v242, v243, 1.0
	v_fmac_f32_e32 v243, v244, v243
	v_div_scale_f32 v244, vcc, 1.0, v241, 1.0
	v_mul_f32_e32 v245, v244, v243
	v_fma_f32 v246, -v242, v245, v244
	v_fmac_f32_e32 v245, v246, v243
	v_fma_f32 v242, -v242, v245, v244
	v_div_fmas_f32 v242, v242, v243, v245
	v_div_fixup_f32 v241, v242, v241, 1.0
	v_div_scale_f32 v248, s[66:67], v247, v247, 1.0
	v_rcp_f32_e32 v249, v248
	s_nop 0
	v_fma_f32 v250, -v248, v249, 1.0
	v_fmac_f32_e32 v249, v250, v249
	v_div_scale_f32 v250, vcc, 1.0, v247, 1.0
	v_mul_f32_e32 v251, v250, v249
	v_fma_f32 v252, -v248, v251, v250
	v_fmac_f32_e32 v251, v252, v249
	v_fma_f32 v248, -v248, v251, v250
	v_div_fmas_f32 v248, v248, v249, v251
	v_div_fixup_f32 v247, v248, v247, 1.0
	v_mul_f32_e32 v100, v100, v168
	v_mul_f32_e32 v105, v105, v174
	v_mul_f32_e32 v110, v110, v241
	v_mul_f32_e32 v115, v115, v247
	v_lshlrev_b32_e32 v103, 16, v103
	v_lshlrev_b32_e32 v108, 16, v108
	v_lshlrev_b32_e32 v113, 16, v113
	v_lshlrev_b32_e32 v118, 16, v118
	v_fma_f32 v100, v6, v100, v7
	v_fma_f32 v105, v6, v105, v7
	v_fma_f32 v110, v6, v110, v7
	v_fma_f32 v115, v6, v115, v7
	v_fmac_f32_e32 v100, s73, v101
	v_fmac_f32_e32 v105, s26, v106
	v_fmac_f32_e32 v110, s27, v111
	v_fmac_f32_e32 v115, s32, v116
	v_mul_f32_e32 v100, v100, v103
	v_mul_f32_e32 v105, v105, v108
	v_mul_f32_e32 v110, v110, v113
	v_mul_f32_e32 v115, v115, v118
	v_cvt_pk_bf16_f32 v169, v100, v100
	v_cvt_pk_bf16_f32 v175, v105, v105
	v_cvt_pk_bf16_f32 v242, v110, v110
	v_cvt_pk_bf16_f32 v248, v115, v115
	global_store_short v2, v169, s[28:29]
	s_add_u32 s28, s28, 0x1000
	s_addc_u32 s29, s29, 0
	global_store_short v2, v175, s[28:29]
	s_add_u32 s28, s28, 0x1000
	s_addc_u32 s29, s29, 0
	global_store_short v2, v242, s[28:29]
	s_add_u32 s28, s28, 0x1000
	s_addc_u32 s29, s29, 0
	global_store_short v2, v248, s[28:29]
	s_add_u32 s28, s28, 0x1000
	s_addc_u32 s29, s29, 0
	s_waitcnt vmcnt(8)
	ds_write_b128 v12, v[120:123] offset:0
	ds_write_b128 v12, v[124:127] offset:1024
	ds_write_b128 v12, v[128:131] offset:16384
	ds_write_b128 v12, v[132:135] offset:17408
	ds_write_b128 v14, v[136:139]
	v_readlane_b32 s69, v159, 0
	v_readlane_b32 s70, v159, 1
	v_readlane_b32 s71, v159, 2
	v_readlane_b32 s72, v159, 3
	v_readlane_b32 s73, v159, 4
	v_readlane_b32 s26, v159, 5
	v_readlane_b32 s27, v159, 6
	v_readlane_b32 s32, v159, 7
	global_load_dwordx4 v[120:123], v11, s[6:7]
	global_load_dwordx4 v[124:127], v11, s[6:7] offset:1024
	global_load_dwordx4 v[128:131], v11, s[8:9]
	global_load_dwordx4 v[132:135], v11, s[8:9] offset:1024
	global_load_dwordx4 v[136:139], v11, s[10:11]
	global_load_dword v159, v158, s[12:13]
	s_add_u32 s6, s6, 0x10000
	s_addc_u32 s7, s7, 0
	s_add_u32 s8, s8, 0x10000
	s_addc_u32 s9, s9, 0
	s_add_u32 s10, s10, 0x8000
	s_addc_u32 s11, s11, 0
	s_add_u32 s12, s12, 0x400
	s_addc_u32 s13, s13, 0
	s_waitcnt lgkmcnt(0)
	s_barrier
; __device__ __forceinline__ float dpp_xor1(float x) { return __builtin_bit_cast(float, __builtin_amdgcn_update_dpp(0, __builtin_bit_cast(int, x), 0xB1, 0xF, 0xF, true)); }
; __device__ __forceinline__ float dpp_xor2(float x) { return __builtin_bit_cast(float, __builtin_amdgcn_update_dpp(0, __builtin_bit_cast(int, x), 0x4E, 0xF, 0xF, true)); }
; __device__ __forceinline__ float dpp_hmir(float x) { return __builtin_bit_cast(float, __builtin_amdgcn_update_dpp(0, __builtin_bit_cast(int, x), 0x141, 0xF, 0xF, true)); }
; __device__ __forceinline__ float dpp_mir(float x)  { return __builtin_bit_cast(float, __builtin_amdgcn_update_dpp(0, __builtin_bit_cast(int, x), 0x140, 0xF, 0xF, true)); }
; __device__ __forceinline__ float red16(float x) { x += dpp_xor1(x); x += dpp_xor2(x); x += dpp_hmir(x); x += dpp_mir(x); return x; }
; __device__ __forceinline__ float wsum(float x) {
;     x = red16(x); const int xi = __builtin_bit_cast(int, x);
;     const float r0 = __builtin_bit_cast(float, __builtin_amdgcn_readlane(xi, 0)), r1 = __builtin_bit_cast(float, __builtin_amdgcn_readlane(xi, 16));
;     const float r2 = __builtin_bit_cast(float, __builtin_amdgcn_readlane(xi, 32)), r3 = __builtin_bit_cast(float, __builtin_amdgcn_readlane(xi, 48));
;     return (r0 + r1) + (r2 + r3);
; __device__ __forceinline__ void rw_post(Frame& F) {
;     ...
;             for (int q = 0; q < 8; ++q) { const int row = rb0 + t0 + q;
;                 const float mean = wsum(y[q]) * (1.f / 64.f); const float dv = y[q] - mean; const float var = wsum(dv * dv) * (1.f / 64.f);
	ds_read_b32 v80, v154 offset:0
	ds_read_b32 v81, v154 offset:16384
	ds_read_u16 v83, v156 offset:0
	ds_read_b32 v85, v154 offset:2048
	ds_read_b32 v86, v154 offset:18432
	ds_read_u16 v88, v156 offset:1024
	ds_read_b32 v90, v154 offset:4096
	ds_read_b32 v91, v154 offset:20480
	ds_read_u16 v93, v156 offset:2048
	ds_read_b32 v95, v154 offset:6144
	ds_read_b32 v96, v154 offset:22528
	ds_read_u16 v98, v156 offset:3072
	ds_read_b32 v100, v154 offset:8192
	ds_read_b32 v101, v154 offset:24576
	ds_read_u16 v103, v156 offset:4096
	ds_read_b32 v105, v154 offset:10240
	ds_read_b32 v106, v154 offset:26624
	ds_read_u16 v108, v156 offset:5120
	ds_read_b32 v110, v154 offset:12288
	ds_read_b32 v111, v154 offset:28672
	ds_read_u16 v113, v156 offset:6144
	ds_read_b32 v115, v154 offset:14336
	ds_read_b32 v116, v154 offset:30720
	ds_read_u16 v118, v156 offset:7168
	s_waitcnt lgkmcnt(0)
	v_add_f32_e32 v80, v80, v48
	v_add_f32_e32 v85, v85, v49
	v_add_f32_e32 v90, v90, v50
	v_add_f32_e32 v95, v95, v51
	v_add_f32_dpp v168, v80, v80 quad_perm:[1,0,3,2] row_mask:0xf bank_mask:0xf bound_ctrl:1
	v_add_f32_dpp v174, v85, v85 quad_perm:[1,0,3,2] row_mask:0xf bank_mask:0xf bound_ctrl:1
	v_add_f32_dpp v241, v90, v90 quad_perm:[1,0,3,2] row_mask:0xf bank_mask:0xf bound_ctrl:1
	v_add_f32_dpp v247, v95, v95 quad_perm:[1,0,3,2] row_mask:0xf bank_mask:0xf bound_ctrl:1
	v_add_f32_dpp v168, v168, v168 quad_perm:[2,3,0,1] row_mask:0xf bank_mask:0xf bound_ctrl:1
	v_add_f32_dpp v174, v174, v174 quad_perm:[2,3,0,1] row_mask:0xf bank_mask:0xf bound_ctrl:1
	v_add_f32_dpp v241, v241, v241 quad_perm:[2,3,0,1] row_mask:0xf bank_mask:0xf bound_ctrl:1
	v_add_f32_dpp v247, v247, v247 quad_perm:[2,3,0,1] row_mask:0xf bank_mask:0xf bound_ctrl:1
	v_add_f32_dpp v168, v168, v168 row_half_mirror row_mask:0xf bank_mask:0xf bound_ctrl:1
	v_add_f32_dpp v174, v174, v174 row_half_mirror row_mask:0xf bank_mask:0xf bound_ctrl:1
	v_add_f32_dpp v241, v241, v241 row_half_mirror row_mask:0xf bank_mask:0xf bound_ctrl:1
	v_add_f32_dpp v247, v247, v247 row_half_mirror row_mask:0xf bank_mask:0xf bound_ctrl:1
	v_add_f32_dpp v168, v168, v168 row_mirror row_mask:0xf bank_mask:0xf bound_ctrl:1
	v_add_f32_dpp v174, v174, v174 row_mirror row_mask:0xf bank_mask:0xf bound_ctrl:1
	v_add_f32_dpp v241, v241, v241 row_mirror row_mask:0xf bank_mask:0xf bound_ctrl:1
	v_add_f32_dpp v247, v247, v247 row_mirror row_mask:0xf bank_mask:0xf bound_ctrl:1
	v_readlane_b32 s36, v168, 16
	v_readlane_b32 s40, v174, 16
	v_readlane_b32 s44, v241, 16
	v_readlane_b32 s48, v247, 16
	v_readlane_b32 s37, v168, 48
	v_readlane_b32 s41, v174, 48
	v_readlane_b32 s45, v241, 48
	v_readlane_b32 s49, v247, 48
	v_readlane_b32 s38, v168, 0
	v_readlane_b32 s42, v174, 0
	v_readlane_b32 s46, v241, 0
	v_readlane_b32 s50, v247, 0
	v_readlane_b32 s39, v168, 32
	v_readlane_b32 s43, v174, 32
	v_readlane_b32 s47, v241, 32
	v_readlane_b32 s51, v247, 32
	v_mov_b32_e32 v168, s36
	v_mov_b32_e32 v174, s40
	v_mov_b32_e32 v241, s44
	v_mov_b32_e32 v247, s48
	v_mov_b32_e32 v169, s37
	v_mov_b32_e32 v175, s41
	v_mov_b32_e32 v242, s45
	v_mov_b32_e32 v248, s49
	v_add_f32_e32 v168, s38, v168
	v_add_f32_e32 v174, s42, v174
	v_add_f32_e32 v241, s46, v241
	v_add_f32_e32 v247, s50, v247
	v_add_f32_e32 v169, s39, v169
	v_add_f32_e32 v175, s43, v175
	v_add_f32_e32 v242, s47, v242
	v_add_f32_e32 v248, s51, v248
	v_add_f32_e32 v168, v168, v169
	v_add_f32_e32 v174, v174, v175
	v_add_f32_e32 v241, v241, v242
	v_add_f32_e32 v247, v247, v248
	v_fmamk_f32 v80, v168, 0xbc800000, v80
	v_fmamk_f32 v85, v174, 0xbc800000, v85
	v_fmamk_f32 v90, v241, 0xbc800000, v90
	v_fmamk_f32 v95, v247, 0xbc800000, v95
	v_mul_f32_e32 v168, v80, v80
	v_mul_f32_e32 v174, v85, v85
	v_mul_f32_e32 v241, v90, v90
	v_mul_f32_e32 v247, v95, v95
	v_mov_b32_dpp v168, v168 quad_perm:[1,0,3,2] row_mask:0xf bank_mask:0xf bound_ctrl:1
	v_mov_b32_dpp v174, v174 quad_perm:[1,0,3,2] row_mask:0xf bank_mask:0xf bound_ctrl:1
	v_mov_b32_dpp v241, v241 quad_perm:[1,0,3,2] row_mask:0xf bank_mask:0xf bound_ctrl:1
	v_mov_b32_dpp v247, v247 quad_perm:[1,0,3,2] row_mask:0xf bank_mask:0xf bound_ctrl:1
	v_fmac_f32_e32 v168, v80, v80
	v_fmac_f32_e32 v174, v85, v85
	v_fmac_f32_e32 v241, v90, v90
	v_fmac_f32_e32 v247, v95, v95
	v_add_f32_dpp v168, v168, v168 quad_perm:[2,3,0,1] row_mask:0xf bank_mask:0xf bound_ctrl:1
	v_add_f32_dpp v174, v174, v174 quad_perm:[2,3,0,1] row_mask:0xf bank_mask:0xf bound_ctrl:1
	v_add_f32_dpp v241, v241, v241 quad_perm:[2,3,0,1] row_mask:0xf bank_mask:0xf bound_ctrl:1
	v_add_f32_dpp v247, v247, v247 quad_perm:[2,3,0,1] row_mask:0xf bank_mask:0xf bound_ctrl:1
	v_add_f32_dpp v168, v168, v168 row_half_mirror row_mask:0xf bank_mask:0xf bound_ctrl:1
	v_add_f32_dpp v174, v174, v174 row_half_mirror row_mask:0xf bank_mask:0xf bound_ctrl:1
	v_add_f32_dpp v241, v241, v241 row_half_mirror row_mask:0xf bank_mask:0xf bound_ctrl:1
	v_add_f32_dpp v247, v247, v247 row_half_mirror row_mask:0xf bank_mask:0xf bound_ctrl:1
	v_add_f32_dpp v168, v168, v168 row_mirror row_mask:0xf bank_mask:0xf bound_ctrl:1
	v_add_f32_dpp v174, v174, v174 row_mirror row_mask:0xf bank_mask:0xf bound_ctrl:1
	v_add_f32_dpp v241, v241, v241 row_mirror row_mask:0xf bank_mask:0xf bound_ctrl:1
	v_add_f32_dpp v247, v247, v247 row_mirror row_mask:0xf bank_mask:0xf bound_ctrl:1
	v_readlane_b32 s36, v168, 16
	v_readlane_b32 s40, v174, 16
	v_readlane_b32 s44, v241, 16
	v_readlane_b32 s48, v247, 16
	v_readlane_b32 s37, v168, 48
	v_readlane_b32 s41, v174, 48
	v_readlane_b32 s45, v241, 48
	v_readlane_b32 s49, v247, 48
	v_readlane_b32 s38, v168, 0
	v_readlane_b32 s42, v174, 0
	v_readlane_b32 s46, v241, 0
	v_readlane_b32 s50, v247, 0
	v_readlane_b32 s39, v168, 32
; __device__ __forceinline__ float bf2f(bf16 x) { return __uint_as_float(((unsigned)x) << 16); }
; __device__ __forceinline__ unsigned f2bf(float f) { return cvt_pk_bf16(f, 0.f) & 0xffffu; }
; __device__ __forceinline__ void rw_post(Frame& F) {
;     ...
;                 const float mean = wsum(y[q]) * (1.f / 64.f); const float dv = y[q] - mean; const float var = wsum(dv * dv) * (1.f / 64.f);
;                 const float yn = dv * (1.f / sqrtf(var + 64e-5f)) * g_ + b_;
;                 OB[(size_t)row * DH + col] = (bf16)f2bf((yn + rk[q] * vv[q]) * bf2f(gg[q])); }
	v_readlane_b32 s43, v174, 32
	v_readlane_b32 s47, v241, 32
	v_readlane_b32 s51, v247, 32
	v_mov_b32_e32 v168, s36
	v_mov_b32_e32 v174, s40
	v_mov_b32_e32 v241, s44
	v_mov_b32_e32 v247, s48
	v_mov_b32_e32 v169, s37
	v_mov_b32_e32 v175, s41
	v_mov_b32_e32 v242, s45
	v_mov_b32_e32 v248, s49
	v_add_f32_e32 v168, s38, v168
	v_add_f32_e32 v174, s42, v174
	v_add_f32_e32 v241, s46, v241
	v_add_f32_e32 v247, s50, v247
	v_add_f32_e32 v169, s39, v169
	v_add_f32_e32 v175, s43, v175
	v_add_f32_e32 v242, s47, v242
	v_add_f32_e32 v248, s51, v248
	v_add_f32_e32 v168, v168, v169
	v_add_f32_e32 v174, v174, v175
	v_add_f32_e32 v241, v241, v242
	v_add_f32_e32 v247, v247, v248
	v_fmamk_f32 v168, v168, 0x3c800000, v9
	v_fmamk_f32 v174, v174, 0x3c800000, v9
	v_fmamk_f32 v241, v241, 0x3c800000, v9
	v_fmamk_f32 v247, v247, 0x3c800000, v9
	v_mul_f32_e32 v169, 0x4f800000, v168
	v_mul_f32_e32 v175, 0x4f800000, v174
	v_mul_f32_e32 v242, 0x4f800000, v241
	v_mul_f32_e32 v248, 0x4f800000, v247
	v_cmp_gt_f32_e64 s[52:53], s68, v168
	v_cmp_gt_f32_e64 s[54:55], s68, v174
	v_cmp_gt_f32_e64 s[56:57], s68, v241
	v_cmp_gt_f32_e64 s[58:59], s68, v247
	v_mov_b32_e32 v170, v168
	v_mov_b32_e32 v176, v174
	v_mov_b32_e32 v243, v241
	v_mov_b32_e32 v249, v247
	v_cndmask_b32_e64 v168, v170, v169, s[52:53]
	v_cndmask_b32_e64 v174, v176, v175, s[54:55]
	v_cndmask_b32_e64 v241, v243, v242, s[56:57]
	v_cndmask_b32_e64 v247, v249, v248, s[58:59]
	v_sqrt_f32_e32 v169, v168
	v_sqrt_f32_e32 v175, v174
	v_sqrt_f32_e32 v242, v241
	v_sqrt_f32_e32 v248, v247
	v_add_u32_e32 v170, -1, v169
	v_add_u32_e32 v176, -1, v175
	v_add_u32_e32 v243, -1, v242
	v_add_u32_e32 v249, -1, v248
	v_fma_f32 v171, -v170, v169, v168
	v_fma_f32 v177, -v176, v175, v174
	v_fma_f32 v244, -v243, v242, v241
	v_fma_f32 v250, -v249, v248, v247
	v_cmp_ge_f32_e64 s[60:61], 0, v171
	v_cmp_ge_f32_e64 s[62:63], 0, v177
	v_cmp_ge_f32_e64 s[64:65], 0, v244
	v_cmp_ge_f32_e64 s[66:67], 0, v250
	v_add_u32_e32 v171, 1, v169
	v_add_u32_e32 v177, 1, v175
	v_add_u32_e32 v244, 1, v242
	v_add_u32_e32 v250, 1, v248
	v_cndmask_b32_e64 v170, v169, v170, s[60:61]
	v_cndmask_b32_e64 v176, v175, v176, s[62:63]
	v_cndmask_b32_e64 v243, v242, v243, s[64:65]
	v_cndmask_b32_e64 v249, v248, v249, s[66:67]
	v_fma_f32 v169, -v171, v169, v168
	v_fma_f32 v175, -v177, v175, v174
	v_fma_f32 v242, -v244, v242, v241
	v_fma_f32 v248, -v250, v248, v247
	v_cmp_lt_f32_e64 s[60:61], 0, v169
	v_cmp_lt_f32_e64 s[62:63], 0, v175
	v_cmp_lt_f32_e64 s[64:65], 0, v242
	v_cmp_lt_f32_e64 s[66:67], 0, v248
	v_cndmask_b32_e64 v169, v170, v171, s[60:61]
	v_cndmask_b32_e64 v175, v176, v177, s[62:63]
	v_cndmask_b32_e64 v242, v243, v244, s[64:65]
	v_cndmask_b32_e64 v248, v249, v250, s[66:67]
	v_mul_f32_e32 v170, 0x37800000, v169
	v_mul_f32_e32 v176, 0x37800000, v175
	v_mul_f32_e32 v243, 0x37800000, v242
	v_mul_f32_e32 v249, 0x37800000, v248
	v_cndmask_b32_e64 v169, v169, v170, s[52:53]
	v_cndmask_b32_e64 v175, v175, v176, s[54:55]
	v_cndmask_b32_e64 v242, v242, v243, s[56:57]
	v_cndmask_b32_e64 v248, v248, v249, s[58:59]
	v_cmp_class_f32_e64 s[60:61], v168, v8
	v_cmp_class_f32_e64 s[62:63], v174, v8
	v_cmp_class_f32_e64 s[64:65], v241, v8
	v_cmp_class_f32_e64 s[66:67], v247, v8
	v_cndmask_b32_e64 v168, v169, v168, s[60:61]
	v_cndmask_b32_e64 v174, v175, v174, s[62:63]
	v_cndmask_b32_e64 v241, v242, v241, s[64:65]
	v_cndmask_b32_e64 v247, v248, v247, s[66:67]
	v_div_scale_f32 v169, s[60:61], v168, v168, 1.0
	v_rcp_f32_e32 v170, v169
	s_nop 0
	v_fma_f32 v171, -v169, v170, 1.0
	v_fmac_f32_e32 v170, v171, v170
	v_div_scale_f32 v171, vcc, 1.0, v168, 1.0
	v_mul_f32_e32 v172, v171, v170
	v_fma_f32 v173, -v169, v172, v171
	v_fmac_f32_e32 v172, v173, v170
	v_fma_f32 v169, -v169, v172, v171
	v_div_fmas_f32 v169, v169, v170, v172
	v_div_fixup_f32 v168, v169, v168, 1.0
	v_div_scale_f32 v175, s[62:63], v174, v174, 1.0
	v_rcp_f32_e32 v176, v175
	s_nop 0
	v_fma_f32 v177, -v175, v176, 1.0
	v_fmac_f32_e32 v176, v177, v176
	v_div_scale_f32 v177, vcc, 1.0, v174, 1.0
	v_mul_f32_e32 v236, v177, v176
	v_fma_f32 v237, -v175, v236, v177
	v_fmac_f32_e32 v236, v237, v176
	v_fma_f32 v175, -v175, v236, v177
	v_div_fmas_f32 v175, v175, v176, v236
	v_div_fixup_f32 v174, v175, v174, 1.0
	v_div_scale_f32 v242, s[64:65], v241, v241, 1.0
	v_rcp_f32_e32 v243, v242
	s_nop 0
	v_fma_f32 v244, -v242, v243, 1.0
	v_fmac_f32_e32 v243, v244, v243
	v_div_scale_f32 v244, vcc, 1.0, v241, 1.0
	v_mul_f32_e32 v245, v244, v243
	v_fma_f32 v246, -v242, v245, v244
	v_fmac_f32_e32 v245, v246, v243
	v_fma_f32 v242, -v242, v245, v244
	v_div_fmas_f32 v242, v242, v243, v245
	v_div_fixup_f32 v241, v242, v241, 1.0
	v_div_scale_f32 v248, s[66:67], v247, v247, 1.0
	v_rcp_f32_e32 v249, v248
	s_nop 0
	v_fma_f32 v250, -v248, v249, 1.0
	v_fmac_f32_e32 v249, v250, v249
	v_div_scale_f32 v250, vcc, 1.0, v247, 1.0
	v_mul_f32_e32 v251, v250, v249
	v_fma_f32 v252, -v248, v251, v250
	v_fmac_f32_e32 v251, v252, v249
	v_fma_f32 v248, -v248, v251, v250
	v_div_fmas_f32 v248, v248, v249, v251
	v_div_fixup_f32 v247, v248, v247, 1.0
	v_mul_f32_e32 v80, v80, v168
	v_mul_f32_e32 v85, v85, v174
	v_mul_f32_e32 v90, v90, v241
	v_mul_f32_e32 v95, v95, v247
	v_lshlrev_b32_e32 v83, 16, v83
	v_lshlrev_b32_e32 v88, 16, v88
	v_lshlrev_b32_e32 v93, 16, v93
	v_lshlrev_b32_e32 v98, 16, v98
	v_fma_f32 v80, v6, v80, v7
	v_fma_f32 v85, v6, v85, v7
	v_fma_f32 v90, v6, v90, v7
	v_fma_f32 v95, v6, v95, v7
	v_fmac_f32_e32 v80, s69, v81
	v_fmac_f32_e32 v85, s70, v86
	v_fmac_f32_e32 v90, s71, v91
	v_fmac_f32_e32 v95, s72, v96
	v_mul_f32_e32 v80, v80, v83
	v_mul_f32_e32 v85, v85, v88
	v_mul_f32_e32 v90, v90, v93
	v_mul_f32_e32 v95, v95, v98
	v_cvt_pk_bf16_f32 v169, v80, v80
; __device__ __forceinline__ float bf2f(bf16 x) { return __uint_as_float(((unsigned)x) << 16); }
; __device__ __forceinline__ unsigned f2bf(float f) { return cvt_pk_bf16(f, 0.f) & 0xffffu; }
; __device__ __forceinline__ float dpp_xor1(float x) { return __builtin_bit_cast(float, __builtin_amdgcn_update_dpp(0, __builtin_bit_cast(int, x), 0xB1, 0xF, 0xF, true)); }
; __device__ __forceinline__ float dpp_xor2(float x) { return __builtin_bit_cast(float, __builtin_amdgcn_update_dpp(0, __builtin_bit_cast(int, x), 0x4E, 0xF, 0xF, true)); }
; __device__ __forceinline__ float dpp_hmir(float x) { return __builtin_bit_cast(float, __builtin_amdgcn_update_dpp(0, __builtin_bit_cast(int, x), 0x141, 0xF, 0xF, true)); }
; __device__ __forceinline__ float dpp_mir(float x)  { return __builtin_bit_cast(float, __builtin_amdgcn_update_dpp(0, __builtin_bit_cast(int, x), 0x140, 0xF, 0xF, true)); }
; __device__ __forceinline__ float red16(float x) { x += dpp_xor1(x); x += dpp_xor2(x); x += dpp_hmir(x); x += dpp_mir(x); return x; }
; __device__ __forceinline__ float wsum(float x) {
;     x = red16(x); const int xi = __builtin_bit_cast(int, x);
;     const float r0 = __builtin_bit_cast(float, __builtin_amdgcn_readlane(xi, 0)), r1 = __builtin_bit_cast(float, __builtin_amdgcn_readlane(xi, 16));
;     const float r2 = __builtin_bit_cast(float, __builtin_amdgcn_readlane(xi, 32)), r3 = __builtin_bit_cast(float, __builtin_amdgcn_readlane(xi, 48));
;     return (r0 + r1) + (r2 + r3);
; __device__ __forceinline__ void rw_post(Frame& F) {
;     ...
;             for (int q = 0; q < 8; ++q) { const int row = rb0 + t0 + q;
;                 const float mean = wsum(y[q]) * (1.f / 64.f); const float dv = y[q] - mean; const float var = wsum(dv * dv) * (1.f / 64.f);
;                 const float yn = dv * (1.f / sqrtf(var + 64e-5f)) * g_ + b_;
;                 OB[(size_t)row * DH + col] = (bf16)f2bf((yn + rk[q] * vv[q]) * bf2f(gg[q])); }
	v_cvt_pk_bf16_f32 v175, v85, v85
	v_cvt_pk_bf16_f32 v242, v90, v90
	v_cvt_pk_bf16_f32 v248, v95, v95
	global_store_short v2, v169, s[28:29]
	s_add_u32 s28, s28, 0x1000
	s_addc_u32 s29, s29, 0
	global_store_short v2, v175, s[28:29]
	s_add_u32 s28, s28, 0x1000
	s_addc_u32 s29, s29, 0
	global_store_short v2, v242, s[28:29]
	s_add_u32 s28, s28, 0x1000
	s_addc_u32 s29, s29, 0
	global_store_short v2, v248, s[28:29]
	s_add_u32 s28, s28, 0x1000
	s_addc_u32 s29, s29, 0
	v_add_f32_e32 v100, v100, v64
	v_add_f32_e32 v105, v105, v65
	v_add_f32_e32 v110, v110, v66
	v_add_f32_e32 v115, v115, v67
	v_add_f32_dpp v168, v100, v100 quad_perm:[1,0,3,2] row_mask:0xf bank_mask:0xf bound_ctrl:1
	v_add_f32_dpp v174, v105, v105 quad_perm:[1,0,3,2] row_mask:0xf bank_mask:0xf bound_ctrl:1
	v_add_f32_dpp v241, v110, v110 quad_perm:[1,0,3,2] row_mask:0xf bank_mask:0xf bound_ctrl:1
	v_add_f32_dpp v247, v115, v115 quad_perm:[1,0,3,2] row_mask:0xf bank_mask:0xf bound_ctrl:1
	v_add_f32_dpp v168, v168, v168 quad_perm:[2,3,0,1] row_mask:0xf bank_mask:0xf bound_ctrl:1
	v_add_f32_dpp v174, v174, v174 quad_perm:[2,3,0,1] row_mask:0xf bank_mask:0xf bound_ctrl:1
	v_add_f32_dpp v241, v241, v241 quad_perm:[2,3,0,1] row_mask:0xf bank_mask:0xf bound_ctrl:1
	v_add_f32_dpp v247, v247, v247 quad_perm:[2,3,0,1] row_mask:0xf bank_mask:0xf bound_ctrl:1
	v_add_f32_dpp v168, v168, v168 row_half_mirror row_mask:0xf bank_mask:0xf bound_ctrl:1
	v_add_f32_dpp v174, v174, v174 row_half_mirror row_mask:0xf bank_mask:0xf bound_ctrl:1
	v_add_f32_dpp v241, v241, v241 row_half_mirror row_mask:0xf bank_mask:0xf bound_ctrl:1
	v_add_f32_dpp v247, v247, v247 row_half_mirror row_mask:0xf bank_mask:0xf bound_ctrl:1
	v_add_f32_dpp v168, v168, v168 row_mirror row_mask:0xf bank_mask:0xf bound_ctrl:1
	v_add_f32_dpp v174, v174, v174 row_mirror row_mask:0xf bank_mask:0xf bound_ctrl:1
	v_add_f32_dpp v241, v241, v241 row_mirror row_mask:0xf bank_mask:0xf bound_ctrl:1
	v_add_f32_dpp v247, v247, v247 row_mirror row_mask:0xf bank_mask:0xf bound_ctrl:1
	v_readlane_b32 s36, v168, 16
	v_readlane_b32 s40, v174, 16
	v_readlane_b32 s44, v241, 16
	v_readlane_b32 s48, v247, 16
	v_readlane_b32 s37, v168, 48
	v_readlane_b32 s41, v174, 48
	v_readlane_b32 s45, v241, 48
	v_readlane_b32 s49, v247, 48
	v_readlane_b32 s38, v168, 0
	v_readlane_b32 s42, v174, 0
	v_readlane_b32 s46, v241, 0
	v_readlane_b32 s50, v247, 0
	v_readlane_b32 s39, v168, 32
	v_readlane_b32 s43, v174, 32
	v_readlane_b32 s47, v241, 32
	v_readlane_b32 s51, v247, 32
	v_mov_b32_e32 v168, s36
	v_mov_b32_e32 v174, s40
	v_mov_b32_e32 v241, s44
	v_mov_b32_e32 v247, s48
	v_mov_b32_e32 v169, s37
	v_mov_b32_e32 v175, s41
	v_mov_b32_e32 v242, s45
	v_mov_b32_e32 v248, s49
	v_add_f32_e32 v168, s38, v168
	v_add_f32_e32 v174, s42, v174
	v_add_f32_e32 v241, s46, v241
	v_add_f32_e32 v247, s50, v247
	v_add_f32_e32 v169, s39, v169
	v_add_f32_e32 v175, s43, v175
	v_add_f32_e32 v242, s47, v242
	v_add_f32_e32 v248, s51, v248
	v_add_f32_e32 v168, v168, v169
	v_add_f32_e32 v174, v174, v175
	v_add_f32_e32 v241, v241, v242
	v_add_f32_e32 v247, v247, v248
	v_fmamk_f32 v100, v168, 0xbc800000, v100
	v_fmamk_f32 v105, v174, 0xbc800000, v105
	v_fmamk_f32 v110, v241, 0xbc800000, v110
	v_fmamk_f32 v115, v247, 0xbc800000, v115
	v_mul_f32_e32 v168, v100, v100
	v_mul_f32_e32 v174, v105, v105
	v_mul_f32_e32 v241, v110, v110
	v_mul_f32_e32 v247, v115, v115
	v_mov_b32_dpp v168, v168 quad_perm:[1,0,3,2] row_mask:0xf bank_mask:0xf bound_ctrl:1
	v_mov_b32_dpp v174, v174 quad_perm:[1,0,3,2] row_mask:0xf bank_mask:0xf bound_ctrl:1
	v_mov_b32_dpp v241, v241 quad_perm:[1,0,3,2] row_mask:0xf bank_mask:0xf bound_ctrl:1
	v_mov_b32_dpp v247, v247 quad_perm:[1,0,3,2] row_mask:0xf bank_mask:0xf bound_ctrl:1
	v_fmac_f32_e32 v168, v100, v100
	v_fmac_f32_e32 v174, v105, v105
	v_fmac_f32_e32 v241, v110, v110
	v_fmac_f32_e32 v247, v115, v115
	v_add_f32_dpp v168, v168, v168 quad_perm:[2,3,0,1] row_mask:0xf bank_mask:0xf bound_ctrl:1
	v_add_f32_dpp v174, v174, v174 quad_perm:[2,3,0,1] row_mask:0xf bank_mask:0xf bound_ctrl:1
	v_add_f32_dpp v241, v241, v241 quad_perm:[2,3,0,1] row_mask:0xf bank_mask:0xf bound_ctrl:1
	v_add_f32_dpp v247, v247, v247 quad_perm:[2,3,0,1] row_mask:0xf bank_mask:0xf bound_ctrl:1
	v_add_f32_dpp v168, v168, v168 row_half_mirror row_mask:0xf bank_mask:0xf bound_ctrl:1
	v_add_f32_dpp v174, v174, v174 row_half_mirror row_mask:0xf bank_mask:0xf bound_ctrl:1
	v_add_f32_dpp v241, v241, v241 row_half_mirror row_mask:0xf bank_mask:0xf bound_ctrl:1
	v_add_f32_dpp v247, v247, v247 row_half_mirror row_mask:0xf bank_mask:0xf bound_ctrl:1
	v_add_f32_dpp v168, v168, v168 row_mirror row_mask:0xf bank_mask:0xf bound_ctrl:1
	v_add_f32_dpp v174, v174, v174 row_mirror row_mask:0xf bank_mask:0xf bound_ctrl:1
	v_add_f32_dpp v241, v241, v241 row_mirror row_mask:0xf bank_mask:0xf bound_ctrl:1
	v_add_f32_dpp v247, v247, v247 row_mirror row_mask:0xf bank_mask:0xf bound_ctrl:1
	v_readlane_b32 s36, v168, 16
	v_readlane_b32 s40, v174, 16
	v_readlane_b32 s44, v241, 16
	v_readlane_b32 s48, v247, 16
	v_readlane_b32 s37, v168, 48
	v_readlane_b32 s41, v174, 48
	v_readlane_b32 s45, v241, 48
	v_readlane_b32 s49, v247, 48
	v_readlane_b32 s38, v168, 0
	v_readlane_b32 s42, v174, 0
	v_readlane_b32 s46, v241, 0
	v_readlane_b32 s50, v247, 0
	v_readlane_b32 s39, v168, 32
	v_readlane_b32 s43, v174, 32
	v_readlane_b32 s47, v241, 32
	v_readlane_b32 s51, v247, 32
	v_mov_b32_e32 v168, s36
	v_mov_b32_e32 v174, s40
	v_mov_b32_e32 v241, s44
	v_mov_b32_e32 v247, s48
	v_mov_b32_e32 v169, s37
	v_mov_b32_e32 v175, s41
	v_mov_b32_e32 v242, s45
	v_mov_b32_e32 v248, s49
	v_add_f32_e32 v168, s38, v168
	v_add_f32_e32 v174, s42, v174
	v_add_f32_e32 v241, s46, v241
; __device__ __forceinline__ float bf2f(bf16 x) { return __uint_as_float(((unsigned)x) << 16); }
; __device__ __forceinline__ unsigned f2bf(float f) { return cvt_pk_bf16(f, 0.f) & 0xffffu; }
; #define POST_LD(Y_, V_, G_, R_, C_, t) do { _Pragma("unroll") for (int q = 0; q < 8; ++q) { const size_t o_ = (size_t)((t) + q) * DH; Y_[q] = yp[o_]; V_[q] = vp[o_]; G_[q] = gp[o_]; R_[q] = rp[((t) + q) * 32]; C_[q] = cp[o_]; } } while (0)
; __device__ __forceinline__ void rw_post(Frame& F) {
;     ...
;         POST_LD(y, vv, gg, rk, cc, 0);
;         for (int t0 = 0; t0 < 64; t0 += 8) {
;             float ny[8], nv[8], nr[8], nc[8]; bf16 ng[8];
;             const int tn = t0 + 8 < 64 ? t0 + 8 : t0;
;             POST_LD(ny, nv, ng, nr, nc, tn);
;     ...
;             for (int q = 0; q < 8; ++q) { const int row = rb0 + t0 + q;
;                 const float mean = wsum(y[q]) * (1.f / 64.f); const float dv = y[q] - mean; const float var = wsum(dv * dv) * (1.f / 64.f);
;                 const float yn = dv * (1.f / sqrtf(var + 64e-5f)) * g_ + b_;
;                 OB[(size_t)row * DH + col] = (bf16)f2bf((yn + rk[q] * vv[q]) * bf2f(gg[q])); }
	v_add_f32_e32 v247, s50, v247
	v_add_f32_e32 v169, s39, v169
	v_add_f32_e32 v175, s43, v175
	v_add_f32_e32 v242, s47, v242
	v_add_f32_e32 v248, s51, v248
	v_add_f32_e32 v168, v168, v169
	v_add_f32_e32 v174, v174, v175
	v_add_f32_e32 v241, v241, v242
	v_add_f32_e32 v247, v247, v248
	v_fmamk_f32 v168, v168, 0x3c800000, v9
	v_fmamk_f32 v174, v174, 0x3c800000, v9
	v_fmamk_f32 v241, v241, 0x3c800000, v9
	v_fmamk_f32 v247, v247, 0x3c800000, v9
	v_mul_f32_e32 v169, 0x4f800000, v168
	v_mul_f32_e32 v175, 0x4f800000, v174
	v_mul_f32_e32 v242, 0x4f800000, v241
	v_mul_f32_e32 v248, 0x4f800000, v247
	v_cmp_gt_f32_e64 s[52:53], s68, v168
	v_cmp_gt_f32_e64 s[54:55], s68, v174
	v_cmp_gt_f32_e64 s[56:57], s68, v241
	v_cmp_gt_f32_e64 s[58:59], s68, v247
	v_mov_b32_e32 v170, v168
	v_mov_b32_e32 v176, v174
	v_mov_b32_e32 v243, v241
	v_mov_b32_e32 v249, v247
	v_cndmask_b32_e64 v168, v170, v169, s[52:53]
	v_cndmask_b32_e64 v174, v176, v175, s[54:55]
	v_cndmask_b32_e64 v241, v243, v242, s[56:57]
	v_cndmask_b32_e64 v247, v249, v248, s[58:59]
	v_sqrt_f32_e32 v169, v168
	v_sqrt_f32_e32 v175, v174
	v_sqrt_f32_e32 v242, v241
	v_sqrt_f32_e32 v248, v247
	v_add_u32_e32 v170, -1, v169
	v_add_u32_e32 v176, -1, v175
	v_add_u32_e32 v243, -1, v242
	v_add_u32_e32 v249, -1, v248
	v_fma_f32 v171, -v170, v169, v168
	v_fma_f32 v177, -v176, v175, v174
	v_fma_f32 v244, -v243, v242, v241
	v_fma_f32 v250, -v249, v248, v247
	v_cmp_ge_f32_e64 s[60:61], 0, v171
	v_cmp_ge_f32_e64 s[62:63], 0, v177
	v_cmp_ge_f32_e64 s[64:65], 0, v244
	v_cmp_ge_f32_e64 s[66:67], 0, v250
	v_add_u32_e32 v171, 1, v169
	v_add_u32_e32 v177, 1, v175
	v_add_u32_e32 v244, 1, v242
	v_add_u32_e32 v250, 1, v248
	v_cndmask_b32_e64 v170, v169, v170, s[60:61]
	v_cndmask_b32_e64 v176, v175, v176, s[62:63]
	v_cndmask_b32_e64 v243, v242, v243, s[64:65]
	v_cndmask_b32_e64 v249, v248, v249, s[66:67]
	v_fma_f32 v169, -v171, v169, v168
	v_fma_f32 v175, -v177, v175, v174
	v_fma_f32 v242, -v244, v242, v241
	v_fma_f32 v248, -v250, v248, v247
	v_cmp_lt_f32_e64 s[60:61], 0, v169
	v_cmp_lt_f32_e64 s[62:63], 0, v175
	v_cmp_lt_f32_e64 s[64:65], 0, v242
	v_cmp_lt_f32_e64 s[66:67], 0, v248
	v_cndmask_b32_e64 v169, v170, v171, s[60:61]
	v_cndmask_b32_e64 v175, v176, v177, s[62:63]
	v_cndmask_b32_e64 v242, v243, v244, s[64:65]
	v_cndmask_b32_e64 v248, v249, v250, s[66:67]
	v_mul_f32_e32 v170, 0x37800000, v169
	v_mul_f32_e32 v176, 0x37800000, v175
	v_mul_f32_e32 v243, 0x37800000, v242
	v_mul_f32_e32 v249, 0x37800000, v248
	v_cndmask_b32_e64 v169, v169, v170, s[52:53]
	v_cndmask_b32_e64 v175, v175, v176, s[54:55]
	v_cndmask_b32_e64 v242, v242, v243, s[56:57]
	v_cndmask_b32_e64 v248, v248, v249, s[58:59]
	v_cmp_class_f32_e64 s[60:61], v168, v8
	v_cmp_class_f32_e64 s[62:63], v174, v8
	v_cmp_class_f32_e64 s[64:65], v241, v8
	v_cmp_class_f32_e64 s[66:67], v247, v8
	v_cndmask_b32_e64 v168, v169, v168, s[60:61]
	v_cndmask_b32_e64 v174, v175, v174, s[62:63]
	v_cndmask_b32_e64 v241, v242, v241, s[64:65]
	v_cndmask_b32_e64 v247, v248, v247, s[66:67]
	v_div_scale_f32 v169, s[60:61], v168, v168, 1.0
	v_rcp_f32_e32 v170, v169
	s_nop 0
	v_fma_f32 v171, -v169, v170, 1.0
	v_fmac_f32_e32 v170, v171, v170
	v_div_scale_f32 v171, vcc, 1.0, v168, 1.0
	v_mul_f32_e32 v172, v171, v170
	v_fma_f32 v173, -v169, v172, v171
	v_fmac_f32_e32 v172, v173, v170
	v_fma_f32 v169, -v169, v172, v171
	v_div_fmas_f32 v169, v169, v170, v172
	v_div_fixup_f32 v168, v169, v168, 1.0
	v_div_scale_f32 v175, s[62:63], v174, v174, 1.0
	v_rcp_f32_e32 v176, v175
	s_nop 0
	v_fma_f32 v177, -v175, v176, 1.0
	v_fmac_f32_e32 v176, v177, v176
	v_div_scale_f32 v177, vcc, 1.0, v174, 1.0
	v_mul_f32_e32 v236, v177, v176
	v_fma_f32 v237, -v175, v236, v177
	v_fmac_f32_e32 v236, v237, v176
	v_fma_f32 v175, -v175, v236, v177
	v_div_fmas_f32 v175, v175, v176, v236
	v_div_fixup_f32 v174, v175, v174, 1.0
	v_div_scale_f32 v242, s[64:65], v241, v241, 1.0
	v_rcp_f32_e32 v243, v242
	s_nop 0
	v_fma_f32 v244, -v242, v243, 1.0
	v_fmac_f32_e32 v243, v244, v243
	v_div_scale_f32 v244, vcc, 1.0, v241, 1.0
	v_mul_f32_e32 v245, v244, v243
	v_fma_f32 v246, -v242, v245, v244
	v_fmac_f32_e32 v245, v246, v243
	v_fma_f32 v242, -v242, v245, v244
	v_div_fmas_f32 v242, v242, v243, v245
	v_div_fixup_f32 v241, v242, v241, 1.0
	v_div_scale_f32 v248, s[66:67], v247, v247, 1.0
	v_rcp_f32_e32 v249, v248
	s_nop 0
	v_fma_f32 v250, -v248, v249, 1.0
	v_fmac_f32_e32 v249, v250, v249
	v_div_scale_f32 v250, vcc, 1.0, v247, 1.0
	v_mul_f32_e32 v251, v250, v249
	v_fma_f32 v252, -v248, v251, v250
	v_fmac_f32_e32 v251, v252, v249
	v_fma_f32 v248, -v248, v251, v250
	v_div_fmas_f32 v248, v248, v249, v251
	v_div_fixup_f32 v247, v248, v247, 1.0
	v_mul_f32_e32 v100, v100, v168
	v_mul_f32_e32 v105, v105, v174
	v_mul_f32_e32 v110, v110, v241
	v_mul_f32_e32 v115, v115, v247
	v_lshlrev_b32_e32 v103, 16, v103
	v_lshlrev_b32_e32 v108, 16, v108
	v_lshlrev_b32_e32 v113, 16, v113
	v_lshlrev_b32_e32 v118, 16, v118
	v_fma_f32 v100, v6, v100, v7
	v_fma_f32 v105, v6, v105, v7
	v_fma_f32 v110, v6, v110, v7
	v_fma_f32 v115, v6, v115, v7
	v_fmac_f32_e32 v100, s73, v101
	v_fmac_f32_e32 v105, s26, v106
	v_fmac_f32_e32 v110, s27, v111
	v_fmac_f32_e32 v115, s32, v116
	v_mul_f32_e32 v100, v100, v103
	v_mul_f32_e32 v105, v105, v108
	v_mul_f32_e32 v110, v110, v113
	v_mul_f32_e32 v115, v115, v118
	v_cvt_pk_bf16_f32 v169, v100, v100
	v_cvt_pk_bf16_f32 v175, v105, v105
	v_cvt_pk_bf16_f32 v242, v110, v110
	v_cvt_pk_bf16_f32 v248, v115, v115
	global_store_short v2, v169, s[28:29]
	s_add_u32 s28, s28, 0x1000
	s_addc_u32 s29, s29, 0
	global_store_short v2, v175, s[28:29]
	s_add_u32 s28, s28, 0x1000
	s_addc_u32 s29, s29, 0
	global_store_short v2, v242, s[28:29]
	s_add_u32 s28, s28, 0x1000
	s_addc_u32 s29, s29, 0
	global_store_short v2, v248, s[28:29]
	s_add_u32 s28, s28, 0x1000
	s_addc_u32 s29, s29, 0
	s_waitcnt vmcnt(8)
	ds_write_b128 v13, v[120:123] offset:0
	ds_write_b128 v13, v[124:127] offset:1024
	ds_write_b128 v13, v[128:131] offset:16384
	ds_write_b128 v13, v[132:135] offset:17408
	ds_write_b128 v15, v[136:139]
	v_readlane_b32 s69, v159, 0
	v_readlane_b32 s70, v159, 1
	v_readlane_b32 s71, v159, 2
	v_readlane_b32 s72, v159, 3
	v_readlane_b32 s73, v159, 4
	v_readlane_b32 s26, v159, 5
	v_readlane_b32 s27, v159, 6
	v_readlane_b32 s32, v159, 7
	global_load_dwordx4 v[120:123], v11, s[6:7]
	global_load_dwordx4 v[124:127], v11, s[6:7] offset:1024
	global_load_dwordx4 v[128:131], v11, s[8:9]
	global_load_dwordx4 v[132:135], v11, s[8:9] offset:1024
	global_load_dwordx4 v[136:139], v11, s[10:11]
	global_load_dword v159, v158, s[12:13]
	s_add_u32 s6, s6, 0x10000
	s_addc_u32 s7, s7, 0
	s_add_u32 s8, s8, 0x10000
	s_addc_u32 s9, s9, 0
	s_add_u32 s10, s10, 0x8000
	s_addc_u32 s11, s11, 0
	s_add_u32 s12, s12, 0x400
	s_addc_u32 s13, s13, 0
	s_waitcnt lgkmcnt(0)
	s_barrier
; __device__ __forceinline__ float dpp_xor1(float x) { return __builtin_bit_cast(float, __builtin_amdgcn_update_dpp(0, __builtin_bit_cast(int, x), 0xB1, 0xF, 0xF, true)); }
; __device__ __forceinline__ float dpp_xor2(float x) { return __builtin_bit_cast(float, __builtin_amdgcn_update_dpp(0, __builtin_bit_cast(int, x), 0x4E, 0xF, 0xF, true)); }
; __device__ __forceinline__ float dpp_hmir(float x) { return __builtin_bit_cast(float, __builtin_amdgcn_update_dpp(0, __builtin_bit_cast(int, x), 0x141, 0xF, 0xF, true)); }
; __device__ __forceinline__ float dpp_mir(float x)  { return __builtin_bit_cast(float, __builtin_amdgcn_update_dpp(0, __builtin_bit_cast(int, x), 0x140, 0xF, 0xF, true)); }
; __device__ __forceinline__ float red16(float x) { x += dpp_xor1(x); x += dpp_xor2(x); x += dpp_hmir(x); x += dpp_mir(x); return x; }
; __device__ __forceinline__ float wsum(float x) {
;     x = red16(x); const int xi = __builtin_bit_cast(int, x);
;     const float r0 = __builtin_bit_cast(float, __builtin_amdgcn_readlane(xi, 0)), r1 = __builtin_bit_cast(float, __builtin_amdgcn_readlane(xi, 16));
;     const float r2 = __builtin_bit_cast(float, __builtin_amdgcn_readlane(xi, 32)), r3 = __builtin_bit_cast(float, __builtin_amdgcn_readlane(xi, 48));
;     return (r0 + r1) + (r2 + r3);
; __device__ __forceinline__ void rw_post(Frame& F) {
;     ...
;             for (int q = 0; q < 8; ++q) { const int row = rb0 + t0 + q;
;                 const float mean = wsum(y[q]) * (1.f / 64.f); const float dv = y[q] - mean; const float var = wsum(dv * dv) * (1.f / 64.f);
	ds_read_b32 v80, v155 offset:0
	ds_read_b32 v81, v155 offset:16384
	ds_read_u16 v83, v157 offset:0
	ds_read_b32 v85, v155 offset:2048
	ds_read_b32 v86, v155 offset:18432
	ds_read_u16 v88, v157 offset:1024
	ds_read_b32 v90, v155 offset:4096
	ds_read_b32 v91, v155 offset:20480
	ds_read_u16 v93, v157 offset:2048
	ds_read_b32 v95, v155 offset:6144
	ds_read_b32 v96, v155 offset:22528
	ds_read_u16 v98, v157 offset:3072
	ds_read_b32 v100, v155 offset:8192
	ds_read_b32 v101, v155 offset:24576
	ds_read_u16 v103, v157 offset:4096
	ds_read_b32 v105, v155 offset:10240
	ds_read_b32 v106, v155 offset:26624
	ds_read_u16 v108, v157 offset:5120
	ds_read_b32 v110, v155 offset:12288
	ds_read_b32 v111, v155 offset:28672
	ds_read_u16 v113, v157 offset:6144
	ds_read_b32 v115, v155 offset:14336
	ds_read_b32 v116, v155 offset:30720
	ds_read_u16 v118, v157 offset:7168
	s_waitcnt lgkmcnt(0)
	v_add_f32_e32 v80, v80, v52
	v_add_f32_e32 v85, v85, v53
	v_add_f32_e32 v90, v90, v54
	v_add_f32_e32 v95, v95, v55
	v_add_f32_dpp v168, v80, v80 quad_perm:[1,0,3,2] row_mask:0xf bank_mask:0xf bound_ctrl:1
	v_add_f32_dpp v174, v85, v85 quad_perm:[1,0,3,2] row_mask:0xf bank_mask:0xf bound_ctrl:1
	v_add_f32_dpp v241, v90, v90 quad_perm:[1,0,3,2] row_mask:0xf bank_mask:0xf bound_ctrl:1
	v_add_f32_dpp v247, v95, v95 quad_perm:[1,0,3,2] row_mask:0xf bank_mask:0xf bound_ctrl:1
	v_add_f32_dpp v168, v168, v168 quad_perm:[2,3,0,1] row_mask:0xf bank_mask:0xf bound_ctrl:1
	v_add_f32_dpp v174, v174, v174 quad_perm:[2,3,0,1] row_mask:0xf bank_mask:0xf bound_ctrl:1
	v_add_f32_dpp v241, v241, v241 quad_perm:[2,3,0,1] row_mask:0xf bank_mask:0xf bound_ctrl:1
	v_add_f32_dpp v247, v247, v247 quad_perm:[2,3,0,1] row_mask:0xf bank_mask:0xf bound_ctrl:1
	v_add_f32_dpp v168, v168, v168 row_half_mirror row_mask:0xf bank_mask:0xf bound_ctrl:1
	v_add_f32_dpp v174, v174, v174 row_half_mirror row_mask:0xf bank_mask:0xf bound_ctrl:1
	v_add_f32_dpp v241, v241, v241 row_half_mirror row_mask:0xf bank_mask:0xf bound_ctrl:1
	v_add_f32_dpp v247, v247, v247 row_half_mirror row_mask:0xf bank_mask:0xf bound_ctrl:1
	v_add_f32_dpp v168, v168, v168 row_mirror row_mask:0xf bank_mask:0xf bound_ctrl:1
	v_add_f32_dpp v174, v174, v174 row_mirror row_mask:0xf bank_mask:0xf bound_ctrl:1
	v_add_f32_dpp v241, v241, v241 row_mirror row_mask:0xf bank_mask:0xf bound_ctrl:1
	v_add_f32_dpp v247, v247, v247 row_mirror row_mask:0xf bank_mask:0xf bound_ctrl:1
	v_readlane_b32 s36, v168, 16
	v_readlane_b32 s40, v174, 16
	v_readlane_b32 s44, v241, 16
	v_readlane_b32 s48, v247, 16
	v_readlane_b32 s37, v168, 48
	v_readlane_b32 s41, v174, 48
	v_readlane_b32 s45, v241, 48
	v_readlane_b32 s49, v247, 48
	v_readlane_b32 s38, v168, 0
	v_readlane_b32 s42, v174, 0
	v_readlane_b32 s46, v241, 0
	v_readlane_b32 s50, v247, 0
	v_readlane_b32 s39, v168, 32
	v_readlane_b32 s43, v174, 32
	v_readlane_b32 s47, v241, 32
	v_readlane_b32 s51, v247, 32
	v_mov_b32_e32 v168, s36
	v_mov_b32_e32 v174, s40
	v_mov_b32_e32 v241, s44
	v_mov_b32_e32 v247, s48
	v_mov_b32_e32 v169, s37
	v_mov_b32_e32 v175, s41
	v_mov_b32_e32 v242, s45
	v_mov_b32_e32 v248, s49
	v_add_f32_e32 v168, s38, v168
	v_add_f32_e32 v174, s42, v174
	v_add_f32_e32 v241, s46, v241
	v_add_f32_e32 v247, s50, v247
	v_add_f32_e32 v169, s39, v169
	v_add_f32_e32 v175, s43, v175
	v_add_f32_e32 v242, s47, v242
	v_add_f32_e32 v248, s51, v248
	v_add_f32_e32 v168, v168, v169
	v_add_f32_e32 v174, v174, v175
	v_add_f32_e32 v241, v241, v242
	v_add_f32_e32 v247, v247, v248
	v_fmamk_f32 v80, v168, 0xbc800000, v80
	v_fmamk_f32 v85, v174, 0xbc800000, v85
	v_fmamk_f32 v90, v241, 0xbc800000, v90
	v_fmamk_f32 v95, v247, 0xbc800000, v95
	v_mul_f32_e32 v168, v80, v80
	v_mul_f32_e32 v174, v85, v85
	v_mul_f32_e32 v241, v90, v90
	v_mul_f32_e32 v247, v95, v95
	v_mov_b32_dpp v168, v168 quad_perm:[1,0,3,2] row_mask:0xf bank_mask:0xf bound_ctrl:1
	v_mov_b32_dpp v174, v174 quad_perm:[1,0,3,2] row_mask:0xf bank_mask:0xf bound_ctrl:1
	v_mov_b32_dpp v241, v241 quad_perm:[1,0,3,2] row_mask:0xf bank_mask:0xf bound_ctrl:1
	v_mov_b32_dpp v247, v247 quad_perm:[1,0,3,2] row_mask:0xf bank_mask:0xf bound_ctrl:1
	v_fmac_f32_e32 v168, v80, v80
	v_fmac_f32_e32 v174, v85, v85
	v_fmac_f32_e32 v241, v90, v90
	v_fmac_f32_e32 v247, v95, v95
	v_add_f32_dpp v168, v168, v168 quad_perm:[2,3,0,1] row_mask:0xf bank_mask:0xf bound_ctrl:1
	v_add_f32_dpp v174, v174, v174 quad_perm:[2,3,0,1] row_mask:0xf bank_mask:0xf bound_ctrl:1
	v_add_f32_dpp v241, v241, v241 quad_perm:[2,3,0,1] row_mask:0xf bank_mask:0xf bound_ctrl:1
	v_add_f32_dpp v247, v247, v247 quad_perm:[2,3,0,1] row_mask:0xf bank_mask:0xf bound_ctrl:1
	v_add_f32_dpp v168, v168, v168 row_half_mirror row_mask:0xf bank_mask:0xf bound_ctrl:1
	v_add_f32_dpp v174, v174, v174 row_half_mirror row_mask:0xf bank_mask:0xf bound_ctrl:1
	v_add_f32_dpp v241, v241, v241 row_half_mirror row_mask:0xf bank_mask:0xf bound_ctrl:1
	v_add_f32_dpp v247, v247, v247 row_half_mirror row_mask:0xf bank_mask:0xf bound_ctrl:1
	v_add_f32_dpp v168, v168, v168 row_mirror row_mask:0xf bank_mask:0xf bound_ctrl:1
	v_add_f32_dpp v174, v174, v174 row_mirror row_mask:0xf bank_mask:0xf bound_ctrl:1
	v_add_f32_dpp v241, v241, v241 row_mirror row_mask:0xf bank_mask:0xf bound_ctrl:1
	v_add_f32_dpp v247, v247, v247 row_mirror row_mask:0xf bank_mask:0xf bound_ctrl:1
	v_readlane_b32 s36, v168, 16
	v_readlane_b32 s40, v174, 16
	v_readlane_b32 s44, v241, 16
	v_readlane_b32 s48, v247, 16
	v_readlane_b32 s37, v168, 48
	v_readlane_b32 s41, v174, 48
	v_readlane_b32 s45, v241, 48
	v_readlane_b32 s49, v247, 48
	v_readlane_b32 s38, v168, 0
	v_readlane_b32 s42, v174, 0
	v_readlane_b32 s46, v241, 0
	v_readlane_b32 s50, v247, 0
	v_readlane_b32 s39, v168, 32
; __device__ __forceinline__ float bf2f(bf16 x) { return __uint_as_float(((unsigned)x) << 16); }
; __device__ __forceinline__ unsigned f2bf(float f) { return cvt_pk_bf16(f, 0.f) & 0xffffu; }
; __device__ __forceinline__ void rw_post(Frame& F) {
;     ...
;                 const float mean = wsum(y[q]) * (1.f / 64.f); const float dv = y[q] - mean; const float var = wsum(dv * dv) * (1.f / 64.f);
;                 const float yn = dv * (1.f / sqrtf(var + 64e-5f)) * g_ + b_;
;                 OB[(size_t)row * DH + col] = (bf16)f2bf((yn + rk[q] * vv[q]) * bf2f(gg[q])); }
	v_readlane_b32 s43, v174, 32
	v_readlane_b32 s47, v241, 32
	v_readlane_b32 s51, v247, 32
	v_mov_b32_e32 v168, s36
	v_mov_b32_e32 v174, s40
	v_mov_b32_e32 v241, s44
	v_mov_b32_e32 v247, s48
	v_mov_b32_e32 v169, s37
	v_mov_b32_e32 v175, s41
	v_mov_b32_e32 v242, s45
	v_mov_b32_e32 v248, s49
	v_add_f32_e32 v168, s38, v168
	v_add_f32_e32 v174, s42, v174
	v_add_f32_e32 v241, s46, v241
	v_add_f32_e32 v247, s50, v247
	v_add_f32_e32 v169, s39, v169
	v_add_f32_e32 v175, s43, v175
	v_add_f32_e32 v242, s47, v242
	v_add_f32_e32 v248, s51, v248
	v_add_f32_e32 v168, v168, v169
	v_add_f32_e32 v174, v174, v175
	v_add_f32_e32 v241, v241, v242
	v_add_f32_e32 v247, v247, v248
	v_fmamk_f32 v168, v168, 0x3c800000, v9
	v_fmamk_f32 v174, v174, 0x3c800000, v9
	v_fmamk_f32 v241, v241, 0x3c800000, v9
	v_fmamk_f32 v247, v247, 0x3c800000, v9
	v_mul_f32_e32 v169, 0x4f800000, v168
	v_mul_f32_e32 v175, 0x4f800000, v174
	v_mul_f32_e32 v242, 0x4f800000, v241
	v_mul_f32_e32 v248, 0x4f800000, v247
	v_cmp_gt_f32_e64 s[52:53], s68, v168
	v_cmp_gt_f32_e64 s[54:55], s68, v174
	v_cmp_gt_f32_e64 s[56:57], s68, v241
	v_cmp_gt_f32_e64 s[58:59], s68, v247
	v_mov_b32_e32 v170, v168
	v_mov_b32_e32 v176, v174
	v_mov_b32_e32 v243, v241
	v_mov_b32_e32 v249, v247
	v_cndmask_b32_e64 v168, v170, v169, s[52:53]
	v_cndmask_b32_e64 v174, v176, v175, s[54:55]
	v_cndmask_b32_e64 v241, v243, v242, s[56:57]
	v_cndmask_b32_e64 v247, v249, v248, s[58:59]
	v_sqrt_f32_e32 v169, v168
	v_sqrt_f32_e32 v175, v174
	v_sqrt_f32_e32 v242, v241
	v_sqrt_f32_e32 v248, v247
	v_add_u32_e32 v170, -1, v169
	v_add_u32_e32 v176, -1, v175
	v_add_u32_e32 v243, -1, v242
	v_add_u32_e32 v249, -1, v248
	v_fma_f32 v171, -v170, v169, v168
	v_fma_f32 v177, -v176, v175, v174
	v_fma_f32 v244, -v243, v242, v241
	v_fma_f32 v250, -v249, v248, v247
	v_cmp_ge_f32_e64 s[60:61], 0, v171
	v_cmp_ge_f32_e64 s[62:63], 0, v177
	v_cmp_ge_f32_e64 s[64:65], 0, v244
	v_cmp_ge_f32_e64 s[66:67], 0, v250
	v_add_u32_e32 v171, 1, v169
	v_add_u32_e32 v177, 1, v175
	v_add_u32_e32 v244, 1, v242
	v_add_u32_e32 v250, 1, v248
	v_cndmask_b32_e64 v170, v169, v170, s[60:61]
	v_cndmask_b32_e64 v176, v175, v176, s[62:63]
	v_cndmask_b32_e64 v243, v242, v243, s[64:65]
	v_cndmask_b32_e64 v249, v248, v249, s[66:67]
	v_fma_f32 v169, -v171, v169, v168
	v_fma_f32 v175, -v177, v175, v174
	v_fma_f32 v242, -v244, v242, v241
	v_fma_f32 v248, -v250, v248, v247
	v_cmp_lt_f32_e64 s[60:61], 0, v169
	v_cmp_lt_f32_e64 s[62:63], 0, v175
	v_cmp_lt_f32_e64 s[64:65], 0, v242
	v_cmp_lt_f32_e64 s[66:67], 0, v248
	v_cndmask_b32_e64 v169, v170, v171, s[60:61]
	v_cndmask_b32_e64 v175, v176, v177, s[62:63]
	v_cndmask_b32_e64 v242, v243, v244, s[64:65]
	v_cndmask_b32_e64 v248, v249, v250, s[66:67]
	v_mul_f32_e32 v170, 0x37800000, v169
	v_mul_f32_e32 v176, 0x37800000, v175
	v_mul_f32_e32 v243, 0x37800000, v242
	v_mul_f32_e32 v249, 0x37800000, v248
	v_cndmask_b32_e64 v169, v169, v170, s[52:53]
	v_cndmask_b32_e64 v175, v175, v176, s[54:55]
	v_cndmask_b32_e64 v242, v242, v243, s[56:57]
	v_cndmask_b32_e64 v248, v248, v249, s[58:59]
	v_cmp_class_f32_e64 s[60:61], v168, v8
	v_cmp_class_f32_e64 s[62:63], v174, v8
	v_cmp_class_f32_e64 s[64:65], v241, v8
	v_cmp_class_f32_e64 s[66:67], v247, v8
	v_cndmask_b32_e64 v168, v169, v168, s[60:61]
	v_cndmask_b32_e64 v174, v175, v174, s[62:63]
	v_cndmask_b32_e64 v241, v242, v241, s[64:65]
	v_cndmask_b32_e64 v247, v248, v247, s[66:67]
	v_div_scale_f32 v169, s[60:61], v168, v168, 1.0
	v_rcp_f32_e32 v170, v169
	s_nop 0
	v_fma_f32 v171, -v169, v170, 1.0
	v_fmac_f32_e32 v170, v171, v170
	v_div_scale_f32 v171, vcc, 1.0, v168, 1.0
	v_mul_f32_e32 v172, v171, v170
	v_fma_f32 v173, -v169, v172, v171
	v_fmac_f32_e32 v172, v173, v170
	v_fma_f32 v169, -v169, v172, v171
	v_div_fmas_f32 v169, v169, v170, v172
	v_div_fixup_f32 v168, v169, v168, 1.0
	v_div_scale_f32 v175, s[62:63], v174, v174, 1.0
	v_rcp_f32_e32 v176, v175
	s_nop 0
	v_fma_f32 v177, -v175, v176, 1.0
	v_fmac_f32_e32 v176, v177, v176
	v_div_scale_f32 v177, vcc, 1.0, v174, 1.0
	v_mul_f32_e32 v236, v177, v176
	v_fma_f32 v237, -v175, v236, v177
	v_fmac_f32_e32 v236, v237, v176
	v_fma_f32 v175, -v175, v236, v177
	v_div_fmas_f32 v175, v175, v176, v236
	v_div_fixup_f32 v174, v175, v174, 1.0
	v_div_scale_f32 v242, s[64:65], v241, v241, 1.0
	v_rcp_f32_e32 v243, v242
	s_nop 0
	v_fma_f32 v244, -v242, v243, 1.0
	v_fmac_f32_e32 v243, v244, v243
	v_div_scale_f32 v244, vcc, 1.0, v241, 1.0
	v_mul_f32_e32 v245, v244, v243
	v_fma_f32 v246, -v242, v245, v244
	v_fmac_f32_e32 v245, v246, v243
	v_fma_f32 v242, -v242, v245, v244
	v_div_fmas_f32 v242, v242, v243, v245
	v_div_fixup_f32 v241, v242, v241, 1.0
	v_div_scale_f32 v248, s[66:67], v247, v247, 1.0
	v_rcp_f32_e32 v249, v248
	s_nop 0
	v_fma_f32 v250, -v248, v249, 1.0
	v_fmac_f32_e32 v249, v250, v249
	v_div_scale_f32 v250, vcc, 1.0, v247, 1.0
	v_mul_f32_e32 v251, v250, v249
	v_fma_f32 v252, -v248, v251, v250
	v_fmac_f32_e32 v251, v252, v249
	v_fma_f32 v248, -v248, v251, v250
	v_div_fmas_f32 v248, v248, v249, v251
	v_div_fixup_f32 v247, v248, v247, 1.0
	v_mul_f32_e32 v80, v80, v168
	v_mul_f32_e32 v85, v85, v174
	v_mul_f32_e32 v90, v90, v241
	v_mul_f32_e32 v95, v95, v247
	v_lshlrev_b32_e32 v83, 16, v83
	v_lshlrev_b32_e32 v88, 16, v88
	v_lshlrev_b32_e32 v93, 16, v93
	v_lshlrev_b32_e32 v98, 16, v98
	v_fma_f32 v80, v6, v80, v7
	v_fma_f32 v85, v6, v85, v7
	v_fma_f32 v90, v6, v90, v7
	v_fma_f32 v95, v6, v95, v7
	v_fmac_f32_e32 v80, s69, v81
	v_fmac_f32_e32 v85, s70, v86
	v_fmac_f32_e32 v90, s71, v91
	v_fmac_f32_e32 v95, s72, v96
	v_mul_f32_e32 v80, v80, v83
	v_mul_f32_e32 v85, v85, v88
	v_mul_f32_e32 v90, v90, v93
	v_mul_f32_e32 v95, v95, v98
	v_cvt_pk_bf16_f32 v169, v80, v80
; __device__ __forceinline__ float bf2f(bf16 x) { return __uint_as_float(((unsigned)x) << 16); }
; __device__ __forceinline__ unsigned f2bf(float f) { return cvt_pk_bf16(f, 0.f) & 0xffffu; }
; __device__ __forceinline__ float dpp_xor1(float x) { return __builtin_bit_cast(float, __builtin_amdgcn_update_dpp(0, __builtin_bit_cast(int, x), 0xB1, 0xF, 0xF, true)); }
; __device__ __forceinline__ float dpp_xor2(float x) { return __builtin_bit_cast(float, __builtin_amdgcn_update_dpp(0, __builtin_bit_cast(int, x), 0x4E, 0xF, 0xF, true)); }
; __device__ __forceinline__ float dpp_hmir(float x) { return __builtin_bit_cast(float, __builtin_amdgcn_update_dpp(0, __builtin_bit_cast(int, x), 0x141, 0xF, 0xF, true)); }
; __device__ __forceinline__ float dpp_mir(float x)  { return __builtin_bit_cast(float, __builtin_amdgcn_update_dpp(0, __builtin_bit_cast(int, x), 0x140, 0xF, 0xF, true)); }
; __device__ __forceinline__ float red16(float x) { x += dpp_xor1(x); x += dpp_xor2(x); x += dpp_hmir(x); x += dpp_mir(x); return x; }
; __device__ __forceinline__ float wsum(float x) {
;     x = red16(x); const int xi = __builtin_bit_cast(int, x);
;     const float r0 = __builtin_bit_cast(float, __builtin_amdgcn_readlane(xi, 0)), r1 = __builtin_bit_cast(float, __builtin_amdgcn_readlane(xi, 16));
;     const float r2 = __builtin_bit_cast(float, __builtin_amdgcn_readlane(xi, 32)), r3 = __builtin_bit_cast(float, __builtin_amdgcn_readlane(xi, 48));
;     return (r0 + r1) + (r2 + r3);
; __device__ __forceinline__ void rw_post(Frame& F) {
;     ...
;             for (int q = 0; q < 8; ++q) { const int row = rb0 + t0 + q;
;                 const float mean = wsum(y[q]) * (1.f / 64.f); const float dv = y[q] - mean; const float var = wsum(dv * dv) * (1.f / 64.f);
;                 const float yn = dv * (1.f / sqrtf(var + 64e-5f)) * g_ + b_;
;                 OB[(size_t)row * DH + col] = (bf16)f2bf((yn + rk[q] * vv[q]) * bf2f(gg[q])); }
	v_cvt_pk_bf16_f32 v175, v85, v85
	v_cvt_pk_bf16_f32 v242, v90, v90
	v_cvt_pk_bf16_f32 v248, v95, v95
	global_store_short v2, v169, s[28:29]
	s_add_u32 s28, s28, 0x1000
	s_addc_u32 s29, s29, 0
	global_store_short v2, v175, s[28:29]
	s_add_u32 s28, s28, 0x1000
	s_addc_u32 s29, s29, 0
	global_store_short v2, v242, s[28:29]
	s_add_u32 s28, s28, 0x1000
	s_addc_u32 s29, s29, 0
	global_store_short v2, v248, s[28:29]
	s_add_u32 s28, s28, 0x1000
	s_addc_u32 s29, s29, 0
	v_add_f32_e32 v100, v100, v68
	v_add_f32_e32 v105, v105, v69
	v_add_f32_e32 v110, v110, v70
	v_add_f32_e32 v115, v115, v71
	v_add_f32_dpp v168, v100, v100 quad_perm:[1,0,3,2] row_mask:0xf bank_mask:0xf bound_ctrl:1
	v_add_f32_dpp v174, v105, v105 quad_perm:[1,0,3,2] row_mask:0xf bank_mask:0xf bound_ctrl:1
	v_add_f32_dpp v241, v110, v110 quad_perm:[1,0,3,2] row_mask:0xf bank_mask:0xf bound_ctrl:1
	v_add_f32_dpp v247, v115, v115 quad_perm:[1,0,3,2] row_mask:0xf bank_mask:0xf bound_ctrl:1
	v_add_f32_dpp v168, v168, v168 quad_perm:[2,3,0,1] row_mask:0xf bank_mask:0xf bound_ctrl:1
	v_add_f32_dpp v174, v174, v174 quad_perm:[2,3,0,1] row_mask:0xf bank_mask:0xf bound_ctrl:1
	v_add_f32_dpp v241, v241, v241 quad_perm:[2,3,0,1] row_mask:0xf bank_mask:0xf bound_ctrl:1
	v_add_f32_dpp v247, v247, v247 quad_perm:[2,3,0,1] row_mask:0xf bank_mask:0xf bound_ctrl:1
	v_add_f32_dpp v168, v168, v168 row_half_mirror row_mask:0xf bank_mask:0xf bound_ctrl:1
	v_add_f32_dpp v174, v174, v174 row_half_mirror row_mask:0xf bank_mask:0xf bound_ctrl:1
	v_add_f32_dpp v241, v241, v241 row_half_mirror row_mask:0xf bank_mask:0xf bound_ctrl:1
	v_add_f32_dpp v247, v247, v247 row_half_mirror row_mask:0xf bank_mask:0xf bound_ctrl:1
	v_add_f32_dpp v168, v168, v168 row_mirror row_mask:0xf bank_mask:0xf bound_ctrl:1
	v_add_f32_dpp v174, v174, v174 row_mirror row_mask:0xf bank_mask:0xf bound_ctrl:1
	v_add_f32_dpp v241, v241, v241 row_mirror row_mask:0xf bank_mask:0xf bound_ctrl:1
	v_add_f32_dpp v247, v247, v247 row_mirror row_mask:0xf bank_mask:0xf bound_ctrl:1
	v_readlane_b32 s36, v168, 16
	v_readlane_b32 s40, v174, 16
	v_readlane_b32 s44, v241, 16
	v_readlane_b32 s48, v247, 16
	v_readlane_b32 s37, v168, 48
	v_readlane_b32 s41, v174, 48
	v_readlane_b32 s45, v241, 48
	v_readlane_b32 s49, v247, 48
	v_readlane_b32 s38, v168, 0
	v_readlane_b32 s42, v174, 0
	v_readlane_b32 s46, v241, 0
	v_readlane_b32 s50, v247, 0
	v_readlane_b32 s39, v168, 32
	v_readlane_b32 s43, v174, 32
	v_readlane_b32 s47, v241, 32
	v_readlane_b32 s51, v247, 32
	v_mov_b32_e32 v168, s36
	v_mov_b32_e32 v174, s40
	v_mov_b32_e32 v241, s44
	v_mov_b32_e32 v247, s48
	v_mov_b32_e32 v169, s37
	v_mov_b32_e32 v175, s41
	v_mov_b32_e32 v242, s45
	v_mov_b32_e32 v248, s49
	v_add_f32_e32 v168, s38, v168
	v_add_f32_e32 v174, s42, v174
	v_add_f32_e32 v241, s46, v241
	v_add_f32_e32 v247, s50, v247
	v_add_f32_e32 v169, s39, v169
	v_add_f32_e32 v175, s43, v175
	v_add_f32_e32 v242, s47, v242
	v_add_f32_e32 v248, s51, v248
	v_add_f32_e32 v168, v168, v169
	v_add_f32_e32 v174, v174, v175
	v_add_f32_e32 v241, v241, v242
	v_add_f32_e32 v247, v247, v248
	v_fmamk_f32 v100, v168, 0xbc800000, v100
	v_fmamk_f32 v105, v174, 0xbc800000, v105
	v_fmamk_f32 v110, v241, 0xbc800000, v110
	v_fmamk_f32 v115, v247, 0xbc800000, v115
	v_mul_f32_e32 v168, v100, v100
	v_mul_f32_e32 v174, v105, v105
	v_mul_f32_e32 v241, v110, v110
	v_mul_f32_e32 v247, v115, v115
	v_mov_b32_dpp v168, v168 quad_perm:[1,0,3,2] row_mask:0xf bank_mask:0xf bound_ctrl:1
	v_mov_b32_dpp v174, v174 quad_perm:[1,0,3,2] row_mask:0xf bank_mask:0xf bound_ctrl:1
	v_mov_b32_dpp v241, v241 quad_perm:[1,0,3,2] row_mask:0xf bank_mask:0xf bound_ctrl:1
	v_mov_b32_dpp v247, v247 quad_perm:[1,0,3,2] row_mask:0xf bank_mask:0xf bound_ctrl:1
	v_fmac_f32_e32 v168, v100, v100
	v_fmac_f32_e32 v174, v105, v105
	v_fmac_f32_e32 v241, v110, v110
	v_fmac_f32_e32 v247, v115, v115
	v_add_f32_dpp v168, v168, v168 quad_perm:[2,3,0,1] row_mask:0xf bank_mask:0xf bound_ctrl:1
	v_add_f32_dpp v174, v174, v174 quad_perm:[2,3,0,1] row_mask:0xf bank_mask:0xf bound_ctrl:1
	v_add_f32_dpp v241, v241, v241 quad_perm:[2,3,0,1] row_mask:0xf bank_mask:0xf bound_ctrl:1
	v_add_f32_dpp v247, v247, v247 quad_perm:[2,3,0,1] row_mask:0xf bank_mask:0xf bound_ctrl:1
	v_add_f32_dpp v168, v168, v168 row_half_mirror row_mask:0xf bank_mask:0xf bound_ctrl:1
	v_add_f32_dpp v174, v174, v174 row_half_mirror row_mask:0xf bank_mask:0xf bound_ctrl:1
	v_add_f32_dpp v241, v241, v241 row_half_mirror row_mask:0xf bank_mask:0xf bound_ctrl:1
	v_add_f32_dpp v247, v247, v247 row_half_mirror row_mask:0xf bank_mask:0xf bound_ctrl:1
	v_add_f32_dpp v168, v168, v168 row_mirror row_mask:0xf bank_mask:0xf bound_ctrl:1
	v_add_f32_dpp v174, v174, v174 row_mirror row_mask:0xf bank_mask:0xf bound_ctrl:1
	v_add_f32_dpp v241, v241, v241 row_mirror row_mask:0xf bank_mask:0xf bound_ctrl:1
	v_add_f32_dpp v247, v247, v247 row_mirror row_mask:0xf bank_mask:0xf bound_ctrl:1
	v_readlane_b32 s36, v168, 16
	v_readlane_b32 s40, v174, 16
	v_readlane_b32 s44, v241, 16
	v_readlane_b32 s48, v247, 16
	v_readlane_b32 s37, v168, 48
	v_readlane_b32 s41, v174, 48
	v_readlane_b32 s45, v241, 48
	v_readlane_b32 s49, v247, 48
	v_readlane_b32 s38, v168, 0
	v_readlane_b32 s42, v174, 0
	v_readlane_b32 s46, v241, 0
	v_readlane_b32 s50, v247, 0
	v_readlane_b32 s39, v168, 32
	v_readlane_b32 s43, v174, 32
	v_readlane_b32 s47, v241, 32
	v_readlane_b32 s51, v247, 32
	v_mov_b32_e32 v168, s36
	v_mov_b32_e32 v174, s40
	v_mov_b32_e32 v241, s44
	v_mov_b32_e32 v247, s48
	v_mov_b32_e32 v169, s37
	v_mov_b32_e32 v175, s41
	v_mov_b32_e32 v242, s45
	v_mov_b32_e32 v248, s49
	v_add_f32_e32 v168, s38, v168
	v_add_f32_e32 v174, s42, v174
	v_add_f32_e32 v241, s46, v241
; __device__ __forceinline__ float bf2f(bf16 x) { return __uint_as_float(((unsigned)x) << 16); }
; __device__ __forceinline__ unsigned f2bf(float f) { return cvt_pk_bf16(f, 0.f) & 0xffffu; }
; #define POST_LD(Y_, V_, G_, R_, C_, t) do { _Pragma("unroll") for (int q = 0; q < 8; ++q) { const size_t o_ = (size_t)((t) + q) * DH; Y_[q] = yp[o_]; V_[q] = vp[o_]; G_[q] = gp[o_]; R_[q] = rp[((t) + q) * 32]; C_[q] = cp[o_]; } } while (0)
; __device__ __forceinline__ void rw_post(Frame& F) {
;     ...
;         POST_LD(y, vv, gg, rk, cc, 0);
;         for (int t0 = 0; t0 < 64; t0 += 8) {
;             float ny[8], nv[8], nr[8], nc[8]; bf16 ng[8];
;             const int tn = t0 + 8 < 64 ? t0 + 8 : t0;
;             POST_LD(ny, nv, ng, nr, nc, tn);
;     ...
;             for (int q = 0; q < 8; ++q) { const int row = rb0 + t0 + q;
;                 const float mean = wsum(y[q]) * (1.f / 64.f); const float dv = y[q] - mean; const float var = wsum(dv * dv) * (1.f / 64.f);
;                 const float yn = dv * (1.f / sqrtf(var + 64e-5f)) * g_ + b_;
;                 OB[(size_t)row * DH + col] = (bf16)f2bf((yn + rk[q] * vv[q]) * bf2f(gg[q])); }
	v_add_f32_e32 v247, s50, v247
	v_add_f32_e32 v169, s39, v169
	v_add_f32_e32 v175, s43, v175
	v_add_f32_e32 v242, s47, v242
	v_add_f32_e32 v248, s51, v248
	v_add_f32_e32 v168, v168, v169
	v_add_f32_e32 v174, v174, v175
	v_add_f32_e32 v241, v241, v242
	v_add_f32_e32 v247, v247, v248
	v_fmamk_f32 v168, v168, 0x3c800000, v9
	v_fmamk_f32 v174, v174, 0x3c800000, v9
	v_fmamk_f32 v241, v241, 0x3c800000, v9
	v_fmamk_f32 v247, v247, 0x3c800000, v9
	v_mul_f32_e32 v169, 0x4f800000, v168
	v_mul_f32_e32 v175, 0x4f800000, v174
	v_mul_f32_e32 v242, 0x4f800000, v241
	v_mul_f32_e32 v248, 0x4f800000, v247
	v_cmp_gt_f32_e64 s[52:53], s68, v168
	v_cmp_gt_f32_e64 s[54:55], s68, v174
	v_cmp_gt_f32_e64 s[56:57], s68, v241
	v_cmp_gt_f32_e64 s[58:59], s68, v247
	v_mov_b32_e32 v170, v168
	v_mov_b32_e32 v176, v174
	v_mov_b32_e32 v243, v241
	v_mov_b32_e32 v249, v247
	v_cndmask_b32_e64 v168, v170, v169, s[52:53]
	v_cndmask_b32_e64 v174, v176, v175, s[54:55]
	v_cndmask_b32_e64 v241, v243, v242, s[56:57]
	v_cndmask_b32_e64 v247, v249, v248, s[58:59]
	v_sqrt_f32_e32 v169, v168
	v_sqrt_f32_e32 v175, v174
	v_sqrt_f32_e32 v242, v241
	v_sqrt_f32_e32 v248, v247
	v_add_u32_e32 v170, -1, v169
	v_add_u32_e32 v176, -1, v175
	v_add_u32_e32 v243, -1, v242
	v_add_u32_e32 v249, -1, v248
	v_fma_f32 v171, -v170, v169, v168
	v_fma_f32 v177, -v176, v175, v174
	v_fma_f32 v244, -v243, v242, v241
	v_fma_f32 v250, -v249, v248, v247
	v_cmp_ge_f32_e64 s[60:61], 0, v171
	v_cmp_ge_f32_e64 s[62:63], 0, v177
	v_cmp_ge_f32_e64 s[64:65], 0, v244
	v_cmp_ge_f32_e64 s[66:67], 0, v250
	v_add_u32_e32 v171, 1, v169
	v_add_u32_e32 v177, 1, v175
	v_add_u32_e32 v244, 1, v242
	v_add_u32_e32 v250, 1, v248
	v_cndmask_b32_e64 v170, v169, v170, s[60:61]
	v_cndmask_b32_e64 v176, v175, v176, s[62:63]
	v_cndmask_b32_e64 v243, v242, v243, s[64:65]
	v_cndmask_b32_e64 v249, v248, v249, s[66:67]
	v_fma_f32 v169, -v171, v169, v168
	v_fma_f32 v175, -v177, v175, v174
	v_fma_f32 v242, -v244, v242, v241
	v_fma_f32 v248, -v250, v248, v247
	v_cmp_lt_f32_e64 s[60:61], 0, v169
	v_cmp_lt_f32_e64 s[62:63], 0, v175
	v_cmp_lt_f32_e64 s[64:65], 0, v242
	v_cmp_lt_f32_e64 s[66:67], 0, v248
	v_cndmask_b32_e64 v169, v170, v171, s[60:61]
	v_cndmask_b32_e64 v175, v176, v177, s[62:63]
	v_cndmask_b32_e64 v242, v243, v244, s[64:65]
	v_cndmask_b32_e64 v248, v249, v250, s[66:67]
	v_mul_f32_e32 v170, 0x37800000, v169
	v_mul_f32_e32 v176, 0x37800000, v175
	v_mul_f32_e32 v243, 0x37800000, v242
	v_mul_f32_e32 v249, 0x37800000, v248
	v_cndmask_b32_e64 v169, v169, v170, s[52:53]
	v_cndmask_b32_e64 v175, v175, v176, s[54:55]
	v_cndmask_b32_e64 v242, v242, v243, s[56:57]
	v_cndmask_b32_e64 v248, v248, v249, s[58:59]
	v_cmp_class_f32_e64 s[60:61], v168, v8
	v_cmp_class_f32_e64 s[62:63], v174, v8
	v_cmp_class_f32_e64 s[64:65], v241, v8
	v_cmp_class_f32_e64 s[66:67], v247, v8
	v_cndmask_b32_e64 v168, v169, v168, s[60:61]
	v_cndmask_b32_e64 v174, v175, v174, s[62:63]
	v_cndmask_b32_e64 v241, v242, v241, s[64:65]
	v_cndmask_b32_e64 v247, v248, v247, s[66:67]
	v_div_scale_f32 v169, s[60:61], v168, v168, 1.0
	v_rcp_f32_e32 v170, v169
	s_nop 0
	v_fma_f32 v171, -v169, v170, 1.0
	v_fmac_f32_e32 v170, v171, v170
	v_div_scale_f32 v171, vcc, 1.0, v168, 1.0
	v_mul_f32_e32 v172, v171, v170
	v_fma_f32 v173, -v169, v172, v171
	v_fmac_f32_e32 v172, v173, v170
	v_fma_f32 v169, -v169, v172, v171
	v_div_fmas_f32 v169, v169, v170, v172
	v_div_fixup_f32 v168, v169, v168, 1.0
	v_div_scale_f32 v175, s[62:63], v174, v174, 1.0
	v_rcp_f32_e32 v176, v175
	s_nop 0
	v_fma_f32 v177, -v175, v176, 1.0
	v_fmac_f32_e32 v176, v177, v176
	v_div_scale_f32 v177, vcc, 1.0, v174, 1.0
	v_mul_f32_e32 v236, v177, v176
	v_fma_f32 v237, -v175, v236, v177
	v_fmac_f32_e32 v236, v237, v176
	v_fma_f32 v175, -v175, v236, v177
	v_div_fmas_f32 v175, v175, v176, v236
	v_div_fixup_f32 v174, v175, v174, 1.0
	v_div_scale_f32 v242, s[64:65], v241, v241, 1.0
	v_rcp_f32_e32 v243, v242
	s_nop 0
	v_fma_f32 v244, -v242, v243, 1.0
	v_fmac_f32_e32 v243, v244, v243
	v_div_scale_f32 v244, vcc, 1.0, v241, 1.0
	v_mul_f32_e32 v245, v244, v243
	v_fma_f32 v246, -v242, v245, v244
	v_fmac_f32_e32 v245, v246, v243
	v_fma_f32 v242, -v242, v245, v244
	v_div_fmas_f32 v242, v242, v243, v245
	v_div_fixup_f32 v241, v242, v241, 1.0
	v_div_scale_f32 v248, s[66:67], v247, v247, 1.0
	v_rcp_f32_e32 v249, v248
	s_nop 0
	v_fma_f32 v250, -v248, v249, 1.0
	v_fmac_f32_e32 v249, v250, v249
	v_div_scale_f32 v250, vcc, 1.0, v247, 1.0
	v_mul_f32_e32 v251, v250, v249
	v_fma_f32 v252, -v248, v251, v250
	v_fmac_f32_e32 v251, v252, v249
	v_fma_f32 v248, -v248, v251, v250
	v_div_fmas_f32 v248, v248, v249, v251
	v_div_fixup_f32 v247, v248, v247, 1.0
	v_mul_f32_e32 v100, v100, v168
	v_mul_f32_e32 v105, v105, v174
	v_mul_f32_e32 v110, v110, v241
	v_mul_f32_e32 v115, v115, v247
	v_lshlrev_b32_e32 v103, 16, v103
	v_lshlrev_b32_e32 v108, 16, v108
	v_lshlrev_b32_e32 v113, 16, v113
	v_lshlrev_b32_e32 v118, 16, v118
	v_fma_f32 v100, v6, v100, v7
	v_fma_f32 v105, v6, v105, v7
	v_fma_f32 v110, v6, v110, v7
	v_fma_f32 v115, v6, v115, v7
	v_fmac_f32_e32 v100, s73, v101
	v_fmac_f32_e32 v105, s26, v106
	v_fmac_f32_e32 v110, s27, v111
	v_fmac_f32_e32 v115, s32, v116
	v_mul_f32_e32 v100, v100, v103
	v_mul_f32_e32 v105, v105, v108
	v_mul_f32_e32 v110, v110, v113
	v_mul_f32_e32 v115, v115, v118
	v_cvt_pk_bf16_f32 v169, v100, v100
	v_cvt_pk_bf16_f32 v175, v105, v105
	v_cvt_pk_bf16_f32 v242, v110, v110
	v_cvt_pk_bf16_f32 v248, v115, v115
	global_store_short v2, v169, s[28:29]
	s_add_u32 s28, s28, 0x1000
	s_addc_u32 s29, s29, 0
	global_store_short v2, v175, s[28:29]
	s_add_u32 s28, s28, 0x1000
	s_addc_u32 s29, s29, 0
	global_store_short v2, v242, s[28:29]
	s_add_u32 s28, s28, 0x1000
	s_addc_u32 s29, s29, 0
	global_store_short v2, v248, s[28:29]
	s_add_u32 s28, s28, 0x1000
	s_addc_u32 s29, s29, 0
	s_waitcnt vmcnt(8)
	ds_write_b128 v12, v[120:123] offset:0
	ds_write_b128 v12, v[124:127] offset:1024
	ds_write_b128 v12, v[128:131] offset:16384
	ds_write_b128 v12, v[132:135] offset:17408
	ds_write_b128 v14, v[136:139]
	v_readlane_b32 s69, v159, 0
	v_readlane_b32 s70, v159, 1
	v_readlane_b32 s71, v159, 2
	v_readlane_b32 s72, v159, 3
	v_readlane_b32 s73, v159, 4
	v_readlane_b32 s26, v159, 5
	v_readlane_b32 s27, v159, 6
	v_readlane_b32 s32, v159, 7
	global_load_dwordx4 v[120:123], v11, s[6:7]
	global_load_dwordx4 v[124:127], v11, s[6:7] offset:1024
	global_load_dwordx4 v[128:131], v11, s[8:9]
	global_load_dwordx4 v[132:135], v11, s[8:9] offset:1024
	global_load_dwordx4 v[136:139], v11, s[10:11]
	global_load_dword v159, v158, s[12:13]
	s_add_u32 s6, s6, 0x10000
	s_addc_u32 s7, s7, 0
	s_add_u32 s8, s8, 0x10000
	s_addc_u32 s9, s9, 0
	s_add_u32 s10, s10, 0x8000
	s_addc_u32 s11, s11, 0
	s_add_u32 s12, s12, 0x400
	s_addc_u32 s13, s13, 0
	s_waitcnt lgkmcnt(0)
	s_barrier
; __device__ __forceinline__ float dpp_xor1(float x) { return __builtin_bit_cast(float, __builtin_amdgcn_update_dpp(0, __builtin_bit_cast(int, x), 0xB1, 0xF, 0xF, true)); }
; __device__ __forceinline__ float dpp_xor2(float x) { return __builtin_bit_cast(float, __builtin_amdgcn_update_dpp(0, __builtin_bit_cast(int, x), 0x4E, 0xF, 0xF, true)); }
; __device__ __forceinline__ float dpp_hmir(float x) { return __builtin_bit_cast(float, __builtin_amdgcn_update_dpp(0, __builtin_bit_cast(int, x), 0x141, 0xF, 0xF, true)); }
; __device__ __forceinline__ float dpp_mir(float x)  { return __builtin_bit_cast(float, __builtin_amdgcn_update_dpp(0, __builtin_bit_cast(int, x), 0x140, 0xF, 0xF, true)); }
; __device__ __forceinline__ float red16(float x) { x += dpp_xor1(x); x += dpp_xor2(x); x += dpp_hmir(x); x += dpp_mir(x); return x; }
; __device__ __forceinline__ float wsum(float x) {
;     x = red16(x); const int xi = __builtin_bit_cast(int, x);
;     const float r0 = __builtin_bit_cast(float, __builtin_amdgcn_readlane(xi, 0)), r1 = __builtin_bit_cast(float, __builtin_amdgcn_readlane(xi, 16));
;     const float r2 = __builtin_bit_cast(float, __builtin_amdgcn_readlane(xi, 32)), r3 = __builtin_bit_cast(float, __builtin_amdgcn_readlane(xi, 48));
;     return (r0 + r1) + (r2 + r3);
; __device__ __forceinline__ void rw_post(Frame& F) {
;     ...
;             for (int q = 0; q < 8; ++q) { const int row = rb0 + t0 + q;
;                 const float mean = wsum(y[q]) * (1.f / 64.f); const float dv = y[q] - mean; const float var = wsum(dv * dv) * (1.f / 64.f);
	ds_read_b32 v80, v154 offset:0
	ds_read_b32 v81, v154 offset:16384
	ds_read_u16 v83, v156 offset:0
	ds_read_b32 v85, v154 offset:2048
	ds_read_b32 v86, v154 offset:18432
	ds_read_u16 v88, v156 offset:1024
	ds_read_b32 v90, v154 offset:4096
	ds_read_b32 v91, v154 offset:20480
	ds_read_u16 v93, v156 offset:2048
	ds_read_b32 v95, v154 offset:6144
	ds_read_b32 v96, v154 offset:22528
	ds_read_u16 v98, v156 offset:3072
	ds_read_b32 v100, v154 offset:8192
	ds_read_b32 v101, v154 offset:24576
	ds_read_u16 v103, v156 offset:4096
	ds_read_b32 v105, v154 offset:10240
	ds_read_b32 v106, v154 offset:26624
	ds_read_u16 v108, v156 offset:5120
	ds_read_b32 v110, v154 offset:12288
	ds_read_b32 v111, v154 offset:28672
	ds_read_u16 v113, v156 offset:6144
	ds_read_b32 v115, v154 offset:14336
	ds_read_b32 v116, v154 offset:30720
	ds_read_u16 v118, v156 offset:7168
	s_waitcnt lgkmcnt(0)
	v_add_f32_e32 v80, v80, v56
	v_add_f32_e32 v85, v85, v57
	v_add_f32_e32 v90, v90, v58
	v_add_f32_e32 v95, v95, v59
	v_add_f32_dpp v168, v80, v80 quad_perm:[1,0,3,2] row_mask:0xf bank_mask:0xf bound_ctrl:1
	v_add_f32_dpp v174, v85, v85 quad_perm:[1,0,3,2] row_mask:0xf bank_mask:0xf bound_ctrl:1
	v_add_f32_dpp v241, v90, v90 quad_perm:[1,0,3,2] row_mask:0xf bank_mask:0xf bound_ctrl:1
	v_add_f32_dpp v247, v95, v95 quad_perm:[1,0,3,2] row_mask:0xf bank_mask:0xf bound_ctrl:1
	v_add_f32_dpp v168, v168, v168 quad_perm:[2,3,0,1] row_mask:0xf bank_mask:0xf bound_ctrl:1
	v_add_f32_dpp v174, v174, v174 quad_perm:[2,3,0,1] row_mask:0xf bank_mask:0xf bound_ctrl:1
	v_add_f32_dpp v241, v241, v241 quad_perm:[2,3,0,1] row_mask:0xf bank_mask:0xf bound_ctrl:1
	v_add_f32_dpp v247, v247, v247 quad_perm:[2,3,0,1] row_mask:0xf bank_mask:0xf bound_ctrl:1
	v_add_f32_dpp v168, v168, v168 row_half_mirror row_mask:0xf bank_mask:0xf bound_ctrl:1
	v_add_f32_dpp v174, v174, v174 row_half_mirror row_mask:0xf bank_mask:0xf bound_ctrl:1
	v_add_f32_dpp v241, v241, v241 row_half_mirror row_mask:0xf bank_mask:0xf bound_ctrl:1
	v_add_f32_dpp v247, v247, v247 row_half_mirror row_mask:0xf bank_mask:0xf bound_ctrl:1
	v_add_f32_dpp v168, v168, v168 row_mirror row_mask:0xf bank_mask:0xf bound_ctrl:1
	v_add_f32_dpp v174, v174, v174 row_mirror row_mask:0xf bank_mask:0xf bound_ctrl:1
	v_add_f32_dpp v241, v241, v241 row_mirror row_mask:0xf bank_mask:0xf bound_ctrl:1
	v_add_f32_dpp v247, v247, v247 row_mirror row_mask:0xf bank_mask:0xf bound_ctrl:1
	v_readlane_b32 s36, v168, 16
	v_readlane_b32 s40, v174, 16
	v_readlane_b32 s44, v241, 16
	v_readlane_b32 s48, v247, 16
	v_readlane_b32 s37, v168, 48
	v_readlane_b32 s41, v174, 48
	v_readlane_b32 s45, v241, 48
	v_readlane_b32 s49, v247, 48
	v_readlane_b32 s38, v168, 0
	v_readlane_b32 s42, v174, 0
	v_readlane_b32 s46, v241, 0
	v_readlane_b32 s50, v247, 0
	v_readlane_b32 s39, v168, 32
	v_readlane_b32 s43, v174, 32
	v_readlane_b32 s47, v241, 32
	v_readlane_b32 s51, v247, 32
	v_mov_b32_e32 v168, s36
	v_mov_b32_e32 v174, s40
	v_mov_b32_e32 v241, s44
	v_mov_b32_e32 v247, s48
	v_mov_b32_e32 v169, s37
	v_mov_b32_e32 v175, s41
	v_mov_b32_e32 v242, s45
	v_mov_b32_e32 v248, s49
	v_add_f32_e32 v168, s38, v168
	v_add_f32_e32 v174, s42, v174
	v_add_f32_e32 v241, s46, v241
	v_add_f32_e32 v247, s50, v247
	v_add_f32_e32 v169, s39, v169
	v_add_f32_e32 v175, s43, v175
	v_add_f32_e32 v242, s47, v242
	v_add_f32_e32 v248, s51, v248
	v_add_f32_e32 v168, v168, v169
	v_add_f32_e32 v174, v174, v175
	v_add_f32_e32 v241, v241, v242
	v_add_f32_e32 v247, v247, v248
	v_fmamk_f32 v80, v168, 0xbc800000, v80
	v_fmamk_f32 v85, v174, 0xbc800000, v85
	v_fmamk_f32 v90, v241, 0xbc800000, v90
	v_fmamk_f32 v95, v247, 0xbc800000, v95
	v_mul_f32_e32 v168, v80, v80
	v_mul_f32_e32 v174, v85, v85
	v_mul_f32_e32 v241, v90, v90
	v_mul_f32_e32 v247, v95, v95
	v_mov_b32_dpp v168, v168 quad_perm:[1,0,3,2] row_mask:0xf bank_mask:0xf bound_ctrl:1
	v_mov_b32_dpp v174, v174 quad_perm:[1,0,3,2] row_mask:0xf bank_mask:0xf bound_ctrl:1
	v_mov_b32_dpp v241, v241 quad_perm:[1,0,3,2] row_mask:0xf bank_mask:0xf bound_ctrl:1
	v_mov_b32_dpp v247, v247 quad_perm:[1,0,3,2] row_mask:0xf bank_mask:0xf bound_ctrl:1
	v_fmac_f32_e32 v168, v80, v80
	v_fmac_f32_e32 v174, v85, v85
	v_fmac_f32_e32 v241, v90, v90
	v_fmac_f32_e32 v247, v95, v95
	v_add_f32_dpp v168, v168, v168 quad_perm:[2,3,0,1] row_mask:0xf bank_mask:0xf bound_ctrl:1
	v_add_f32_dpp v174, v174, v174 quad_perm:[2,3,0,1] row_mask:0xf bank_mask:0xf bound_ctrl:1
	v_add_f32_dpp v241, v241, v241 quad_perm:[2,3,0,1] row_mask:0xf bank_mask:0xf bound_ctrl:1
	v_add_f32_dpp v247, v247, v247 quad_perm:[2,3,0,1] row_mask:0xf bank_mask:0xf bound_ctrl:1
	v_add_f32_dpp v168, v168, v168 row_half_mirror row_mask:0xf bank_mask:0xf bound_ctrl:1
	v_add_f32_dpp v174, v174, v174 row_half_mirror row_mask:0xf bank_mask:0xf bound_ctrl:1
	v_add_f32_dpp v241, v241, v241 row_half_mirror row_mask:0xf bank_mask:0xf bound_ctrl:1
	v_add_f32_dpp v247, v247, v247 row_half_mirror row_mask:0xf bank_mask:0xf bound_ctrl:1
	v_add_f32_dpp v168, v168, v168 row_mirror row_mask:0xf bank_mask:0xf bound_ctrl:1
	v_add_f32_dpp v174, v174, v174 row_mirror row_mask:0xf bank_mask:0xf bound_ctrl:1
	v_add_f32_dpp v241, v241, v241 row_mirror row_mask:0xf bank_mask:0xf bound_ctrl:1
	v_add_f32_dpp v247, v247, v247 row_mirror row_mask:0xf bank_mask:0xf bound_ctrl:1
	v_readlane_b32 s36, v168, 16
	v_readlane_b32 s40, v174, 16
	v_readlane_b32 s44, v241, 16
	v_readlane_b32 s48, v247, 16
	v_readlane_b32 s37, v168, 48
	v_readlane_b32 s41, v174, 48
	v_readlane_b32 s45, v241, 48
	v_readlane_b32 s49, v247, 48
	v_readlane_b32 s38, v168, 0
	v_readlane_b32 s42, v174, 0
	v_readlane_b32 s46, v241, 0
	v_readlane_b32 s50, v247, 0
	v_readlane_b32 s39, v168, 32
; __device__ __forceinline__ float bf2f(bf16 x) { return __uint_as_float(((unsigned)x) << 16); }
; __device__ __forceinline__ unsigned f2bf(float f) { return cvt_pk_bf16(f, 0.f) & 0xffffu; }
; __device__ __forceinline__ void rw_post(Frame& F) {
;     ...
;                 const float mean = wsum(y[q]) * (1.f / 64.f); const float dv = y[q] - mean; const float var = wsum(dv * dv) * (1.f / 64.f);
;                 const float yn = dv * (1.f / sqrtf(var + 64e-5f)) * g_ + b_;
;                 OB[(size_t)row * DH + col] = (bf16)f2bf((yn + rk[q] * vv[q]) * bf2f(gg[q])); }
	v_readlane_b32 s43, v174, 32
	v_readlane_b32 s47, v241, 32
	v_readlane_b32 s51, v247, 32
	v_mov_b32_e32 v168, s36
	v_mov_b32_e32 v174, s40
	v_mov_b32_e32 v241, s44
	v_mov_b32_e32 v247, s48
	v_mov_b32_e32 v169, s37
	v_mov_b32_e32 v175, s41
	v_mov_b32_e32 v242, s45
	v_mov_b32_e32 v248, s49
	v_add_f32_e32 v168, s38, v168
	v_add_f32_e32 v174, s42, v174
	v_add_f32_e32 v241, s46, v241
	v_add_f32_e32 v247, s50, v247
	v_add_f32_e32 v169, s39, v169
	v_add_f32_e32 v175, s43, v175
	v_add_f32_e32 v242, s47, v242
	v_add_f32_e32 v248, s51, v248
	v_add_f32_e32 v168, v168, v169
	v_add_f32_e32 v174, v174, v175
	v_add_f32_e32 v241, v241, v242
	v_add_f32_e32 v247, v247, v248
	v_fmamk_f32 v168, v168, 0x3c800000, v9
	v_fmamk_f32 v174, v174, 0x3c800000, v9
	v_fmamk_f32 v241, v241, 0x3c800000, v9
	v_fmamk_f32 v247, v247, 0x3c800000, v9
	v_mul_f32_e32 v169, 0x4f800000, v168
	v_mul_f32_e32 v175, 0x4f800000, v174
	v_mul_f32_e32 v242, 0x4f800000, v241
	v_mul_f32_e32 v248, 0x4f800000, v247
	v_cmp_gt_f32_e64 s[52:53], s68, v168
	v_cmp_gt_f32_e64 s[54:55], s68, v174
	v_cmp_gt_f32_e64 s[56:57], s68, v241
	v_cmp_gt_f32_e64 s[58:59], s68, v247
	v_mov_b32_e32 v170, v168
	v_mov_b32_e32 v176, v174
	v_mov_b32_e32 v243, v241
	v_mov_b32_e32 v249, v247
	v_cndmask_b32_e64 v168, v170, v169, s[52:53]
	v_cndmask_b32_e64 v174, v176, v175, s[54:55]
	v_cndmask_b32_e64 v241, v243, v242, s[56:57]
	v_cndmask_b32_e64 v247, v249, v248, s[58:59]
	v_sqrt_f32_e32 v169, v168
	v_sqrt_f32_e32 v175, v174
	v_sqrt_f32_e32 v242, v241
	v_sqrt_f32_e32 v248, v247
	v_add_u32_e32 v170, -1, v169
	v_add_u32_e32 v176, -1, v175
	v_add_u32_e32 v243, -1, v242
	v_add_u32_e32 v249, -1, v248
	v_fma_f32 v171, -v170, v169, v168
	v_fma_f32 v177, -v176, v175, v174
	v_fma_f32 v244, -v243, v242, v241
	v_fma_f32 v250, -v249, v248, v247
	v_cmp_ge_f32_e64 s[60:61], 0, v171
	v_cmp_ge_f32_e64 s[62:63], 0, v177
	v_cmp_ge_f32_e64 s[64:65], 0, v244
	v_cmp_ge_f32_e64 s[66:67], 0, v250
	v_add_u32_e32 v171, 1, v169
	v_add_u32_e32 v177, 1, v175
	v_add_u32_e32 v244, 1, v242
	v_add_u32_e32 v250, 1, v248
	v_cndmask_b32_e64 v170, v169, v170, s[60:61]
	v_cndmask_b32_e64 v176, v175, v176, s[62:63]
	v_cndmask_b32_e64 v243, v242, v243, s[64:65]
	v_cndmask_b32_e64 v249, v248, v249, s[66:67]
	v_fma_f32 v169, -v171, v169, v168
	v_fma_f32 v175, -v177, v175, v174
	v_fma_f32 v242, -v244, v242, v241
	v_fma_f32 v248, -v250, v248, v247
	v_cmp_lt_f32_e64 s[60:61], 0, v169
	v_cmp_lt_f32_e64 s[62:63], 0, v175
	v_cmp_lt_f32_e64 s[64:65], 0, v242
	v_cmp_lt_f32_e64 s[66:67], 0, v248
	v_cndmask_b32_e64 v169, v170, v171, s[60:61]
	v_cndmask_b32_e64 v175, v176, v177, s[62:63]
	v_cndmask_b32_e64 v242, v243, v244, s[64:65]
	v_cndmask_b32_e64 v248, v249, v250, s[66:67]
	v_mul_f32_e32 v170, 0x37800000, v169
	v_mul_f32_e32 v176, 0x37800000, v175
	v_mul_f32_e32 v243, 0x37800000, v242
	v_mul_f32_e32 v249, 0x37800000, v248
	v_cndmask_b32_e64 v169, v169, v170, s[52:53]
	v_cndmask_b32_e64 v175, v175, v176, s[54:55]
	v_cndmask_b32_e64 v242, v242, v243, s[56:57]
	v_cndmask_b32_e64 v248, v248, v249, s[58:59]
	v_cmp_class_f32_e64 s[60:61], v168, v8
	v_cmp_class_f32_e64 s[62:63], v174, v8
	v_cmp_class_f32_e64 s[64:65], v241, v8
	v_cmp_class_f32_e64 s[66:67], v247, v8
	v_cndmask_b32_e64 v168, v169, v168, s[60:61]
	v_cndmask_b32_e64 v174, v175, v174, s[62:63]
	v_cndmask_b32_e64 v241, v242, v241, s[64:65]
	v_cndmask_b32_e64 v247, v248, v247, s[66:67]
	v_div_scale_f32 v169, s[60:61], v168, v168, 1.0
	v_rcp_f32_e32 v170, v169
	s_nop 0
	v_fma_f32 v171, -v169, v170, 1.0
	v_fmac_f32_e32 v170, v171, v170
	v_div_scale_f32 v171, vcc, 1.0, v168, 1.0
	v_mul_f32_e32 v172, v171, v170
	v_fma_f32 v173, -v169, v172, v171
	v_fmac_f32_e32 v172, v173, v170
	v_fma_f32 v169, -v169, v172, v171
	v_div_fmas_f32 v169, v169, v170, v172
	v_div_fixup_f32 v168, v169, v168, 1.0
	v_div_scale_f32 v175, s[62:63], v174, v174, 1.0
	v_rcp_f32_e32 v176, v175
	s_nop 0
	v_fma_f32 v177, -v175, v176, 1.0
	v_fmac_f32_e32 v176, v177, v176
	v_div_scale_f32 v177, vcc, 1.0, v174, 1.0
	v_mul_f32_e32 v236, v177, v176
	v_fma_f32 v237, -v175, v236, v177
	v_fmac_f32_e32 v236, v237, v176
	v_fma_f32 v175, -v175, v236, v177
	v_div_fmas_f32 v175, v175, v176, v236
	v_div_fixup_f32 v174, v175, v174, 1.0
	v_div_scale_f32 v242, s[64:65], v241, v241, 1.0
	v_rcp_f32_e32 v243, v242
	s_nop 0
	v_fma_f32 v244, -v242, v243, 1.0
	v_fmac_f32_e32 v243, v244, v243
	v_div_scale_f32 v244, vcc, 1.0, v241, 1.0
	v_mul_f32_e32 v245, v244, v243
	v_fma_f32 v246, -v242, v245, v244
	v_fmac_f32_e32 v245, v246, v243
	v_fma_f32 v242, -v242, v245, v244
	v_div_fmas_f32 v242, v242, v243, v245
	v_div_fixup_f32 v241, v242, v241, 1.0
	v_div_scale_f32 v248, s[66:67], v247, v247, 1.0
	v_rcp_f32_e32 v249, v248
	s_nop 0
	v_fma_f32 v250, -v248, v249, 1.0
	v_fmac_f32_e32 v249, v250, v249
	v_div_scale_f32 v250, vcc, 1.0, v247, 1.0
	v_mul_f32_e32 v251, v250, v249
	v_fma_f32 v252, -v248, v251, v250
	v_fmac_f32_e32 v251, v252, v249
	v_fma_f32 v248, -v248, v251, v250
	v_div_fmas_f32 v248, v248, v249, v251
	v_div_fixup_f32 v247, v248, v247, 1.0
	v_mul_f32_e32 v80, v80, v168
	v_mul_f32_e32 v85, v85, v174
	v_mul_f32_e32 v90, v90, v241
	v_mul_f32_e32 v95, v95, v247
	v_lshlrev_b32_e32 v83, 16, v83
	v_lshlrev_b32_e32 v88, 16, v88
	v_lshlrev_b32_e32 v93, 16, v93
	v_lshlrev_b32_e32 v98, 16, v98
	v_fma_f32 v80, v6, v80, v7
	v_fma_f32 v85, v6, v85, v7
	v_fma_f32 v90, v6, v90, v7
	v_fma_f32 v95, v6, v95, v7
	v_fmac_f32_e32 v80, s69, v81
	v_fmac_f32_e32 v85, s70, v86
	v_fmac_f32_e32 v90, s71, v91
	v_fmac_f32_e32 v95, s72, v96
	v_mul_f32_e32 v80, v80, v83
	v_mul_f32_e32 v85, v85, v88
	v_mul_f32_e32 v90, v90, v93
	v_mul_f32_e32 v95, v95, v98
	v_cvt_pk_bf16_f32 v169, v80, v80
; __device__ __forceinline__ float bf2f(bf16 x) { return __uint_as_float(((unsigned)x) << 16); }
; __device__ __forceinline__ unsigned f2bf(float f) { return cvt_pk_bf16(f, 0.f) & 0xffffu; }
; __device__ __forceinline__ float dpp_xor1(float x) { return __builtin_bit_cast(float, __builtin_amdgcn_update_dpp(0, __builtin_bit_cast(int, x), 0xB1, 0xF, 0xF, true)); }
; __device__ __forceinline__ float dpp_xor2(float x) { return __builtin_bit_cast(float, __builtin_amdgcn_update_dpp(0, __builtin_bit_cast(int, x), 0x4E, 0xF, 0xF, true)); }
; __device__ __forceinline__ float dpp_hmir(float x) { return __builtin_bit_cast(float, __builtin_amdgcn_update_dpp(0, __builtin_bit_cast(int, x), 0x141, 0xF, 0xF, true)); }
; __device__ __forceinline__ float dpp_mir(float x)  { return __builtin_bit_cast(float, __builtin_amdgcn_update_dpp(0, __builtin_bit_cast(int, x), 0x140, 0xF, 0xF, true)); }
; __device__ __forceinline__ float red16(float x) { x += dpp_xor1(x); x += dpp_xor2(x); x += dpp_hmir(x); x += dpp_mir(x); return x; }
; __device__ __forceinline__ float wsum(float x) {
;     x = red16(x); const int xi = __builtin_bit_cast(int, x);
;     const float r0 = __builtin_bit_cast(float, __builtin_amdgcn_readlane(xi, 0)), r1 = __builtin_bit_cast(float, __builtin_amdgcn_readlane(xi, 16));
;     const float r2 = __builtin_bit_cast(float, __builtin_amdgcn_readlane(xi, 32)), r3 = __builtin_bit_cast(float, __builtin_amdgcn_readlane(xi, 48));
;     return (r0 + r1) + (r2 + r3);
; __device__ __forceinline__ void rw_post(Frame& F) {
;     ...
;             for (int q = 0; q < 8; ++q) { const int row = rb0 + t0 + q;
;                 const float mean = wsum(y[q]) * (1.f / 64.f); const float dv = y[q] - mean; const float var = wsum(dv * dv) * (1.f / 64.f);
;                 const float yn = dv * (1.f / sqrtf(var + 64e-5f)) * g_ + b_;
;                 OB[(size_t)row * DH + col] = (bf16)f2bf((yn + rk[q] * vv[q]) * bf2f(gg[q])); }
	v_cvt_pk_bf16_f32 v175, v85, v85
	v_cvt_pk_bf16_f32 v242, v90, v90
	v_cvt_pk_bf16_f32 v248, v95, v95
	global_store_short v2, v169, s[28:29]
	s_add_u32 s28, s28, 0x1000
	s_addc_u32 s29, s29, 0
	global_store_short v2, v175, s[28:29]
	s_add_u32 s28, s28, 0x1000
	s_addc_u32 s29, s29, 0
	global_store_short v2, v242, s[28:29]
	s_add_u32 s28, s28, 0x1000
	s_addc_u32 s29, s29, 0
	global_store_short v2, v248, s[28:29]
	s_add_u32 s28, s28, 0x1000
	s_addc_u32 s29, s29, 0
	v_add_f32_e32 v100, v100, v72
	v_add_f32_e32 v105, v105, v73
	v_add_f32_e32 v110, v110, v74
	v_add_f32_e32 v115, v115, v75
	v_add_f32_dpp v168, v100, v100 quad_perm:[1,0,3,2] row_mask:0xf bank_mask:0xf bound_ctrl:1
	v_add_f32_dpp v174, v105, v105 quad_perm:[1,0,3,2] row_mask:0xf bank_mask:0xf bound_ctrl:1
	v_add_f32_dpp v241, v110, v110 quad_perm:[1,0,3,2] row_mask:0xf bank_mask:0xf bound_ctrl:1
	v_add_f32_dpp v247, v115, v115 quad_perm:[1,0,3,2] row_mask:0xf bank_mask:0xf bound_ctrl:1
	v_add_f32_dpp v168, v168, v168 quad_perm:[2,3,0,1] row_mask:0xf bank_mask:0xf bound_ctrl:1
	v_add_f32_dpp v174, v174, v174 quad_perm:[2,3,0,1] row_mask:0xf bank_mask:0xf bound_ctrl:1
	v_add_f32_dpp v241, v241, v241 quad_perm:[2,3,0,1] row_mask:0xf bank_mask:0xf bound_ctrl:1
	v_add_f32_dpp v247, v247, v247 quad_perm:[2,3,0,1] row_mask:0xf bank_mask:0xf bound_ctrl:1
	v_add_f32_dpp v168, v168, v168 row_half_mirror row_mask:0xf bank_mask:0xf bound_ctrl:1
	v_add_f32_dpp v174, v174, v174 row_half_mirror row_mask:0xf bank_mask:0xf bound_ctrl:1
	v_add_f32_dpp v241, v241, v241 row_half_mirror row_mask:0xf bank_mask:0xf bound_ctrl:1
	v_add_f32_dpp v247, v247, v247 row_half_mirror row_mask:0xf bank_mask:0xf bound_ctrl:1
	v_add_f32_dpp v168, v168, v168 row_mirror row_mask:0xf bank_mask:0xf bound_ctrl:1
	v_add_f32_dpp v174, v174, v174 row_mirror row_mask:0xf bank_mask:0xf bound_ctrl:1
	v_add_f32_dpp v241, v241, v241 row_mirror row_mask:0xf bank_mask:0xf bound_ctrl:1
	v_add_f32_dpp v247, v247, v247 row_mirror row_mask:0xf bank_mask:0xf bound_ctrl:1
	v_readlane_b32 s36, v168, 16
	v_readlane_b32 s40, v174, 16
	v_readlane_b32 s44, v241, 16
	v_readlane_b32 s48, v247, 16
	v_readlane_b32 s37, v168, 48
	v_readlane_b32 s41, v174, 48
	v_readlane_b32 s45, v241, 48
	v_readlane_b32 s49, v247, 48
	v_readlane_b32 s38, v168, 0
	v_readlane_b32 s42, v174, 0
	v_readlane_b32 s46, v241, 0
	v_readlane_b32 s50, v247, 0
	v_readlane_b32 s39, v168, 32
	v_readlane_b32 s43, v174, 32
	v_readlane_b32 s47, v241, 32
	v_readlane_b32 s51, v247, 32
	v_mov_b32_e32 v168, s36
	v_mov_b32_e32 v174, s40
	v_mov_b32_e32 v241, s44
	v_mov_b32_e32 v247, s48
	v_mov_b32_e32 v169, s37
	v_mov_b32_e32 v175, s41
	v_mov_b32_e32 v242, s45
	v_mov_b32_e32 v248, s49
	v_add_f32_e32 v168, s38, v168
	v_add_f32_e32 v174, s42, v174
	v_add_f32_e32 v241, s46, v241
	v_add_f32_e32 v247, s50, v247
	v_add_f32_e32 v169, s39, v169
	v_add_f32_e32 v175, s43, v175
	v_add_f32_e32 v242, s47, v242
	v_add_f32_e32 v248, s51, v248
	v_add_f32_e32 v168, v168, v169
	v_add_f32_e32 v174, v174, v175
	v_add_f32_e32 v241, v241, v242
	v_add_f32_e32 v247, v247, v248
	v_fmamk_f32 v100, v168, 0xbc800000, v100
	v_fmamk_f32 v105, v174, 0xbc800000, v105
	v_fmamk_f32 v110, v241, 0xbc800000, v110
	v_fmamk_f32 v115, v247, 0xbc800000, v115
	v_mul_f32_e32 v168, v100, v100
	v_mul_f32_e32 v174, v105, v105
	v_mul_f32_e32 v241, v110, v110
	v_mul_f32_e32 v247, v115, v115
	v_mov_b32_dpp v168, v168 quad_perm:[1,0,3,2] row_mask:0xf bank_mask:0xf bound_ctrl:1
	v_mov_b32_dpp v174, v174 quad_perm:[1,0,3,2] row_mask:0xf bank_mask:0xf bound_ctrl:1
	v_mov_b32_dpp v241, v241 quad_perm:[1,0,3,2] row_mask:0xf bank_mask:0xf bound_ctrl:1
	v_mov_b32_dpp v247, v247 quad_perm:[1,0,3,2] row_mask:0xf bank_mask:0xf bound_ctrl:1
	v_fmac_f32_e32 v168, v100, v100
	v_fmac_f32_e32 v174, v105, v105
	v_fmac_f32_e32 v241, v110, v110
	v_fmac_f32_e32 v247, v115, v115
	v_add_f32_dpp v168, v168, v168 quad_perm:[2,3,0,1] row_mask:0xf bank_mask:0xf bound_ctrl:1
	v_add_f32_dpp v174, v174, v174 quad_perm:[2,3,0,1] row_mask:0xf bank_mask:0xf bound_ctrl:1
	v_add_f32_dpp v241, v241, v241 quad_perm:[2,3,0,1] row_mask:0xf bank_mask:0xf bound_ctrl:1
	v_add_f32_dpp v247, v247, v247 quad_perm:[2,3,0,1] row_mask:0xf bank_mask:0xf bound_ctrl:1
	v_add_f32_dpp v168, v168, v168 row_half_mirror row_mask:0xf bank_mask:0xf bound_ctrl:1
	v_add_f32_dpp v174, v174, v174 row_half_mirror row_mask:0xf bank_mask:0xf bound_ctrl:1
	v_add_f32_dpp v241, v241, v241 row_half_mirror row_mask:0xf bank_mask:0xf bound_ctrl:1
	v_add_f32_dpp v247, v247, v247 row_half_mirror row_mask:0xf bank_mask:0xf bound_ctrl:1
	v_add_f32_dpp v168, v168, v168 row_mirror row_mask:0xf bank_mask:0xf bound_ctrl:1
	v_add_f32_dpp v174, v174, v174 row_mirror row_mask:0xf bank_mask:0xf bound_ctrl:1
	v_add_f32_dpp v241, v241, v241 row_mirror row_mask:0xf bank_mask:0xf bound_ctrl:1
	v_add_f32_dpp v247, v247, v247 row_mirror row_mask:0xf bank_mask:0xf bound_ctrl:1
	v_readlane_b32 s36, v168, 16
	v_readlane_b32 s40, v174, 16
	v_readlane_b32 s44, v241, 16
	v_readlane_b32 s48, v247, 16
	v_readlane_b32 s37, v168, 48
	v_readlane_b32 s41, v174, 48
	v_readlane_b32 s45, v241, 48
	v_readlane_b32 s49, v247, 48
	v_readlane_b32 s38, v168, 0
	v_readlane_b32 s42, v174, 0
	v_readlane_b32 s46, v241, 0
	v_readlane_b32 s50, v247, 0
	v_readlane_b32 s39, v168, 32
	v_readlane_b32 s43, v174, 32
	v_readlane_b32 s47, v241, 32
	v_readlane_b32 s51, v247, 32
	v_mov_b32_e32 v168, s36
	v_mov_b32_e32 v174, s40
	v_mov_b32_e32 v241, s44
	v_mov_b32_e32 v247, s48
	v_mov_b32_e32 v169, s37
	v_mov_b32_e32 v175, s41
	v_mov_b32_e32 v242, s45
	v_mov_b32_e32 v248, s49
	v_add_f32_e32 v168, s38, v168
	v_add_f32_e32 v174, s42, v174
	v_add_f32_e32 v241, s46, v241
; __device__ __forceinline__ float bf2f(bf16 x) { return __uint_as_float(((unsigned)x) << 16); }
; __device__ __forceinline__ unsigned f2bf(float f) { return cvt_pk_bf16(f, 0.f) & 0xffffu; }
; #define POST_LD(Y_, V_, G_, R_, C_, t) do { _Pragma("unroll") for (int q = 0; q < 8; ++q) { const size_t o_ = (size_t)((t) + q) * DH; Y_[q] = yp[o_]; V_[q] = vp[o_]; G_[q] = gp[o_]; R_[q] = rp[((t) + q) * 32]; C_[q] = cp[o_]; } } while (0)
; __device__ __forceinline__ void rw_post(Frame& F) {
;     ...
;         POST_LD(y, vv, gg, rk, cc, 0);
;         for (int t0 = 0; t0 < 64; t0 += 8) {
;             float ny[8], nv[8], nr[8], nc[8]; bf16 ng[8];
;             const int tn = t0 + 8 < 64 ? t0 + 8 : t0;
;             POST_LD(ny, nv, ng, nr, nc, tn);
;     ...
;             for (int q = 0; q < 8; ++q) { const int row = rb0 + t0 + q;
;                 const float mean = wsum(y[q]) * (1.f / 64.f); const float dv = y[q] - mean; const float var = wsum(dv * dv) * (1.f / 64.f);
;                 const float yn = dv * (1.f / sqrtf(var + 64e-5f)) * g_ + b_;
;                 OB[(size_t)row * DH + col] = (bf16)f2bf((yn + rk[q] * vv[q]) * bf2f(gg[q])); }
	v_add_f32_e32 v247, s50, v247
	v_add_f32_e32 v169, s39, v169
	v_add_f32_e32 v175, s43, v175
	v_add_f32_e32 v242, s47, v242
	v_add_f32_e32 v248, s51, v248
	v_add_f32_e32 v168, v168, v169
	v_add_f32_e32 v174, v174, v175
	v_add_f32_e32 v241, v241, v242
	v_add_f32_e32 v247, v247, v248
	v_fmamk_f32 v168, v168, 0x3c800000, v9
	v_fmamk_f32 v174, v174, 0x3c800000, v9
	v_fmamk_f32 v241, v241, 0x3c800000, v9
	v_fmamk_f32 v247, v247, 0x3c800000, v9
	v_mul_f32_e32 v169, 0x4f800000, v168
	v_mul_f32_e32 v175, 0x4f800000, v174
	v_mul_f32_e32 v242, 0x4f800000, v241
	v_mul_f32_e32 v248, 0x4f800000, v247
	v_cmp_gt_f32_e64 s[52:53], s68, v168
	v_cmp_gt_f32_e64 s[54:55], s68, v174
	v_cmp_gt_f32_e64 s[56:57], s68, v241
	v_cmp_gt_f32_e64 s[58:59], s68, v247
	v_mov_b32_e32 v170, v168
	v_mov_b32_e32 v176, v174
	v_mov_b32_e32 v243, v241
	v_mov_b32_e32 v249, v247
	v_cndmask_b32_e64 v168, v170, v169, s[52:53]
	v_cndmask_b32_e64 v174, v176, v175, s[54:55]
	v_cndmask_b32_e64 v241, v243, v242, s[56:57]
	v_cndmask_b32_e64 v247, v249, v248, s[58:59]
	v_sqrt_f32_e32 v169, v168
	v_sqrt_f32_e32 v175, v174
	v_sqrt_f32_e32 v242, v241
	v_sqrt_f32_e32 v248, v247
	v_add_u32_e32 v170, -1, v169
	v_add_u32_e32 v176, -1, v175
	v_add_u32_e32 v243, -1, v242
	v_add_u32_e32 v249, -1, v248
	v_fma_f32 v171, -v170, v169, v168
	v_fma_f32 v177, -v176, v175, v174
	v_fma_f32 v244, -v243, v242, v241
	v_fma_f32 v250, -v249, v248, v247
	v_cmp_ge_f32_e64 s[60:61], 0, v171
	v_cmp_ge_f32_e64 s[62:63], 0, v177
	v_cmp_ge_f32_e64 s[64:65], 0, v244
	v_cmp_ge_f32_e64 s[66:67], 0, v250
	v_add_u32_e32 v171, 1, v169
	v_add_u32_e32 v177, 1, v175
	v_add_u32_e32 v244, 1, v242
	v_add_u32_e32 v250, 1, v248
	v_cndmask_b32_e64 v170, v169, v170, s[60:61]
	v_cndmask_b32_e64 v176, v175, v176, s[62:63]
	v_cndmask_b32_e64 v243, v242, v243, s[64:65]
	v_cndmask_b32_e64 v249, v248, v249, s[66:67]
	v_fma_f32 v169, -v171, v169, v168
	v_fma_f32 v175, -v177, v175, v174
	v_fma_f32 v242, -v244, v242, v241
	v_fma_f32 v248, -v250, v248, v247
	v_cmp_lt_f32_e64 s[60:61], 0, v169
	v_cmp_lt_f32_e64 s[62:63], 0, v175
	v_cmp_lt_f32_e64 s[64:65], 0, v242
	v_cmp_lt_f32_e64 s[66:67], 0, v248
	v_cndmask_b32_e64 v169, v170, v171, s[60:61]
	v_cndmask_b32_e64 v175, v176, v177, s[62:63]
	v_cndmask_b32_e64 v242, v243, v244, s[64:65]
	v_cndmask_b32_e64 v248, v249, v250, s[66:67]
	v_mul_f32_e32 v170, 0x37800000, v169
	v_mul_f32_e32 v176, 0x37800000, v175
	v_mul_f32_e32 v243, 0x37800000, v242
	v_mul_f32_e32 v249, 0x37800000, v248
	v_cndmask_b32_e64 v169, v169, v170, s[52:53]
	v_cndmask_b32_e64 v175, v175, v176, s[54:55]
	v_cndmask_b32_e64 v242, v242, v243, s[56:57]
	v_cndmask_b32_e64 v248, v248, v249, s[58:59]
	v_cmp_class_f32_e64 s[60:61], v168, v8
	v_cmp_class_f32_e64 s[62:63], v174, v8
	v_cmp_class_f32_e64 s[64:65], v241, v8
	v_cmp_class_f32_e64 s[66:67], v247, v8
	v_cndmask_b32_e64 v168, v169, v168, s[60:61]
	v_cndmask_b32_e64 v174, v175, v174, s[62:63]
	v_cndmask_b32_e64 v241, v242, v241, s[64:65]
	v_cndmask_b32_e64 v247, v248, v247, s[66:67]
	v_div_scale_f32 v169, s[60:61], v168, v168, 1.0
	v_rcp_f32_e32 v170, v169
	s_nop 0
	v_fma_f32 v171, -v169, v170, 1.0
	v_fmac_f32_e32 v170, v171, v170
	v_div_scale_f32 v171, vcc, 1.0, v168, 1.0
	v_mul_f32_e32 v172, v171, v170
	v_fma_f32 v173, -v169, v172, v171
	v_fmac_f32_e32 v172, v173, v170
	v_fma_f32 v169, -v169, v172, v171
	v_div_fmas_f32 v169, v169, v170, v172
	v_div_fixup_f32 v168, v169, v168, 1.0
	v_div_scale_f32 v175, s[62:63], v174, v174, 1.0
	v_rcp_f32_e32 v176, v175
	s_nop 0
	v_fma_f32 v177, -v175, v176, 1.0
	v_fmac_f32_e32 v176, v177, v176
	v_div_scale_f32 v177, vcc, 1.0, v174, 1.0
	v_mul_f32_e32 v236, v177, v176
	v_fma_f32 v237, -v175, v236, v177
	v_fmac_f32_e32 v236, v237, v176
	v_fma_f32 v175, -v175, v236, v177
	v_div_fmas_f32 v175, v175, v176, v236
	v_div_fixup_f32 v174, v175, v174, 1.0
	v_div_scale_f32 v242, s[64:65], v241, v241, 1.0
	v_rcp_f32_e32 v243, v242
	s_nop 0
	v_fma_f32 v244, -v242, v243, 1.0
	v_fmac_f32_e32 v243, v244, v243
	v_div_scale_f32 v244, vcc, 1.0, v241, 1.0
	v_mul_f32_e32 v245, v244, v243
	v_fma_f32 v246, -v242, v245, v244
	v_fmac_f32_e32 v245, v246, v243
	v_fma_f32 v242, -v242, v245, v244
	v_div_fmas_f32 v242, v242, v243, v245
	v_div_fixup_f32 v241, v242, v241, 1.0
	v_div_scale_f32 v248, s[66:67], v247, v247, 1.0
	v_rcp_f32_e32 v249, v248
	s_nop 0
	v_fma_f32 v250, -v248, v249, 1.0
	v_fmac_f32_e32 v249, v250, v249
	v_div_scale_f32 v250, vcc, 1.0, v247, 1.0
	v_mul_f32_e32 v251, v250, v249
	v_fma_f32 v252, -v248, v251, v250
	v_fmac_f32_e32 v251, v252, v249
	v_fma_f32 v248, -v248, v251, v250
	v_div_fmas_f32 v248, v248, v249, v251
	v_div_fixup_f32 v247, v248, v247, 1.0
	v_mul_f32_e32 v100, v100, v168
	v_mul_f32_e32 v105, v105, v174
	v_mul_f32_e32 v110, v110, v241
	v_mul_f32_e32 v115, v115, v247
	v_lshlrev_b32_e32 v103, 16, v103
	v_lshlrev_b32_e32 v108, 16, v108
	v_lshlrev_b32_e32 v113, 16, v113
	v_lshlrev_b32_e32 v118, 16, v118
	v_fma_f32 v100, v6, v100, v7
	v_fma_f32 v105, v6, v105, v7
	v_fma_f32 v110, v6, v110, v7
	v_fma_f32 v115, v6, v115, v7
	v_fmac_f32_e32 v100, s73, v101
	v_fmac_f32_e32 v105, s26, v106
	v_fmac_f32_e32 v110, s27, v111
	v_fmac_f32_e32 v115, s32, v116
	v_mul_f32_e32 v100, v100, v103
	v_mul_f32_e32 v105, v105, v108
	v_mul_f32_e32 v110, v110, v113
	v_mul_f32_e32 v115, v115, v118
	v_cvt_pk_bf16_f32 v169, v100, v100
	v_cvt_pk_bf16_f32 v175, v105, v105
	v_cvt_pk_bf16_f32 v242, v110, v110
	v_cvt_pk_bf16_f32 v248, v115, v115
	global_store_short v2, v169, s[28:29]
	s_add_u32 s28, s28, 0x1000
	s_addc_u32 s29, s29, 0
	global_store_short v2, v175, s[28:29]
	s_add_u32 s28, s28, 0x1000
	s_addc_u32 s29, s29, 0
	global_store_short v2, v242, s[28:29]
	s_add_u32 s28, s28, 0x1000
	s_addc_u32 s29, s29, 0
	global_store_short v2, v248, s[28:29]
	s_add_u32 s28, s28, 0x1000
	s_addc_u32 s29, s29, 0
	s_waitcnt vmcnt(8)
	ds_write_b128 v13, v[120:123] offset:0
	ds_write_b128 v13, v[124:127] offset:1024
	ds_write_b128 v13, v[128:131] offset:16384
	ds_write_b128 v13, v[132:135] offset:17408
	ds_write_b128 v15, v[136:139]
	v_readlane_b32 s69, v159, 0
	v_readlane_b32 s70, v159, 1
	v_readlane_b32 s71, v159, 2
	v_readlane_b32 s72, v159, 3
	v_readlane_b32 s73, v159, 4
	v_readlane_b32 s26, v159, 5
	v_readlane_b32 s27, v159, 6
	v_readlane_b32 s32, v159, 7
	s_waitcnt lgkmcnt(0)
	s_barrier
; __device__ __forceinline__ float dpp_xor1(float x) { return __builtin_bit_cast(float, __builtin_amdgcn_update_dpp(0, __builtin_bit_cast(int, x), 0xB1, 0xF, 0xF, true)); }
; __device__ __forceinline__ float dpp_xor2(float x) { return __builtin_bit_cast(float, __builtin_amdgcn_update_dpp(0, __builtin_bit_cast(int, x), 0x4E, 0xF, 0xF, true)); }
; __device__ __forceinline__ float dpp_hmir(float x) { return __builtin_bit_cast(float, __builtin_amdgcn_update_dpp(0, __builtin_bit_cast(int, x), 0x141, 0xF, 0xF, true)); }
; __device__ __forceinline__ float dpp_mir(float x)  { return __builtin_bit_cast(float, __builtin_amdgcn_update_dpp(0, __builtin_bit_cast(int, x), 0x140, 0xF, 0xF, true)); }
; __device__ __forceinline__ float red16(float x) { x += dpp_xor1(x); x += dpp_xor2(x); x += dpp_hmir(x); x += dpp_mir(x); return x; }
; __device__ __forceinline__ float wsum(float x) {
;     x = red16(x); const int xi = __builtin_bit_cast(int, x);
;     const float r0 = __builtin_bit_cast(float, __builtin_amdgcn_readlane(xi, 0)), r1 = __builtin_bit_cast(float, __builtin_amdgcn_readlane(xi, 16));
;     const float r2 = __builtin_bit_cast(float, __builtin_amdgcn_readlane(xi, 32)), r3 = __builtin_bit_cast(float, __builtin_amdgcn_readlane(xi, 48));
;     return (r0 + r1) + (r2 + r3);
; __device__ __forceinline__ void rw_post(Frame& F) {
;     ...
;             for (int q = 0; q < 8; ++q) { const int row = rb0 + t0 + q;
;                 const float mean = wsum(y[q]) * (1.f / 64.f); const float dv = y[q] - mean; const float var = wsum(dv * dv) * (1.f / 64.f);
	ds_read_b32 v80, v155 offset:0
	ds_read_b32 v81, v155 offset:16384
	ds_read_u16 v83, v157 offset:0
	ds_read_b32 v85, v155 offset:2048
	ds_read_b32 v86, v155 offset:18432
	ds_read_u16 v88, v157 offset:1024
	ds_read_b32 v90, v155 offset:4096
	ds_read_b32 v91, v155 offset:20480
	ds_read_u16 v93, v157 offset:2048
	ds_read_b32 v95, v155 offset:6144
	ds_read_b32 v96, v155 offset:22528
	ds_read_u16 v98, v157 offset:3072
	ds_read_b32 v100, v155 offset:8192
	ds_read_b32 v101, v155 offset:24576
	ds_read_u16 v103, v157 offset:4096
	ds_read_b32 v105, v155 offset:10240
	ds_read_b32 v106, v155 offset:26624
	ds_read_u16 v108, v157 offset:5120
	ds_read_b32 v110, v155 offset:12288
	ds_read_b32 v111, v155 offset:28672
	ds_read_u16 v113, v157 offset:6144
	ds_read_b32 v115, v155 offset:14336
	ds_read_b32 v116, v155 offset:30720
	ds_read_u16 v118, v157 offset:7168
	s_waitcnt lgkmcnt(0)
	v_add_f32_e32 v80, v80, v60
	v_add_f32_e32 v85, v85, v61
	v_add_f32_e32 v90, v90, v62
	v_add_f32_e32 v95, v95, v63
	v_add_f32_dpp v168, v80, v80 quad_perm:[1,0,3,2] row_mask:0xf bank_mask:0xf bound_ctrl:1
	v_add_f32_dpp v174, v85, v85 quad_perm:[1,0,3,2] row_mask:0xf bank_mask:0xf bound_ctrl:1
	v_add_f32_dpp v241, v90, v90 quad_perm:[1,0,3,2] row_mask:0xf bank_mask:0xf bound_ctrl:1
	v_add_f32_dpp v247, v95, v95 quad_perm:[1,0,3,2] row_mask:0xf bank_mask:0xf bound_ctrl:1
	v_add_f32_dpp v168, v168, v168 quad_perm:[2,3,0,1] row_mask:0xf bank_mask:0xf bound_ctrl:1
	v_add_f32_dpp v174, v174, v174 quad_perm:[2,3,0,1] row_mask:0xf bank_mask:0xf bound_ctrl:1
	v_add_f32_dpp v241, v241, v241 quad_perm:[2,3,0,1] row_mask:0xf bank_mask:0xf bound_ctrl:1
	v_add_f32_dpp v247, v247, v247 quad_perm:[2,3,0,1] row_mask:0xf bank_mask:0xf bound_ctrl:1
	v_add_f32_dpp v168, v168, v168 row_half_mirror row_mask:0xf bank_mask:0xf bound_ctrl:1
	v_add_f32_dpp v174, v174, v174 row_half_mirror row_mask:0xf bank_mask:0xf bound_ctrl:1
	v_add_f32_dpp v241, v241, v241 row_half_mirror row_mask:0xf bank_mask:0xf bound_ctrl:1
	v_add_f32_dpp v247, v247, v247 row_half_mirror row_mask:0xf bank_mask:0xf bound_ctrl:1
	v_add_f32_dpp v168, v168, v168 row_mirror row_mask:0xf bank_mask:0xf bound_ctrl:1
	v_add_f32_dpp v174, v174, v174 row_mirror row_mask:0xf bank_mask:0xf bound_ctrl:1
	v_add_f32_dpp v241, v241, v241 row_mirror row_mask:0xf bank_mask:0xf bound_ctrl:1
	v_add_f32_dpp v247, v247, v247 row_mirror row_mask:0xf bank_mask:0xf bound_ctrl:1
	v_readlane_b32 s36, v168, 16
	v_readlane_b32 s40, v174, 16
	v_readlane_b32 s44, v241, 16
	v_readlane_b32 s48, v247, 16
	v_readlane_b32 s37, v168, 48
	v_readlane_b32 s41, v174, 48
	v_readlane_b32 s45, v241, 48
	v_readlane_b32 s49, v247, 48
	v_readlane_b32 s38, v168, 0
	v_readlane_b32 s42, v174, 0
	v_readlane_b32 s46, v241, 0
	v_readlane_b32 s50, v247, 0
	v_readlane_b32 s39, v168, 32
	v_readlane_b32 s43, v174, 32
	v_readlane_b32 s47, v241, 32
	v_readlane_b32 s51, v247, 32
	v_mov_b32_e32 v168, s36
	v_mov_b32_e32 v174, s40
	v_mov_b32_e32 v241, s44
	v_mov_b32_e32 v247, s48
	v_mov_b32_e32 v169, s37
	v_mov_b32_e32 v175, s41
	v_mov_b32_e32 v242, s45
	v_mov_b32_e32 v248, s49
	v_add_f32_e32 v168, s38, v168
	v_add_f32_e32 v174, s42, v174
	v_add_f32_e32 v241, s46, v241
	v_add_f32_e32 v247, s50, v247
	v_add_f32_e32 v169, s39, v169
	v_add_f32_e32 v175, s43, v175
	v_add_f32_e32 v242, s47, v242
	v_add_f32_e32 v248, s51, v248
	v_add_f32_e32 v168, v168, v169
	v_add_f32_e32 v174, v174, v175
	v_add_f32_e32 v241, v241, v242
	v_add_f32_e32 v247, v247, v248
	v_fmamk_f32 v80, v168, 0xbc800000, v80
	v_fmamk_f32 v85, v174, 0xbc800000, v85
	v_fmamk_f32 v90, v241, 0xbc800000, v90
	v_fmamk_f32 v95, v247, 0xbc800000, v95
	v_mul_f32_e32 v168, v80, v80
	v_mul_f32_e32 v174, v85, v85
	v_mul_f32_e32 v241, v90, v90
	v_mul_f32_e32 v247, v95, v95
	v_mov_b32_dpp v168, v168 quad_perm:[1,0,3,2] row_mask:0xf bank_mask:0xf bound_ctrl:1
	v_mov_b32_dpp v174, v174 quad_perm:[1,0,3,2] row_mask:0xf bank_mask:0xf bound_ctrl:1
	v_mov_b32_dpp v241, v241 quad_perm:[1,0,3,2] row_mask:0xf bank_mask:0xf bound_ctrl:1
	v_mov_b32_dpp v247, v247 quad_perm:[1,0,3,2] row_mask:0xf bank_mask:0xf bound_ctrl:1
	v_fmac_f32_e32 v168, v80, v80
	v_fmac_f32_e32 v174, v85, v85
	v_fmac_f32_e32 v241, v90, v90
	v_fmac_f32_e32 v247, v95, v95
	v_add_f32_dpp v168, v168, v168 quad_perm:[2,3,0,1] row_mask:0xf bank_mask:0xf bound_ctrl:1
	v_add_f32_dpp v174, v174, v174 quad_perm:[2,3,0,1] row_mask:0xf bank_mask:0xf bound_ctrl:1
	v_add_f32_dpp v241, v241, v241 quad_perm:[2,3,0,1] row_mask:0xf bank_mask:0xf bound_ctrl:1
	v_add_f32_dpp v247, v247, v247 quad_perm:[2,3,0,1] row_mask:0xf bank_mask:0xf bound_ctrl:1
	v_add_f32_dpp v168, v168, v168 row_half_mirror row_mask:0xf bank_mask:0xf bound_ctrl:1
	v_add_f32_dpp v174, v174, v174 row_half_mirror row_mask:0xf bank_mask:0xf bound_ctrl:1
	v_add_f32_dpp v241, v241, v241 row_half_mirror row_mask:0xf bank_mask:0xf bound_ctrl:1
	v_add_f32_dpp v247, v247, v247 row_half_mirror row_mask:0xf bank_mask:0xf bound_ctrl:1
	v_add_f32_dpp v168, v168, v168 row_mirror row_mask:0xf bank_mask:0xf bound_ctrl:1
	v_add_f32_dpp v174, v174, v174 row_mirror row_mask:0xf bank_mask:0xf bound_ctrl:1
	v_add_f32_dpp v241, v241, v241 row_mirror row_mask:0xf bank_mask:0xf bound_ctrl:1
	v_add_f32_dpp v247, v247, v247 row_mirror row_mask:0xf bank_mask:0xf bound_ctrl:1
	v_readlane_b32 s36, v168, 16
	v_readlane_b32 s40, v174, 16
	v_readlane_b32 s44, v241, 16
	v_readlane_b32 s48, v247, 16
	v_readlane_b32 s37, v168, 48
	v_readlane_b32 s41, v174, 48
	v_readlane_b32 s45, v241, 48
	v_readlane_b32 s49, v247, 48
	v_readlane_b32 s38, v168, 0
	v_readlane_b32 s42, v174, 0
	v_readlane_b32 s46, v241, 0
	v_readlane_b32 s50, v247, 0
	v_readlane_b32 s39, v168, 32
; __device__ __forceinline__ float bf2f(bf16 x) { return __uint_as_float(((unsigned)x) << 16); }
; __device__ __forceinline__ unsigned f2bf(float f) { return cvt_pk_bf16(f, 0.f) & 0xffffu; }
; __device__ __forceinline__ void rw_post(Frame& F) {
;     ...
;                 const float mean = wsum(y[q]) * (1.f / 64.f); const float dv = y[q] - mean; const float var = wsum(dv * dv) * (1.f / 64.f);
;                 const float yn = dv * (1.f / sqrtf(var + 64e-5f)) * g_ + b_;
;                 OB[(size_t)row * DH + col] = (bf16)f2bf((yn + rk[q] * vv[q]) * bf2f(gg[q])); }
	v_readlane_b32 s43, v174, 32
	v_readlane_b32 s47, v241, 32
	v_readlane_b32 s51, v247, 32
	v_mov_b32_e32 v168, s36
	v_mov_b32_e32 v174, s40
	v_mov_b32_e32 v241, s44
	v_mov_b32_e32 v247, s48
	v_mov_b32_e32 v169, s37
	v_mov_b32_e32 v175, s41
	v_mov_b32_e32 v242, s45
	v_mov_b32_e32 v248, s49
	v_add_f32_e32 v168, s38, v168
	v_add_f32_e32 v174, s42, v174
	v_add_f32_e32 v241, s46, v241
	v_add_f32_e32 v247, s50, v247
	v_add_f32_e32 v169, s39, v169
	v_add_f32_e32 v175, s43, v175
	v_add_f32_e32 v242, s47, v242
	v_add_f32_e32 v248, s51, v248
	v_add_f32_e32 v168, v168, v169
	v_add_f32_e32 v174, v174, v175
	v_add_f32_e32 v241, v241, v242
	v_add_f32_e32 v247, v247, v248
	v_fmamk_f32 v168, v168, 0x3c800000, v9
	v_fmamk_f32 v174, v174, 0x3c800000, v9
	v_fmamk_f32 v241, v241, 0x3c800000, v9
	v_fmamk_f32 v247, v247, 0x3c800000, v9
	v_mul_f32_e32 v169, 0x4f800000, v168
	v_mul_f32_e32 v175, 0x4f800000, v174
	v_mul_f32_e32 v242, 0x4f800000, v241
	v_mul_f32_e32 v248, 0x4f800000, v247
	v_cmp_gt_f32_e64 s[52:53], s68, v168
	v_cmp_gt_f32_e64 s[54:55], s68, v174
	v_cmp_gt_f32_e64 s[56:57], s68, v241
	v_cmp_gt_f32_e64 s[58:59], s68, v247
	v_mov_b32_e32 v170, v168
	v_mov_b32_e32 v176, v174
	v_mov_b32_e32 v243, v241
	v_mov_b32_e32 v249, v247
	v_cndmask_b32_e64 v168, v170, v169, s[52:53]
	v_cndmask_b32_e64 v174, v176, v175, s[54:55]
	v_cndmask_b32_e64 v241, v243, v242, s[56:57]
	v_cndmask_b32_e64 v247, v249, v248, s[58:59]
	v_sqrt_f32_e32 v169, v168
	v_sqrt_f32_e32 v175, v174
	v_sqrt_f32_e32 v242, v241
	v_sqrt_f32_e32 v248, v247
	v_add_u32_e32 v170, -1, v169
	v_add_u32_e32 v176, -1, v175
	v_add_u32_e32 v243, -1, v242
	v_add_u32_e32 v249, -1, v248
	v_fma_f32 v171, -v170, v169, v168
	v_fma_f32 v177, -v176, v175, v174
	v_fma_f32 v244, -v243, v242, v241
	v_fma_f32 v250, -v249, v248, v247
	v_cmp_ge_f32_e64 s[60:61], 0, v171
	v_cmp_ge_f32_e64 s[62:63], 0, v177
	v_cmp_ge_f32_e64 s[64:65], 0, v244
	v_cmp_ge_f32_e64 s[66:67], 0, v250
	v_add_u32_e32 v171, 1, v169
	v_add_u32_e32 v177, 1, v175
	v_add_u32_e32 v244, 1, v242
	v_add_u32_e32 v250, 1, v248
	v_cndmask_b32_e64 v170, v169, v170, s[60:61]
	v_cndmask_b32_e64 v176, v175, v176, s[62:63]
	v_cndmask_b32_e64 v243, v242, v243, s[64:65]
	v_cndmask_b32_e64 v249, v248, v249, s[66:67]
	v_fma_f32 v169, -v171, v169, v168
	v_fma_f32 v175, -v177, v175, v174
	v_fma_f32 v242, -v244, v242, v241
	v_fma_f32 v248, -v250, v248, v247
	v_cmp_lt_f32_e64 s[60:61], 0, v169
	v_cmp_lt_f32_e64 s[62:63], 0, v175
	v_cmp_lt_f32_e64 s[64:65], 0, v242
	v_cmp_lt_f32_e64 s[66:67], 0, v248
	v_cndmask_b32_e64 v169, v170, v171, s[60:61]
	v_cndmask_b32_e64 v175, v176, v177, s[62:63]
	v_cndmask_b32_e64 v242, v243, v244, s[64:65]
	v_cndmask_b32_e64 v248, v249, v250, s[66:67]
	v_mul_f32_e32 v170, 0x37800000, v169
	v_mul_f32_e32 v176, 0x37800000, v175
	v_mul_f32_e32 v243, 0x37800000, v242
	v_mul_f32_e32 v249, 0x37800000, v248
	v_cndmask_b32_e64 v169, v169, v170, s[52:53]
	v_cndmask_b32_e64 v175, v175, v176, s[54:55]
	v_cndmask_b32_e64 v242, v242, v243, s[56:57]
	v_cndmask_b32_e64 v248, v248, v249, s[58:59]
	v_cmp_class_f32_e64 s[60:61], v168, v8
	v_cmp_class_f32_e64 s[62:63], v174, v8
	v_cmp_class_f32_e64 s[64:65], v241, v8
	v_cmp_class_f32_e64 s[66:67], v247, v8
	v_cndmask_b32_e64 v168, v169, v168, s[60:61]
	v_cndmask_b32_e64 v174, v175, v174, s[62:63]
	v_cndmask_b32_e64 v241, v242, v241, s[64:65]
	v_cndmask_b32_e64 v247, v248, v247, s[66:67]
	v_div_scale_f32 v169, s[60:61], v168, v168, 1.0
	v_rcp_f32_e32 v170, v169
	s_nop 0
	v_fma_f32 v171, -v169, v170, 1.0
	v_fmac_f32_e32 v170, v171, v170
	v_div_scale_f32 v171, vcc, 1.0, v168, 1.0
	v_mul_f32_e32 v172, v171, v170
	v_fma_f32 v173, -v169, v172, v171
	v_fmac_f32_e32 v172, v173, v170
	v_fma_f32 v169, -v169, v172, v171
	v_div_fmas_f32 v169, v169, v170, v172
	v_div_fixup_f32 v168, v169, v168, 1.0
	v_div_scale_f32 v175, s[62:63], v174, v174, 1.0
	v_rcp_f32_e32 v176, v175
	s_nop 0
	v_fma_f32 v177, -v175, v176, 1.0
	v_fmac_f32_e32 v176, v177, v176
	v_div_scale_f32 v177, vcc, 1.0, v174, 1.0
	v_mul_f32_e32 v236, v177, v176
	v_fma_f32 v237, -v175, v236, v177
	v_fmac_f32_e32 v236, v237, v176
	v_fma_f32 v175, -v175, v236, v177
	v_div_fmas_f32 v175, v175, v176, v236
	v_div_fixup_f32 v174, v175, v174, 1.0
	v_div_scale_f32 v242, s[64:65], v241, v241, 1.0
	v_rcp_f32_e32 v243, v242
	s_nop 0
	v_fma_f32 v244, -v242, v243, 1.0
	v_fmac_f32_e32 v243, v244, v243
	v_div_scale_f32 v244, vcc, 1.0, v241, 1.0
	v_mul_f32_e32 v245, v244, v243
	v_fma_f32 v246, -v242, v245, v244
	v_fmac_f32_e32 v245, v246, v243
	v_fma_f32 v242, -v242, v245, v244
	v_div_fmas_f32 v242, v242, v243, v245
	v_div_fixup_f32 v241, v242, v241, 1.0
	v_div_scale_f32 v248, s[66:67], v247, v247, 1.0
	v_rcp_f32_e32 v249, v248
	s_nop 0
	v_fma_f32 v250, -v248, v249, 1.0
	v_fmac_f32_e32 v249, v250, v249
	v_div_scale_f32 v250, vcc, 1.0, v247, 1.0
	v_mul_f32_e32 v251, v250, v249
	v_fma_f32 v252, -v248, v251, v250
	v_fmac_f32_e32 v251, v252, v249
	v_fma_f32 v248, -v248, v251, v250
	v_div_fmas_f32 v248, v248, v249, v251
	v_div_fixup_f32 v247, v248, v247, 1.0
	v_mul_f32_e32 v80, v80, v168
	v_mul_f32_e32 v85, v85, v174
	v_mul_f32_e32 v90, v90, v241
	v_mul_f32_e32 v95, v95, v247
	v_lshlrev_b32_e32 v83, 16, v83
	v_lshlrev_b32_e32 v88, 16, v88
	v_lshlrev_b32_e32 v93, 16, v93
	v_lshlrev_b32_e32 v98, 16, v98
	v_fma_f32 v80, v6, v80, v7
	v_fma_f32 v85, v6, v85, v7
	v_fma_f32 v90, v6, v90, v7
	v_fma_f32 v95, v6, v95, v7
	v_fmac_f32_e32 v80, s69, v81
	v_fmac_f32_e32 v85, s70, v86
	v_fmac_f32_e32 v90, s71, v91
	v_fmac_f32_e32 v95, s72, v96
	v_mul_f32_e32 v80, v80, v83
	v_mul_f32_e32 v85, v85, v88
	v_mul_f32_e32 v90, v90, v93
	v_mul_f32_e32 v95, v95, v98
	v_cvt_pk_bf16_f32 v169, v80, v80
; __device__ __forceinline__ float bf2f(bf16 x) { return __uint_as_float(((unsigned)x) << 16); }
; __device__ __forceinline__ unsigned f2bf(float f) { return cvt_pk_bf16(f, 0.f) & 0xffffu; }
; __device__ __forceinline__ float dpp_xor1(float x) { return __builtin_bit_cast(float, __builtin_amdgcn_update_dpp(0, __builtin_bit_cast(int, x), 0xB1, 0xF, 0xF, true)); }
; __device__ __forceinline__ float dpp_xor2(float x) { return __builtin_bit_cast(float, __builtin_amdgcn_update_dpp(0, __builtin_bit_cast(int, x), 0x4E, 0xF, 0xF, true)); }
; __device__ __forceinline__ float dpp_hmir(float x) { return __builtin_bit_cast(float, __builtin_amdgcn_update_dpp(0, __builtin_bit_cast(int, x), 0x141, 0xF, 0xF, true)); }
; __device__ __forceinline__ float dpp_mir(float x)  { return __builtin_bit_cast(float, __builtin_amdgcn_update_dpp(0, __builtin_bit_cast(int, x), 0x140, 0xF, 0xF, true)); }
; __device__ __forceinline__ float red16(float x) { x += dpp_xor1(x); x += dpp_xor2(x); x += dpp_hmir(x); x += dpp_mir(x); return x; }
; __device__ __forceinline__ float wsum(float x) {
;     x = red16(x); const int xi = __builtin_bit_cast(int, x);
;     const float r0 = __builtin_bit_cast(float, __builtin_amdgcn_readlane(xi, 0)), r1 = __builtin_bit_cast(float, __builtin_amdgcn_readlane(xi, 16));
;     const float r2 = __builtin_bit_cast(float, __builtin_amdgcn_readlane(xi, 32)), r3 = __builtin_bit_cast(float, __builtin_amdgcn_readlane(xi, 48));
;     return (r0 + r1) + (r2 + r3);
; __device__ __forceinline__ void rw_post(Frame& F) {
;     ...
;             for (int q = 0; q < 8; ++q) { const int row = rb0 + t0 + q;
;                 const float mean = wsum(y[q]) * (1.f / 64.f); const float dv = y[q] - mean; const float var = wsum(dv * dv) * (1.f / 64.f);
;                 const float yn = dv * (1.f / sqrtf(var + 64e-5f)) * g_ + b_;
;                 OB[(size_t)row * DH + col] = (bf16)f2bf((yn + rk[q] * vv[q]) * bf2f(gg[q])); }
	v_cvt_pk_bf16_f32 v175, v85, v85
	v_cvt_pk_bf16_f32 v242, v90, v90
	v_cvt_pk_bf16_f32 v248, v95, v95
	global_store_short v2, v169, s[28:29]
	s_add_u32 s28, s28, 0x1000
	s_addc_u32 s29, s29, 0
	global_store_short v2, v175, s[28:29]
	s_add_u32 s28, s28, 0x1000
	s_addc_u32 s29, s29, 0
	global_store_short v2, v242, s[28:29]
	s_add_u32 s28, s28, 0x1000
	s_addc_u32 s29, s29, 0
	global_store_short v2, v248, s[28:29]
	s_add_u32 s28, s28, 0x1000
	s_addc_u32 s29, s29, 0
	v_add_f32_e32 v100, v100, v76
	v_add_f32_e32 v105, v105, v77
	v_add_f32_e32 v110, v110, v78
	v_add_f32_e32 v115, v115, v79
	v_add_f32_dpp v168, v100, v100 quad_perm:[1,0,3,2] row_mask:0xf bank_mask:0xf bound_ctrl:1
	v_add_f32_dpp v174, v105, v105 quad_perm:[1,0,3,2] row_mask:0xf bank_mask:0xf bound_ctrl:1
	v_add_f32_dpp v241, v110, v110 quad_perm:[1,0,3,2] row_mask:0xf bank_mask:0xf bound_ctrl:1
	v_add_f32_dpp v247, v115, v115 quad_perm:[1,0,3,2] row_mask:0xf bank_mask:0xf bound_ctrl:1
	v_add_f32_dpp v168, v168, v168 quad_perm:[2,3,0,1] row_mask:0xf bank_mask:0xf bound_ctrl:1
	v_add_f32_dpp v174, v174, v174 quad_perm:[2,3,0,1] row_mask:0xf bank_mask:0xf bound_ctrl:1
	v_add_f32_dpp v241, v241, v241 quad_perm:[2,3,0,1] row_mask:0xf bank_mask:0xf bound_ctrl:1
	v_add_f32_dpp v247, v247, v247 quad_perm:[2,3,0,1] row_mask:0xf bank_mask:0xf bound_ctrl:1
	v_add_f32_dpp v168, v168, v168 row_half_mirror row_mask:0xf bank_mask:0xf bound_ctrl:1
	v_add_f32_dpp v174, v174, v174 row_half_mirror row_mask:0xf bank_mask:0xf bound_ctrl:1
	v_add_f32_dpp v241, v241, v241 row_half_mirror row_mask:0xf bank_mask:0xf bound_ctrl:1
	v_add_f32_dpp v247, v247, v247 row_half_mirror row_mask:0xf bank_mask:0xf bound_ctrl:1
	v_add_f32_dpp v168, v168, v168 row_mirror row_mask:0xf bank_mask:0xf bound_ctrl:1
	v_add_f32_dpp v174, v174, v174 row_mirror row_mask:0xf bank_mask:0xf bound_ctrl:1
	v_add_f32_dpp v241, v241, v241 row_mirror row_mask:0xf bank_mask:0xf bound_ctrl:1
	v_add_f32_dpp v247, v247, v247 row_mirror row_mask:0xf bank_mask:0xf bound_ctrl:1
	v_readlane_b32 s36, v168, 16
	v_readlane_b32 s40, v174, 16
	v_readlane_b32 s44, v241, 16
	v_readlane_b32 s48, v247, 16
	v_readlane_b32 s37, v168, 48
	v_readlane_b32 s41, v174, 48
	v_readlane_b32 s45, v241, 48
	v_readlane_b32 s49, v247, 48
	v_readlane_b32 s38, v168, 0
	v_readlane_b32 s42, v174, 0
	v_readlane_b32 s46, v241, 0
	v_readlane_b32 s50, v247, 0
	v_readlane_b32 s39, v168, 32
	v_readlane_b32 s43, v174, 32
	v_readlane_b32 s47, v241, 32
	v_readlane_b32 s51, v247, 32
	v_mov_b32_e32 v168, s36
	v_mov_b32_e32 v174, s40
	v_mov_b32_e32 v241, s44
	v_mov_b32_e32 v247, s48
	v_mov_b32_e32 v169, s37
	v_mov_b32_e32 v175, s41
	v_mov_b32_e32 v242, s45
	v_mov_b32_e32 v248, s49
	v_add_f32_e32 v168, s38, v168
	v_add_f32_e32 v174, s42, v174
	v_add_f32_e32 v241, s46, v241
	v_add_f32_e32 v247, s50, v247
	v_add_f32_e32 v169, s39, v169
	v_add_f32_e32 v175, s43, v175
	v_add_f32_e32 v242, s47, v242
	v_add_f32_e32 v248, s51, v248
	v_add_f32_e32 v168, v168, v169
	v_add_f32_e32 v174, v174, v175
	v_add_f32_e32 v241, v241, v242
	v_add_f32_e32 v247, v247, v248
	v_fmamk_f32 v100, v168, 0xbc800000, v100
	v_fmamk_f32 v105, v174, 0xbc800000, v105
	v_fmamk_f32 v110, v241, 0xbc800000, v110
	v_fmamk_f32 v115, v247, 0xbc800000, v115
	v_mul_f32_e32 v168, v100, v100
	v_mul_f32_e32 v174, v105, v105
	v_mul_f32_e32 v241, v110, v110
	v_mul_f32_e32 v247, v115, v115
	v_mov_b32_dpp v168, v168 quad_perm:[1,0,3,2] row_mask:0xf bank_mask:0xf bound_ctrl:1
	v_mov_b32_dpp v174, v174 quad_perm:[1,0,3,2] row_mask:0xf bank_mask:0xf bound_ctrl:1
	v_mov_b32_dpp v241, v241 quad_perm:[1,0,3,2] row_mask:0xf bank_mask:0xf bound_ctrl:1
	v_mov_b32_dpp v247, v247 quad_perm:[1,0,3,2] row_mask:0xf bank_mask:0xf bound_ctrl:1
	v_fmac_f32_e32 v168, v100, v100
	v_fmac_f32_e32 v174, v105, v105
	v_fmac_f32_e32 v241, v110, v110
	v_fmac_f32_e32 v247, v115, v115
	v_add_f32_dpp v168, v168, v168 quad_perm:[2,3,0,1] row_mask:0xf bank_mask:0xf bound_ctrl:1
	v_add_f32_dpp v174, v174, v174 quad_perm:[2,3,0,1] row_mask:0xf bank_mask:0xf bound_ctrl:1
	v_add_f32_dpp v241, v241, v241 quad_perm:[2,3,0,1] row_mask:0xf bank_mask:0xf bound_ctrl:1
	v_add_f32_dpp v247, v247, v247 quad_perm:[2,3,0,1] row_mask:0xf bank_mask:0xf bound_ctrl:1
	v_add_f32_dpp v168, v168, v168 row_half_mirror row_mask:0xf bank_mask:0xf bound_ctrl:1
	v_add_f32_dpp v174, v174, v174 row_half_mirror row_mask:0xf bank_mask:0xf bound_ctrl:1
	v_add_f32_dpp v241, v241, v241 row_half_mirror row_mask:0xf bank_mask:0xf bound_ctrl:1
	v_add_f32_dpp v247, v247, v247 row_half_mirror row_mask:0xf bank_mask:0xf bound_ctrl:1
	v_add_f32_dpp v168, v168, v168 row_mirror row_mask:0xf bank_mask:0xf bound_ctrl:1
	v_add_f32_dpp v174, v174, v174 row_mirror row_mask:0xf bank_mask:0xf bound_ctrl:1
	v_add_f32_dpp v241, v241, v241 row_mirror row_mask:0xf bank_mask:0xf bound_ctrl:1
	v_add_f32_dpp v247, v247, v247 row_mirror row_mask:0xf bank_mask:0xf bound_ctrl:1
	v_readlane_b32 s36, v168, 16
	v_readlane_b32 s40, v174, 16
	v_readlane_b32 s44, v241, 16
	v_readlane_b32 s48, v247, 16
	v_readlane_b32 s37, v168, 48
	v_readlane_b32 s41, v174, 48
	v_readlane_b32 s45, v241, 48
	v_readlane_b32 s49, v247, 48
	v_readlane_b32 s38, v168, 0
	v_readlane_b32 s42, v174, 0
	v_readlane_b32 s46, v241, 0
	v_readlane_b32 s50, v247, 0
	v_readlane_b32 s39, v168, 32
	v_readlane_b32 s43, v174, 32
	v_readlane_b32 s47, v241, 32
	v_readlane_b32 s51, v247, 32
	v_mov_b32_e32 v168, s36
	v_mov_b32_e32 v174, s40
	v_mov_b32_e32 v241, s44
	v_mov_b32_e32 v247, s48
	v_mov_b32_e32 v169, s37
	v_mov_b32_e32 v175, s41
	v_mov_b32_e32 v242, s45
	v_mov_b32_e32 v248, s49
	v_add_f32_e32 v168, s38, v168
	v_add_f32_e32 v174, s42, v174
	v_add_f32_e32 v241, s46, v241
; __device__ __forceinline__ float bf2f(bf16 x) { return __uint_as_float(((unsigned)x) << 16); }
; __device__ __forceinline__ unsigned f2bf(float f) { return cvt_pk_bf16(f, 0.f) & 0xffffu; }
; __device__ __forceinline__ void rw_post(Frame& F) {
;     ...
;     for (int u = F.gw; u < 32 * (MR / 64); u += F.NGW) { const int h = u & 31, rb0 = (u >> 5) * 64, col = h * 64 + lane;
;     ...
;             for (int q = 0; q < 8; ++q) { const int row = rb0 + t0 + q;
;                 const float mean = wsum(y[q]) * (1.f / 64.f); const float dv = y[q] - mean; const float var = wsum(dv * dv) * (1.f / 64.f);
;                 const float yn = dv * (1.f / sqrtf(var + 64e-5f)) * g_ + b_;
;                 OB[(size_t)row * DH + col] = (bf16)f2bf((yn + rk[q] * vv[q]) * bf2f(gg[q])); }
	v_add_f32_e32 v247, s50, v247
	v_add_f32_e32 v169, s39, v169
	v_add_f32_e32 v175, s43, v175
	v_add_f32_e32 v242, s47, v242
	v_add_f32_e32 v248, s51, v248
	v_add_f32_e32 v168, v168, v169
	v_add_f32_e32 v174, v174, v175
	v_add_f32_e32 v241, v241, v242
	v_add_f32_e32 v247, v247, v248
	v_fmamk_f32 v168, v168, 0x3c800000, v9
	v_fmamk_f32 v174, v174, 0x3c800000, v9
	v_fmamk_f32 v241, v241, 0x3c800000, v9
	v_fmamk_f32 v247, v247, 0x3c800000, v9
	v_mul_f32_e32 v169, 0x4f800000, v168
	v_mul_f32_e32 v175, 0x4f800000, v174
	v_mul_f32_e32 v242, 0x4f800000, v241
	v_mul_f32_e32 v248, 0x4f800000, v247
	v_cmp_gt_f32_e64 s[52:53], s68, v168
	v_cmp_gt_f32_e64 s[54:55], s68, v174
	v_cmp_gt_f32_e64 s[56:57], s68, v241
	v_cmp_gt_f32_e64 s[58:59], s68, v247
	v_mov_b32_e32 v170, v168
	v_mov_b32_e32 v176, v174
	v_mov_b32_e32 v243, v241
	v_mov_b32_e32 v249, v247
	v_cndmask_b32_e64 v168, v170, v169, s[52:53]
	v_cndmask_b32_e64 v174, v176, v175, s[54:55]
	v_cndmask_b32_e64 v241, v243, v242, s[56:57]
	v_cndmask_b32_e64 v247, v249, v248, s[58:59]
	v_sqrt_f32_e32 v169, v168
	v_sqrt_f32_e32 v175, v174
	v_sqrt_f32_e32 v242, v241
	v_sqrt_f32_e32 v248, v247
	v_add_u32_e32 v170, -1, v169
	v_add_u32_e32 v176, -1, v175
	v_add_u32_e32 v243, -1, v242
	v_add_u32_e32 v249, -1, v248
	v_fma_f32 v171, -v170, v169, v168
	v_fma_f32 v177, -v176, v175, v174
	v_fma_f32 v244, -v243, v242, v241
	v_fma_f32 v250, -v249, v248, v247
	v_cmp_ge_f32_e64 s[60:61], 0, v171
	v_cmp_ge_f32_e64 s[62:63], 0, v177
	v_cmp_ge_f32_e64 s[64:65], 0, v244
	v_cmp_ge_f32_e64 s[66:67], 0, v250
	v_add_u32_e32 v171, 1, v169
	v_add_u32_e32 v177, 1, v175
	v_add_u32_e32 v244, 1, v242
	v_add_u32_e32 v250, 1, v248
	v_cndmask_b32_e64 v170, v169, v170, s[60:61]
	v_cndmask_b32_e64 v176, v175, v176, s[62:63]
	v_cndmask_b32_e64 v243, v242, v243, s[64:65]
	v_cndmask_b32_e64 v249, v248, v249, s[66:67]
	v_fma_f32 v169, -v171, v169, v168
	v_fma_f32 v175, -v177, v175, v174
	v_fma_f32 v242, -v244, v242, v241
	v_fma_f32 v248, -v250, v248, v247
	v_cmp_lt_f32_e64 s[60:61], 0, v169
	v_cmp_lt_f32_e64 s[62:63], 0, v175
	v_cmp_lt_f32_e64 s[64:65], 0, v242
	v_cmp_lt_f32_e64 s[66:67], 0, v248
	v_cndmask_b32_e64 v169, v170, v171, s[60:61]
	v_cndmask_b32_e64 v175, v176, v177, s[62:63]
	v_cndmask_b32_e64 v242, v243, v244, s[64:65]
	v_cndmask_b32_e64 v248, v249, v250, s[66:67]
	v_mul_f32_e32 v170, 0x37800000, v169
	v_mul_f32_e32 v176, 0x37800000, v175
	v_mul_f32_e32 v243, 0x37800000, v242
	v_mul_f32_e32 v249, 0x37800000, v248
	v_cndmask_b32_e64 v169, v169, v170, s[52:53]
	v_cndmask_b32_e64 v175, v175, v176, s[54:55]
	v_cndmask_b32_e64 v242, v242, v243, s[56:57]
	v_cndmask_b32_e64 v248, v248, v249, s[58:59]
	v_cmp_class_f32_e64 s[60:61], v168, v8
	v_cmp_class_f32_e64 s[62:63], v174, v8
	v_cmp_class_f32_e64 s[64:65], v241, v8
	v_cmp_class_f32_e64 s[66:67], v247, v8
	v_cndmask_b32_e64 v168, v169, v168, s[60:61]
	v_cndmask_b32_e64 v174, v175, v174, s[62:63]
	v_cndmask_b32_e64 v241, v242, v241, s[64:65]
	v_cndmask_b32_e64 v247, v248, v247, s[66:67]
	v_div_scale_f32 v169, s[60:61], v168, v168, 1.0
	v_rcp_f32_e32 v170, v169
	s_nop 0
	v_fma_f32 v171, -v169, v170, 1.0
	v_fmac_f32_e32 v170, v171, v170
	v_div_scale_f32 v171, vcc, 1.0, v168, 1.0
	v_mul_f32_e32 v172, v171, v170
	v_fma_f32 v173, -v169, v172, v171
	v_fmac_f32_e32 v172, v173, v170
	v_fma_f32 v169, -v169, v172, v171
	v_div_fmas_f32 v169, v169, v170, v172
	v_div_fixup_f32 v168, v169, v168, 1.0
	v_div_scale_f32 v175, s[62:63], v174, v174, 1.0
	v_rcp_f32_e32 v176, v175
	s_nop 0
	v_fma_f32 v177, -v175, v176, 1.0
	v_fmac_f32_e32 v176, v177, v176
	v_div_scale_f32 v177, vcc, 1.0, v174, 1.0
	v_mul_f32_e32 v236, v177, v176
	v_fma_f32 v237, -v175, v236, v177
	v_fmac_f32_e32 v236, v237, v176
	v_fma_f32 v175, -v175, v236, v177
	v_div_fmas_f32 v175, v175, v176, v236
	v_div_fixup_f32 v174, v175, v174, 1.0
	v_div_scale_f32 v242, s[64:65], v241, v241, 1.0
	v_rcp_f32_e32 v243, v242
	s_nop 0
	v_fma_f32 v244, -v242, v243, 1.0
	v_fmac_f32_e32 v243, v244, v243
	v_div_scale_f32 v244, vcc, 1.0, v241, 1.0
	v_mul_f32_e32 v245, v244, v243
	v_fma_f32 v246, -v242, v245, v244
	v_fmac_f32_e32 v245, v246, v243
	v_fma_f32 v242, -v242, v245, v244
	v_div_fmas_f32 v242, v242, v243, v245
	v_div_fixup_f32 v241, v242, v241, 1.0
	v_div_scale_f32 v248, s[66:67], v247, v247, 1.0
	v_rcp_f32_e32 v249, v248
	s_nop 0
	v_fma_f32 v250, -v248, v249, 1.0
	v_fmac_f32_e32 v249, v250, v249
	v_div_scale_f32 v250, vcc, 1.0, v247, 1.0
	v_mul_f32_e32 v251, v250, v249
	v_fma_f32 v252, -v248, v251, v250
	v_fmac_f32_e32 v251, v252, v249
	v_fma_f32 v248, -v248, v251, v250
	v_div_fmas_f32 v248, v248, v249, v251
	v_div_fixup_f32 v247, v248, v247, 1.0
	v_mul_f32_e32 v100, v100, v168
	v_mul_f32_e32 v105, v105, v174
	v_mul_f32_e32 v110, v110, v241
	v_mul_f32_e32 v115, v115, v247
	v_lshlrev_b32_e32 v103, 16, v103
	v_lshlrev_b32_e32 v108, 16, v108
	v_lshlrev_b32_e32 v113, 16, v113
	v_lshlrev_b32_e32 v118, 16, v118
	v_fma_f32 v100, v6, v100, v7
	v_fma_f32 v105, v6, v105, v7
	v_fma_f32 v110, v6, v110, v7
	v_fma_f32 v115, v6, v115, v7
	v_fmac_f32_e32 v100, s73, v101
	v_fmac_f32_e32 v105, s26, v106
	v_fmac_f32_e32 v110, s27, v111
	v_fmac_f32_e32 v115, s32, v116
	v_mul_f32_e32 v100, v100, v103
	v_mul_f32_e32 v105, v105, v108
	v_mul_f32_e32 v110, v110, v113
	v_mul_f32_e32 v115, v115, v118
	v_cvt_pk_bf16_f32 v169, v100, v100
	v_cvt_pk_bf16_f32 v175, v105, v105
	v_cvt_pk_bf16_f32 v242, v110, v110
	v_cvt_pk_bf16_f32 v248, v115, v115
	global_store_short v2, v169, s[28:29]
	s_add_u32 s28, s28, 0x1000
	s_addc_u32 s29, s29, 0
	global_store_short v2, v175, s[28:29]
	s_add_u32 s28, s28, 0x1000
	s_addc_u32 s29, s29, 0
	global_store_short v2, v242, s[28:29]
	s_add_u32 s28, s28, 0x1000
	s_addc_u32 s29, s29, 0
	global_store_short v2, v248, s[28:29]
	s_add_u32 s28, s28, 0x1000
	s_addc_u32 s29, s29, 0
	s_add_i32 s20, s20, s92
	s_cmpk_lt_i32 s20, 0x2040
	s_cbranch_scc1 .Lpo_unit
